# scan operands prefetched two steps ahead (3 register sets); GEMM mainloop per-phase s_setprio flips removed
# speedup vs baseline: 1.0163x; 1.0008x over previous
; #define LAS __attribute__((address_space(3)))
; __device__ __forceinline__ float red8(float x) { x += dpp_mov<0xB1>(x); x += dpp_mov<0x4E>(x); x += dpp_mov<0x141>(x); return x; }
; __device__ __forceinline__ void scan_phase(const KP& P, LAS unsigned char* lds, const int tid, const int bx, const int G) {
;     ...
;         for (int c = 0; c < NCH; ++c) {
;             if (c + 1 < NCH) SC_LOAD(c + 1);
;             const LAS float* cb = buf + (c & 1) * 12288 + kc * 8;
; #pragma unroll 16
;             for (int s = 0; s < 32; ++s) {
;                 const LAS float* p = cb + s * 384;
;                 const f32x4 w0 = *(const LAS f32x4*)(p), w1 = *(const LAS f32x4*)(p + 4);
;                 const f32x4 k0 = *(const LAS f32x4*)(p + 64), k1 = *(const LAS f32x4*)(p + 68);
;                 const f32x4 a0 = *(const LAS f32x4*)(p + 128), a1 = *(const LAS f32x4*)(p + 132);
;                 const f32x4 b0 = *(const LAS f32x4*)(p + 192), b1 = *(const LAS f32x4*)(p + 196);
;                 const f32x4 r0 = *(const LAS f32x4*)(p + 256), r1 = *(const LAS f32x4*)(p + 260);
;                 const float vv = buf[(c & 1) * 12288 + s * 384 + 320 + v];
;                 f32x2 sa2 = S[0] * (f32x2){a0.x, a0.y};
;                 sa2 += S[1] * (f32x2){a0.z, a0.w}; sa2 += S[2] * (f32x2){a1.x, a1.y}; sa2 += S[3] * (f32x2){a1.z, a1.w};
;                 const float sa = red8(sa2.x + sa2.y);
;                 const f32x2 sav = {sa, sa}, vv2 = {vv, vv};
;                 S[0] = S[0] * (f32x2){w0.x, w0.y} + sav * (f32x2){b0.x, b0.y} + vv2 * (f32x2){k0.x, k0.y};
;                 S[1] = S[1] * (f32x2){w0.z, w0.w} + sav * (f32x2){b0.z, b0.w} + vv2 * (f32x2){k0.z, k0.w};
;                 S[2] = S[2] * (f32x2){w1.x, w1.y} + sav * (f32x2){b1.x, b1.y} + vv2 * (f32x2){k1.x, k1.y};
;                 S[3] = S[3] * (f32x2){w1.z, w1.w} + sav * (f32x2){b1.z, b1.w} + vv2 * (f32x2){k1.z, k1.w};
;                 f32x2 y2 = S[0] * (f32x2){r0.x, r0.y};
;                 y2 += S[1] * (f32x2){r0.z, r0.w}; y2 += S[2] * (f32x2){r1.x, r1.y}; y2 += S[3] * (f32x2){r1.z, r1.w};
;                 const float y = red8(y2.x + y2.y);
;                 if (kc == 0) ybuf[s * 64 + v] = y;
;             }
.Lscan_compute:
	s_bitcmp1_b32 s3, 0
	s_cselect_b32 s0, 0xc000, 0
	v_lshlrev_b32_e32 v45, 1, v58
	v_or_b32_e32 v44, s0, v56
	v_add_u32_e32 v46, s0, v45
	v_add_u32_e32 v46, 0x500, v46
	v_add_u32_e32 v45, 0x18000, v45
	s_mov_b64 s[0:1], exec
	ds_read_b128 v[148:151], v44 offset:512
	ds_read_b128 v[152:155], v44 offset:528
	ds_read_b128 v[156:159], v44 offset:2048
	ds_read_b128 v[160:163], v44 offset:2064
	ds_read_b128 v[120:123], v44 offset:256
	ds_read_b128 v[124:127], v44 offset:272
	ds_read_b128 v[128:131], v44 offset:768
	ds_read_b128 v[132:135], v44 offset:784
	ds_read_b128 v[136:139], v44 offset:1024
	ds_read_b128 v[140:143], v44 offset:1040
	ds_read_b64 v[144:145], v46 offset:0
	ds_read_b128 v[112:115], v44 offset:47616
	ds_read_b128 v[116:119], v44 offset:47632
	ds_read_b128 v[62:65], v44 offset:3584
	ds_read_b128 v[66:69], v44 offset:3600
	ds_read_b128 v[70:73], v44 offset:1792
	ds_read_b128 v[74:77], v44 offset:1808
	ds_read_b128 v[78:81], v44 offset:2304
	ds_read_b128 v[82:85], v44 offset:2320
	ds_read_b128 v[86:89], v44 offset:2560
	ds_read_b128 v[90:93], v44 offset:2576
	ds_read_b64 v[146:147], v46 offset:1536
	s_waitcnt lgkmcnt(15)
	v_pk_mul_f32 v[18:19], v[96:97], v[148:149] op_sel:[0,0] op_sel_hi:[1,0]
	v_pk_mul_f32 v[20:21], v[98:99], v[148:149] op_sel:[0,1] op_sel_hi:[1,1]
	v_pk_fma_f32 v[18:19], v[100:101], v[150:151], v[18:19] op_sel:[0,0,0] op_sel_hi:[1,0,1]
	v_pk_fma_f32 v[20:21], v[102:103], v[150:151], v[20:21] op_sel:[0,1,0] op_sel_hi:[1,1,1]
	v_pk_fma_f32 v[18:19], v[104:105], v[152:153], v[18:19] op_sel:[0,0,0] op_sel_hi:[1,0,1]
	v_pk_fma_f32 v[20:21], v[106:107], v[152:153], v[20:21] op_sel:[0,1,0] op_sel_hi:[1,1,1]
	v_pk_fma_f32 v[18:19], v[108:109], v[154:155], v[18:19] op_sel:[0,0,0] op_sel_hi:[1,0,1]
	v_pk_fma_f32 v[20:21], v[110:111], v[154:155], v[20:21] op_sel:[0,1,0] op_sel_hi:[1,1,1]
	v_pk_add_f32 v[50:51], v[18:19], v[20:21]
	s_waitcnt lgkmcnt(9)
	ds_read_b128 v[168:171], v44 offset:3328
	ds_read_b128 v[172:175], v44 offset:3344
	ds_read_b128 v[176:179], v44 offset:3840
	ds_read_b128 v[180:183], v44 offset:3856
	ds_read_b128 v[184:187], v44 offset:4096
	ds_read_b128 v[188:191], v44 offset:4112
	ds_read_b64 v[192:193], v46 offset:3072
	ds_read_b128 v[148:151], v44 offset:5120
	ds_read_b128 v[152:155], v44 offset:5136
	v_add_f32_dpp v50, v50, v50 quad_perm:[1,0,3,2] row_mask:0xf bank_mask:0xf bound_ctrl:1
	v_add_f32_dpp v51, v51, v51 quad_perm:[1,0,3,2] row_mask:0xf bank_mask:0xf bound_ctrl:1
	v_pk_fma_f32 v[96:97], v[144:145], v[120:121], v[96:97] op_sel:[0,0,0] op_sel_hi:[1,0,1]
	v_pk_fma_f32 v[98:99], v[144:145], v[120:121], v[98:99] op_sel:[0,1,0] op_sel_hi:[1,1,1]
	v_pk_fma_f32 v[100:101], v[144:145], v[122:123], v[100:101] op_sel:[0,0,0] op_sel_hi:[1,0,1]
	v_add_f32_dpp v50, v50, v50 quad_perm:[2,3,0,1] row_mask:0xf bank_mask:0xf bound_ctrl:1
	v_add_f32_dpp v51, v51, v51 quad_perm:[2,3,0,1] row_mask:0xf bank_mask:0xf bound_ctrl:1
	v_pk_fma_f32 v[102:103], v[144:145], v[122:123], v[102:103] op_sel:[0,1,0] op_sel_hi:[1,1,1]
	v_pk_fma_f32 v[104:105], v[144:145], v[124:125], v[104:105] op_sel:[0,0,0] op_sel_hi:[1,0,1]
	v_pk_fma_f32 v[106:107], v[144:145], v[124:125], v[106:107] op_sel:[0,1,0] op_sel_hi:[1,1,1]
	v_add_f32_dpp v50, v50, v50 row_half_mirror row_mask:0xf bank_mask:0xf bound_ctrl:1
	v_add_f32_dpp v51, v51, v51 row_half_mirror row_mask:0xf bank_mask:0xf bound_ctrl:1
	v_pk_fma_f32 v[108:109], v[144:145], v[126:127], v[108:109] op_sel:[0,0,0] op_sel_hi:[1,0,1]
	v_pk_fma_f32 v[110:111], v[144:145], v[126:127], v[110:111] op_sel:[0,1,0] op_sel_hi:[1,1,1]
	s_nop 0
	v_pk_fma_f32 v[96:97], v[50:51], v[128:129], v[96:97] op_sel:[0,0,0] op_sel_hi:[1,0,1]
	v_pk_fma_f32 v[98:99], v[50:51], v[128:129], v[98:99] op_sel:[0,1,0] op_sel_hi:[1,1,1]
	v_pk_fma_f32 v[100:101], v[50:51], v[130:131], v[100:101] op_sel:[0,0,0] op_sel_hi:[1,0,1]
	v_pk_fma_f32 v[102:103], v[50:51], v[130:131], v[102:103] op_sel:[0,1,0] op_sel_hi:[1,1,1]
	v_pk_fma_f32 v[104:105], v[50:51], v[132:133], v[104:105] op_sel:[0,0,0] op_sel_hi:[1,0,1]
	v_pk_fma_f32 v[106:107], v[50:51], v[132:133], v[106:107] op_sel:[0,1,0] op_sel_hi:[1,1,1]
	v_pk_fma_f32 v[108:109], v[50:51], v[134:135], v[108:109] op_sel:[0,0,0] op_sel_hi:[1,0,1]
	v_pk_fma_f32 v[110:111], v[50:51], v[134:135], v[110:111] op_sel:[0,1,0] op_sel_hi:[1,1,1]
	v_pk_mul_f32 v[14:15], v[96:97], v[136:137] op_sel:[0,0] op_sel_hi:[1,0]
	v_pk_mul_f32 v[18:19], v[96:97], v[156:157] op_sel:[0,0] op_sel_hi:[1,0]
	v_pk_mul_f32 v[16:17], v[98:99], v[136:137] op_sel:[0,1] op_sel_hi:[1,1]
	v_pk_mul_f32 v[20:21], v[98:99], v[156:157] op_sel:[0,1] op_sel_hi:[1,1]
	v_pk_fma_f32 v[14:15], v[100:101], v[138:139], v[14:15] op_sel:[0,0,0] op_sel_hi:[1,0,1]
	v_pk_fma_f32 v[18:19], v[100:101], v[158:159], v[18:19] op_sel:[0,0,0] op_sel_hi:[1,0,1]
	v_pk_fma_f32 v[16:17], v[102:103], v[138:139], v[16:17] op_sel:[0,1,0] op_sel_hi:[1,1,1]
	v_pk_fma_f32 v[20:21], v[102:103], v[158:159], v[20:21] op_sel:[0,1,0] op_sel_hi:[1,1,1]
	v_pk_fma_f32 v[14:15], v[104:105], v[140:141], v[14:15] op_sel:[0,0,0] op_sel_hi:[1,0,1]
	v_pk_fma_f32 v[18:19], v[104:105], v[160:161], v[18:19] op_sel:[0,0,0] op_sel_hi:[1,0,1]
	v_pk_fma_f32 v[16:17], v[106:107], v[140:141], v[16:17] op_sel:[0,1,0] op_sel_hi:[1,1,1]
	v_pk_fma_f32 v[20:21], v[106:107], v[160:161], v[20:21] op_sel:[0,1,0] op_sel_hi:[1,1,1]
	v_pk_fma_f32 v[14:15], v[108:109], v[142:143], v[14:15] op_sel:[0,0,0] op_sel_hi:[1,0,1]
	v_pk_fma_f32 v[18:19], v[108:109], v[162:163], v[18:19] op_sel:[0,0,0] op_sel_hi:[1,0,1]
	v_pk_fma_f32 v[16:17], v[110:111], v[142:143], v[16:17] op_sel:[0,1,0] op_sel_hi:[1,1,1]
	v_pk_fma_f32 v[20:21], v[110:111], v[162:163], v[20:21] op_sel:[0,1,0] op_sel_hi:[1,1,1]
	v_pk_add_f32 v[48:49], v[14:15], v[16:17]
	v_pk_add_f32 v[50:51], v[18:19], v[20:21]
	s_waitcnt lgkmcnt(9)
; #define LAS __attribute__((address_space(3)))
; __device__ __forceinline__ float red8(float x) { x += dpp_mov<0xB1>(x); x += dpp_mov<0x4E>(x); x += dpp_mov<0x141>(x); return x; }
; __device__ __forceinline__ void scan_phase(const KP& P, LAS unsigned char* lds, const int tid, const int bx, const int G) {
;     ...
;             for (int s = 0; s < 32; ++s) {
;                 const LAS float* p = cb + s * 384;
;                 const f32x4 w0 = *(const LAS f32x4*)(p), w1 = *(const LAS f32x4*)(p + 4);
;                 const f32x4 k0 = *(const LAS f32x4*)(p + 64), k1 = *(const LAS f32x4*)(p + 68);
;                 const f32x4 a0 = *(const LAS f32x4*)(p + 128), a1 = *(const LAS f32x4*)(p + 132);
;                 const f32x4 b0 = *(const LAS f32x4*)(p + 192), b1 = *(const LAS f32x4*)(p + 196);
;                 const f32x4 r0 = *(const LAS f32x4*)(p + 256), r1 = *(const LAS f32x4*)(p + 260);
;                 const float vv = buf[(c & 1) * 12288 + s * 384 + 320 + v];
;                 f32x2 sa2 = S[0] * (f32x2){a0.x, a0.y};
;                 sa2 += S[1] * (f32x2){a0.z, a0.w}; sa2 += S[2] * (f32x2){a1.x, a1.y}; sa2 += S[3] * (f32x2){a1.z, a1.w};
;                 const float sa = red8(sa2.x + sa2.y);
;                 const f32x2 sav = {sa, sa}, vv2 = {vv, vv};
;                 S[0] = S[0] * (f32x2){w0.x, w0.y} + sav * (f32x2){b0.x, b0.y} + vv2 * (f32x2){k0.x, k0.y};
;                 S[1] = S[1] * (f32x2){w0.z, w0.w} + sav * (f32x2){b0.z, b0.w} + vv2 * (f32x2){k0.z, k0.w};
;                 S[2] = S[2] * (f32x2){w1.x, w1.y} + sav * (f32x2){b1.x, b1.y} + vv2 * (f32x2){k1.x, k1.y};
;                 S[3] = S[3] * (f32x2){w1.z, w1.w} + sav * (f32x2){b1.z, b1.w} + vv2 * (f32x2){k1.z, k1.w};
;                 f32x2 y2 = S[0] * (f32x2){r0.x, r0.y};
;                 y2 += S[1] * (f32x2){r0.z, r0.w}; y2 += S[2] * (f32x2){r1.x, r1.y}; y2 += S[3] * (f32x2){r1.z, r1.w};
;                 const float y = red8(y2.x + y2.y);
;                 if (kc == 0) ybuf[s * 64 + v] = y;
	ds_read_b128 v[120:123], v44 offset:4864
	ds_read_b128 v[124:127], v44 offset:4880
	ds_read_b128 v[128:131], v44 offset:5376
	ds_read_b128 v[132:135], v44 offset:5392
	ds_read_b128 v[136:139], v44 offset:5632
	ds_read_b128 v[140:143], v44 offset:5648
	ds_read_b64 v[144:145], v46 offset:4608
	ds_read_b128 v[156:159], v44 offset:6656
	ds_read_b128 v[160:163], v44 offset:6672
	v_add_f32_dpp v48, v48, v48 quad_perm:[1,0,3,2] row_mask:0xf bank_mask:0xf bound_ctrl:1
	v_add_f32_dpp v49, v49, v49 quad_perm:[1,0,3,2] row_mask:0xf bank_mask:0xf bound_ctrl:1
	v_add_f32_dpp v50, v50, v50 quad_perm:[1,0,3,2] row_mask:0xf bank_mask:0xf bound_ctrl:1
	v_add_f32_dpp v51, v51, v51 quad_perm:[1,0,3,2] row_mask:0xf bank_mask:0xf bound_ctrl:1
	v_pk_fma_f32 v[96:97], v[146:147], v[70:71], v[96:97] op_sel:[0,0,0] op_sel_hi:[1,0,1]
	v_pk_fma_f32 v[98:99], v[146:147], v[70:71], v[98:99] op_sel:[0,1,0] op_sel_hi:[1,1,1]
	v_pk_fma_f32 v[100:101], v[146:147], v[72:73], v[100:101] op_sel:[0,0,0] op_sel_hi:[1,0,1]
	v_add_f32_dpp v48, v48, v48 quad_perm:[2,3,0,1] row_mask:0xf bank_mask:0xf bound_ctrl:1
	v_add_f32_dpp v49, v49, v49 quad_perm:[2,3,0,1] row_mask:0xf bank_mask:0xf bound_ctrl:1
	v_add_f32_dpp v50, v50, v50 quad_perm:[2,3,0,1] row_mask:0xf bank_mask:0xf bound_ctrl:1
	v_add_f32_dpp v51, v51, v51 quad_perm:[2,3,0,1] row_mask:0xf bank_mask:0xf bound_ctrl:1
	v_pk_fma_f32 v[102:103], v[146:147], v[72:73], v[102:103] op_sel:[0,1,0] op_sel_hi:[1,1,1]
	v_pk_fma_f32 v[104:105], v[146:147], v[74:75], v[104:105] op_sel:[0,0,0] op_sel_hi:[1,0,1]
	v_pk_fma_f32 v[106:107], v[146:147], v[74:75], v[106:107] op_sel:[0,1,0] op_sel_hi:[1,1,1]
	v_add_f32_dpp v48, v48, v48 row_half_mirror row_mask:0xf bank_mask:0xf bound_ctrl:1
	v_add_f32_dpp v49, v49, v49 row_half_mirror row_mask:0xf bank_mask:0xf bound_ctrl:1
	v_add_f32_dpp v50, v50, v50 row_half_mirror row_mask:0xf bank_mask:0xf bound_ctrl:1
	v_add_f32_dpp v51, v51, v51 row_half_mirror row_mask:0xf bank_mask:0xf bound_ctrl:1
	v_pk_fma_f32 v[108:109], v[146:147], v[76:77], v[108:109] op_sel:[0,0,0] op_sel_hi:[1,0,1]
	s_mov_b64 exec, s[10:11]
	ds_write_b64 v45, v[48:49] offset:0
	s_mov_b64 exec, s[0:1]
	v_pk_fma_f32 v[110:111], v[146:147], v[76:77], v[110:111] op_sel:[0,1,0] op_sel_hi:[1,1,1]
	s_nop 0
	v_pk_fma_f32 v[96:97], v[50:51], v[78:79], v[96:97] op_sel:[0,0,0] op_sel_hi:[1,0,1]
	v_pk_fma_f32 v[98:99], v[50:51], v[78:79], v[98:99] op_sel:[0,1,0] op_sel_hi:[1,1,1]
	v_pk_fma_f32 v[100:101], v[50:51], v[80:81], v[100:101] op_sel:[0,0,0] op_sel_hi:[1,0,1]
	v_pk_fma_f32 v[102:103], v[50:51], v[80:81], v[102:103] op_sel:[0,1,0] op_sel_hi:[1,1,1]
	v_pk_fma_f32 v[104:105], v[50:51], v[82:83], v[104:105] op_sel:[0,0,0] op_sel_hi:[1,0,1]
	v_pk_fma_f32 v[106:107], v[50:51], v[82:83], v[106:107] op_sel:[0,1,0] op_sel_hi:[1,1,1]
	v_pk_fma_f32 v[108:109], v[50:51], v[84:85], v[108:109] op_sel:[0,0,0] op_sel_hi:[1,0,1]
	v_pk_fma_f32 v[110:111], v[50:51], v[84:85], v[110:111] op_sel:[0,1,0] op_sel_hi:[1,1,1]
	v_pk_mul_f32 v[14:15], v[96:97], v[86:87] op_sel:[0,0] op_sel_hi:[1,0]
	v_pk_mul_f32 v[18:19], v[96:97], v[62:63] op_sel:[0,0] op_sel_hi:[1,0]
	v_pk_mul_f32 v[16:17], v[98:99], v[86:87] op_sel:[0,1] op_sel_hi:[1,1]
	v_pk_mul_f32 v[20:21], v[98:99], v[62:63] op_sel:[0,1] op_sel_hi:[1,1]
	v_pk_fma_f32 v[14:15], v[100:101], v[88:89], v[14:15] op_sel:[0,0,0] op_sel_hi:[1,0,1]
	v_pk_fma_f32 v[18:19], v[100:101], v[64:65], v[18:19] op_sel:[0,0,0] op_sel_hi:[1,0,1]
	v_pk_fma_f32 v[16:17], v[102:103], v[88:89], v[16:17] op_sel:[0,1,0] op_sel_hi:[1,1,1]
	v_pk_fma_f32 v[20:21], v[102:103], v[64:65], v[20:21] op_sel:[0,1,0] op_sel_hi:[1,1,1]
	v_pk_fma_f32 v[14:15], v[104:105], v[90:91], v[14:15] op_sel:[0,0,0] op_sel_hi:[1,0,1]
	v_pk_fma_f32 v[18:19], v[104:105], v[66:67], v[18:19] op_sel:[0,0,0] op_sel_hi:[1,0,1]
	v_pk_fma_f32 v[16:17], v[106:107], v[90:91], v[16:17] op_sel:[0,1,0] op_sel_hi:[1,1,1]
	v_pk_fma_f32 v[20:21], v[106:107], v[66:67], v[20:21] op_sel:[0,1,0] op_sel_hi:[1,1,1]
	v_pk_fma_f32 v[14:15], v[108:109], v[92:93], v[14:15] op_sel:[0,0,0] op_sel_hi:[1,0,1]
	v_pk_fma_f32 v[18:19], v[108:109], v[68:69], v[18:19] op_sel:[0,0,0] op_sel_hi:[1,0,1]
	v_pk_fma_f32 v[16:17], v[110:111], v[92:93], v[16:17] op_sel:[0,1,0] op_sel_hi:[1,1,1]
	v_pk_fma_f32 v[20:21], v[110:111], v[68:69], v[20:21] op_sel:[0,1,0] op_sel_hi:[1,1,1]
	v_pk_add_f32 v[48:49], v[14:15], v[16:17]
	v_pk_add_f32 v[50:51], v[18:19], v[20:21]
	s_waitcnt lgkmcnt(10)
; #define LAS __attribute__((address_space(3)))
; __device__ __forceinline__ float red8(float x) { x += dpp_mov<0xB1>(x); x += dpp_mov<0x4E>(x); x += dpp_mov<0x141>(x); return x; }
; __device__ __forceinline__ void scan_phase(const KP& P, LAS unsigned char* lds, const int tid, const int bx, const int G) {
;     ...
;             for (int s = 0; s < 32; ++s) {
;                 const LAS float* p = cb + s * 384;
;                 const f32x4 w0 = *(const LAS f32x4*)(p), w1 = *(const LAS f32x4*)(p + 4);
;                 const f32x4 k0 = *(const LAS f32x4*)(p + 64), k1 = *(const LAS f32x4*)(p + 68);
;                 const f32x4 a0 = *(const LAS f32x4*)(p + 128), a1 = *(const LAS f32x4*)(p + 132);
;                 const f32x4 b0 = *(const LAS f32x4*)(p + 192), b1 = *(const LAS f32x4*)(p + 196);
;                 const f32x4 r0 = *(const LAS f32x4*)(p + 256), r1 = *(const LAS f32x4*)(p + 260);
;                 const float vv = buf[(c & 1) * 12288 + s * 384 + 320 + v];
;                 f32x2 sa2 = S[0] * (f32x2){a0.x, a0.y};
;                 sa2 += S[1] * (f32x2){a0.z, a0.w}; sa2 += S[2] * (f32x2){a1.x, a1.y}; sa2 += S[3] * (f32x2){a1.z, a1.w};
;                 const float sa = red8(sa2.x + sa2.y);
;                 const f32x2 sav = {sa, sa}, vv2 = {vv, vv};
;                 S[0] = S[0] * (f32x2){w0.x, w0.y} + sav * (f32x2){b0.x, b0.y} + vv2 * (f32x2){k0.x, k0.y};
;                 S[1] = S[1] * (f32x2){w0.z, w0.w} + sav * (f32x2){b0.z, b0.w} + vv2 * (f32x2){k0.z, k0.w};
;                 S[2] = S[2] * (f32x2){w1.x, w1.y} + sav * (f32x2){b1.x, b1.y} + vv2 * (f32x2){k1.x, k1.y};
;                 S[3] = S[3] * (f32x2){w1.z, w1.w} + sav * (f32x2){b1.z, b1.w} + vv2 * (f32x2){k1.z, k1.w};
;                 f32x2 y2 = S[0] * (f32x2){r0.x, r0.y};
;                 y2 += S[1] * (f32x2){r0.z, r0.w}; y2 += S[2] * (f32x2){r1.x, r1.y}; y2 += S[3] * (f32x2){r1.z, r1.w};
;                 const float y = red8(y2.x + y2.y);
;                 if (kc == 0) ybuf[s * 64 + v] = y;
	ds_read_b128 v[70:73], v44 offset:6400
	ds_read_b128 v[74:77], v44 offset:6416
	ds_read_b128 v[78:81], v44 offset:6912
	ds_read_b128 v[82:85], v44 offset:6928
	ds_read_b128 v[86:89], v44 offset:7168
	ds_read_b128 v[90:93], v44 offset:7184
	ds_read_b64 v[146:147], v46 offset:6144
	ds_read_b128 v[62:65], v44 offset:8192
	ds_read_b128 v[66:69], v44 offset:8208
	v_add_f32_dpp v48, v48, v48 quad_perm:[1,0,3,2] row_mask:0xf bank_mask:0xf bound_ctrl:1
	v_add_f32_dpp v49, v49, v49 quad_perm:[1,0,3,2] row_mask:0xf bank_mask:0xf bound_ctrl:1
	v_add_f32_dpp v50, v50, v50 quad_perm:[1,0,3,2] row_mask:0xf bank_mask:0xf bound_ctrl:1
	v_add_f32_dpp v51, v51, v51 quad_perm:[1,0,3,2] row_mask:0xf bank_mask:0xf bound_ctrl:1
	v_pk_fma_f32 v[96:97], v[192:193], v[168:169], v[96:97] op_sel:[0,0,0] op_sel_hi:[1,0,1]
	v_pk_fma_f32 v[98:99], v[192:193], v[168:169], v[98:99] op_sel:[0,1,0] op_sel_hi:[1,1,1]
	v_pk_fma_f32 v[100:101], v[192:193], v[170:171], v[100:101] op_sel:[0,0,0] op_sel_hi:[1,0,1]
	v_add_f32_dpp v48, v48, v48 quad_perm:[2,3,0,1] row_mask:0xf bank_mask:0xf bound_ctrl:1
	v_add_f32_dpp v49, v49, v49 quad_perm:[2,3,0,1] row_mask:0xf bank_mask:0xf bound_ctrl:1
	v_add_f32_dpp v50, v50, v50 quad_perm:[2,3,0,1] row_mask:0xf bank_mask:0xf bound_ctrl:1
	v_add_f32_dpp v51, v51, v51 quad_perm:[2,3,0,1] row_mask:0xf bank_mask:0xf bound_ctrl:1
	v_pk_fma_f32 v[102:103], v[192:193], v[170:171], v[102:103] op_sel:[0,1,0] op_sel_hi:[1,1,1]
	v_pk_fma_f32 v[104:105], v[192:193], v[172:173], v[104:105] op_sel:[0,0,0] op_sel_hi:[1,0,1]
	v_pk_fma_f32 v[106:107], v[192:193], v[172:173], v[106:107] op_sel:[0,1,0] op_sel_hi:[1,1,1]
	v_add_f32_dpp v48, v48, v48 row_half_mirror row_mask:0xf bank_mask:0xf bound_ctrl:1
	v_add_f32_dpp v49, v49, v49 row_half_mirror row_mask:0xf bank_mask:0xf bound_ctrl:1
	v_add_f32_dpp v50, v50, v50 row_half_mirror row_mask:0xf bank_mask:0xf bound_ctrl:1
	v_add_f32_dpp v51, v51, v51 row_half_mirror row_mask:0xf bank_mask:0xf bound_ctrl:1
	v_pk_fma_f32 v[108:109], v[192:193], v[174:175], v[108:109] op_sel:[0,0,0] op_sel_hi:[1,0,1]
	s_mov_b64 exec, s[10:11]
	ds_write_b64 v45, v[48:49] offset:256
	s_mov_b64 exec, s[0:1]
	v_pk_fma_f32 v[110:111], v[192:193], v[174:175], v[110:111] op_sel:[0,1,0] op_sel_hi:[1,1,1]
	s_nop 0
	v_pk_fma_f32 v[96:97], v[50:51], v[176:177], v[96:97] op_sel:[0,0,0] op_sel_hi:[1,0,1]
	v_pk_fma_f32 v[98:99], v[50:51], v[176:177], v[98:99] op_sel:[0,1,0] op_sel_hi:[1,1,1]
	v_pk_fma_f32 v[100:101], v[50:51], v[178:179], v[100:101] op_sel:[0,0,0] op_sel_hi:[1,0,1]
	v_pk_fma_f32 v[102:103], v[50:51], v[178:179], v[102:103] op_sel:[0,1,0] op_sel_hi:[1,1,1]
	v_pk_fma_f32 v[104:105], v[50:51], v[180:181], v[104:105] op_sel:[0,0,0] op_sel_hi:[1,0,1]
	v_pk_fma_f32 v[106:107], v[50:51], v[180:181], v[106:107] op_sel:[0,1,0] op_sel_hi:[1,1,1]
	v_pk_fma_f32 v[108:109], v[50:51], v[182:183], v[108:109] op_sel:[0,0,0] op_sel_hi:[1,0,1]
	v_pk_fma_f32 v[110:111], v[50:51], v[182:183], v[110:111] op_sel:[0,1,0] op_sel_hi:[1,1,1]
	v_pk_mul_f32 v[14:15], v[96:97], v[184:185] op_sel:[0,0] op_sel_hi:[1,0]
	v_pk_mul_f32 v[18:19], v[96:97], v[148:149] op_sel:[0,0] op_sel_hi:[1,0]
	v_pk_mul_f32 v[16:17], v[98:99], v[184:185] op_sel:[0,1] op_sel_hi:[1,1]
	v_pk_mul_f32 v[20:21], v[98:99], v[148:149] op_sel:[0,1] op_sel_hi:[1,1]
	v_pk_fma_f32 v[14:15], v[100:101], v[186:187], v[14:15] op_sel:[0,0,0] op_sel_hi:[1,0,1]
	v_pk_fma_f32 v[18:19], v[100:101], v[150:151], v[18:19] op_sel:[0,0,0] op_sel_hi:[1,0,1]
	v_pk_fma_f32 v[16:17], v[102:103], v[186:187], v[16:17] op_sel:[0,1,0] op_sel_hi:[1,1,1]
	v_pk_fma_f32 v[20:21], v[102:103], v[150:151], v[20:21] op_sel:[0,1,0] op_sel_hi:[1,1,1]
	v_pk_fma_f32 v[14:15], v[104:105], v[188:189], v[14:15] op_sel:[0,0,0] op_sel_hi:[1,0,1]
	v_pk_fma_f32 v[18:19], v[104:105], v[152:153], v[18:19] op_sel:[0,0,0] op_sel_hi:[1,0,1]
	v_pk_fma_f32 v[16:17], v[106:107], v[188:189], v[16:17] op_sel:[0,1,0] op_sel_hi:[1,1,1]
	v_pk_fma_f32 v[20:21], v[106:107], v[152:153], v[20:21] op_sel:[0,1,0] op_sel_hi:[1,1,1]
	v_pk_fma_f32 v[14:15], v[108:109], v[190:191], v[14:15] op_sel:[0,0,0] op_sel_hi:[1,0,1]
	v_pk_fma_f32 v[18:19], v[108:109], v[154:155], v[18:19] op_sel:[0,0,0] op_sel_hi:[1,0,1]
	v_pk_fma_f32 v[16:17], v[110:111], v[190:191], v[16:17] op_sel:[0,1,0] op_sel_hi:[1,1,1]
	v_pk_fma_f32 v[20:21], v[110:111], v[154:155], v[20:21] op_sel:[0,1,0] op_sel_hi:[1,1,1]
	v_pk_add_f32 v[48:49], v[14:15], v[16:17]
	v_pk_add_f32 v[50:51], v[18:19], v[20:21]
	s_waitcnt lgkmcnt(11)
; #define LAS __attribute__((address_space(3)))
; __device__ __forceinline__ float red8(float x) { x += dpp_mov<0xB1>(x); x += dpp_mov<0x4E>(x); x += dpp_mov<0x141>(x); return x; }
; __device__ __forceinline__ void scan_phase(const KP& P, LAS unsigned char* lds, const int tid, const int bx, const int G) {
;     ...
;             for (int s = 0; s < 32; ++s) {
;                 const LAS float* p = cb + s * 384;
;                 const f32x4 w0 = *(const LAS f32x4*)(p), w1 = *(const LAS f32x4*)(p + 4);
;                 const f32x4 k0 = *(const LAS f32x4*)(p + 64), k1 = *(const LAS f32x4*)(p + 68);
;                 const f32x4 a0 = *(const LAS f32x4*)(p + 128), a1 = *(const LAS f32x4*)(p + 132);
;                 const f32x4 b0 = *(const LAS f32x4*)(p + 192), b1 = *(const LAS f32x4*)(p + 196);
;                 const f32x4 r0 = *(const LAS f32x4*)(p + 256), r1 = *(const LAS f32x4*)(p + 260);
;                 const float vv = buf[(c & 1) * 12288 + s * 384 + 320 + v];
;                 f32x2 sa2 = S[0] * (f32x2){a0.x, a0.y};
;                 sa2 += S[1] * (f32x2){a0.z, a0.w}; sa2 += S[2] * (f32x2){a1.x, a1.y}; sa2 += S[3] * (f32x2){a1.z, a1.w};
;                 const float sa = red8(sa2.x + sa2.y);
;                 const f32x2 sav = {sa, sa}, vv2 = {vv, vv};
;                 S[0] = S[0] * (f32x2){w0.x, w0.y} + sav * (f32x2){b0.x, b0.y} + vv2 * (f32x2){k0.x, k0.y};
;                 S[1] = S[1] * (f32x2){w0.z, w0.w} + sav * (f32x2){b0.z, b0.w} + vv2 * (f32x2){k0.z, k0.w};
;                 S[2] = S[2] * (f32x2){w1.x, w1.y} + sav * (f32x2){b1.x, b1.y} + vv2 * (f32x2){k1.x, k1.y};
;                 S[3] = S[3] * (f32x2){w1.z, w1.w} + sav * (f32x2){b1.z, b1.w} + vv2 * (f32x2){k1.z, k1.w};
;                 f32x2 y2 = S[0] * (f32x2){r0.x, r0.y};
;                 y2 += S[1] * (f32x2){r0.z, r0.w}; y2 += S[2] * (f32x2){r1.x, r1.y}; y2 += S[3] * (f32x2){r1.z, r1.w};
;                 const float y = red8(y2.x + y2.y);
;                 if (kc == 0) ybuf[s * 64 + v] = y;
	ds_read_b128 v[168:171], v44 offset:7936
	ds_read_b128 v[172:175], v44 offset:7952
	ds_read_b128 v[176:179], v44 offset:8448
	ds_read_b128 v[180:183], v44 offset:8464
	ds_read_b128 v[184:187], v44 offset:8704
	ds_read_b128 v[188:191], v44 offset:8720
	ds_read_b64 v[192:193], v46 offset:7680
	ds_read_b128 v[148:151], v44 offset:9728
	ds_read_b128 v[152:155], v44 offset:9744
	v_add_f32_dpp v48, v48, v48 quad_perm:[1,0,3,2] row_mask:0xf bank_mask:0xf bound_ctrl:1
	v_add_f32_dpp v49, v49, v49 quad_perm:[1,0,3,2] row_mask:0xf bank_mask:0xf bound_ctrl:1
	v_add_f32_dpp v50, v50, v50 quad_perm:[1,0,3,2] row_mask:0xf bank_mask:0xf bound_ctrl:1
	v_add_f32_dpp v51, v51, v51 quad_perm:[1,0,3,2] row_mask:0xf bank_mask:0xf bound_ctrl:1
	v_pk_fma_f32 v[96:97], v[144:145], v[120:121], v[96:97] op_sel:[0,0,0] op_sel_hi:[1,0,1]
	v_pk_fma_f32 v[98:99], v[144:145], v[120:121], v[98:99] op_sel:[0,1,0] op_sel_hi:[1,1,1]
	v_pk_fma_f32 v[100:101], v[144:145], v[122:123], v[100:101] op_sel:[0,0,0] op_sel_hi:[1,0,1]
	v_add_f32_dpp v48, v48, v48 quad_perm:[2,3,0,1] row_mask:0xf bank_mask:0xf bound_ctrl:1
	v_add_f32_dpp v49, v49, v49 quad_perm:[2,3,0,1] row_mask:0xf bank_mask:0xf bound_ctrl:1
	v_add_f32_dpp v50, v50, v50 quad_perm:[2,3,0,1] row_mask:0xf bank_mask:0xf bound_ctrl:1
	v_add_f32_dpp v51, v51, v51 quad_perm:[2,3,0,1] row_mask:0xf bank_mask:0xf bound_ctrl:1
	v_pk_fma_f32 v[102:103], v[144:145], v[122:123], v[102:103] op_sel:[0,1,0] op_sel_hi:[1,1,1]
	v_pk_fma_f32 v[104:105], v[144:145], v[124:125], v[104:105] op_sel:[0,0,0] op_sel_hi:[1,0,1]
	v_pk_fma_f32 v[106:107], v[144:145], v[124:125], v[106:107] op_sel:[0,1,0] op_sel_hi:[1,1,1]
	v_add_f32_dpp v48, v48, v48 row_half_mirror row_mask:0xf bank_mask:0xf bound_ctrl:1
	v_add_f32_dpp v49, v49, v49 row_half_mirror row_mask:0xf bank_mask:0xf bound_ctrl:1
	v_add_f32_dpp v50, v50, v50 row_half_mirror row_mask:0xf bank_mask:0xf bound_ctrl:1
	v_add_f32_dpp v51, v51, v51 row_half_mirror row_mask:0xf bank_mask:0xf bound_ctrl:1
	v_pk_fma_f32 v[108:109], v[144:145], v[126:127], v[108:109] op_sel:[0,0,0] op_sel_hi:[1,0,1]
	s_mov_b64 exec, s[10:11]
	ds_write_b64 v45, v[48:49] offset:512
	s_mov_b64 exec, s[0:1]
	v_pk_fma_f32 v[110:111], v[144:145], v[126:127], v[110:111] op_sel:[0,1,0] op_sel_hi:[1,1,1]
	s_nop 0
	v_pk_fma_f32 v[96:97], v[50:51], v[128:129], v[96:97] op_sel:[0,0,0] op_sel_hi:[1,0,1]
	v_pk_fma_f32 v[98:99], v[50:51], v[128:129], v[98:99] op_sel:[0,1,0] op_sel_hi:[1,1,1]
	v_pk_fma_f32 v[100:101], v[50:51], v[130:131], v[100:101] op_sel:[0,0,0] op_sel_hi:[1,0,1]
	v_pk_fma_f32 v[102:103], v[50:51], v[130:131], v[102:103] op_sel:[0,1,0] op_sel_hi:[1,1,1]
	v_pk_fma_f32 v[104:105], v[50:51], v[132:133], v[104:105] op_sel:[0,0,0] op_sel_hi:[1,0,1]
	v_pk_fma_f32 v[106:107], v[50:51], v[132:133], v[106:107] op_sel:[0,1,0] op_sel_hi:[1,1,1]
	v_pk_fma_f32 v[108:109], v[50:51], v[134:135], v[108:109] op_sel:[0,0,0] op_sel_hi:[1,0,1]
	v_pk_fma_f32 v[110:111], v[50:51], v[134:135], v[110:111] op_sel:[0,1,0] op_sel_hi:[1,1,1]
	v_pk_mul_f32 v[14:15], v[96:97], v[136:137] op_sel:[0,0] op_sel_hi:[1,0]
	v_pk_mul_f32 v[18:19], v[96:97], v[156:157] op_sel:[0,0] op_sel_hi:[1,0]
	v_pk_mul_f32 v[16:17], v[98:99], v[136:137] op_sel:[0,1] op_sel_hi:[1,1]
	v_pk_mul_f32 v[20:21], v[98:99], v[156:157] op_sel:[0,1] op_sel_hi:[1,1]
	v_pk_fma_f32 v[14:15], v[100:101], v[138:139], v[14:15] op_sel:[0,0,0] op_sel_hi:[1,0,1]
	v_pk_fma_f32 v[18:19], v[100:101], v[158:159], v[18:19] op_sel:[0,0,0] op_sel_hi:[1,0,1]
	v_pk_fma_f32 v[16:17], v[102:103], v[138:139], v[16:17] op_sel:[0,1,0] op_sel_hi:[1,1,1]
	v_pk_fma_f32 v[20:21], v[102:103], v[158:159], v[20:21] op_sel:[0,1,0] op_sel_hi:[1,1,1]
	v_pk_fma_f32 v[14:15], v[104:105], v[140:141], v[14:15] op_sel:[0,0,0] op_sel_hi:[1,0,1]
	v_pk_fma_f32 v[18:19], v[104:105], v[160:161], v[18:19] op_sel:[0,0,0] op_sel_hi:[1,0,1]
	v_pk_fma_f32 v[16:17], v[106:107], v[140:141], v[16:17] op_sel:[0,1,0] op_sel_hi:[1,1,1]
	v_pk_fma_f32 v[20:21], v[106:107], v[160:161], v[20:21] op_sel:[0,1,0] op_sel_hi:[1,1,1]
	v_pk_fma_f32 v[14:15], v[108:109], v[142:143], v[14:15] op_sel:[0,0,0] op_sel_hi:[1,0,1]
	v_pk_fma_f32 v[18:19], v[108:109], v[162:163], v[18:19] op_sel:[0,0,0] op_sel_hi:[1,0,1]
	v_pk_fma_f32 v[16:17], v[110:111], v[142:143], v[16:17] op_sel:[0,1,0] op_sel_hi:[1,1,1]
	v_pk_fma_f32 v[20:21], v[110:111], v[162:163], v[20:21] op_sel:[0,1,0] op_sel_hi:[1,1,1]
	v_pk_add_f32 v[48:49], v[14:15], v[16:17]
	v_pk_add_f32 v[50:51], v[18:19], v[20:21]
	s_waitcnt lgkmcnt(11)
; #define LAS __attribute__((address_space(3)))
; __device__ __forceinline__ float red8(float x) { x += dpp_mov<0xB1>(x); x += dpp_mov<0x4E>(x); x += dpp_mov<0x141>(x); return x; }
; __device__ __forceinline__ void scan_phase(const KP& P, LAS unsigned char* lds, const int tid, const int bx, const int G) {
;     ...
;             for (int s = 0; s < 32; ++s) {
;                 const LAS float* p = cb + s * 384;
;                 const f32x4 w0 = *(const LAS f32x4*)(p), w1 = *(const LAS f32x4*)(p + 4);
;                 const f32x4 k0 = *(const LAS f32x4*)(p + 64), k1 = *(const LAS f32x4*)(p + 68);
;                 const f32x4 a0 = *(const LAS f32x4*)(p + 128), a1 = *(const LAS f32x4*)(p + 132);
;                 const f32x4 b0 = *(const LAS f32x4*)(p + 192), b1 = *(const LAS f32x4*)(p + 196);
;                 const f32x4 r0 = *(const LAS f32x4*)(p + 256), r1 = *(const LAS f32x4*)(p + 260);
;                 const float vv = buf[(c & 1) * 12288 + s * 384 + 320 + v];
;                 f32x2 sa2 = S[0] * (f32x2){a0.x, a0.y};
;                 sa2 += S[1] * (f32x2){a0.z, a0.w}; sa2 += S[2] * (f32x2){a1.x, a1.y}; sa2 += S[3] * (f32x2){a1.z, a1.w};
;                 const float sa = red8(sa2.x + sa2.y);
;                 const f32x2 sav = {sa, sa}, vv2 = {vv, vv};
;                 S[0] = S[0] * (f32x2){w0.x, w0.y} + sav * (f32x2){b0.x, b0.y} + vv2 * (f32x2){k0.x, k0.y};
;                 S[1] = S[1] * (f32x2){w0.z, w0.w} + sav * (f32x2){b0.z, b0.w} + vv2 * (f32x2){k0.z, k0.w};
;                 S[2] = S[2] * (f32x2){w1.x, w1.y} + sav * (f32x2){b1.x, b1.y} + vv2 * (f32x2){k1.x, k1.y};
;                 S[3] = S[3] * (f32x2){w1.z, w1.w} + sav * (f32x2){b1.z, b1.w} + vv2 * (f32x2){k1.z, k1.w};
;                 f32x2 y2 = S[0] * (f32x2){r0.x, r0.y};
;                 y2 += S[1] * (f32x2){r0.z, r0.w}; y2 += S[2] * (f32x2){r1.x, r1.y}; y2 += S[3] * (f32x2){r1.z, r1.w};
;                 const float y = red8(y2.x + y2.y);
;                 if (kc == 0) ybuf[s * 64 + v] = y;
	ds_read_b128 v[120:123], v44 offset:9472
	ds_read_b128 v[124:127], v44 offset:9488
	ds_read_b128 v[128:131], v44 offset:9984
	ds_read_b128 v[132:135], v44 offset:10000
	ds_read_b128 v[136:139], v44 offset:10240
	ds_read_b128 v[140:143], v44 offset:10256
	ds_read_b64 v[144:145], v46 offset:9216
	ds_read_b128 v[156:159], v44 offset:11264
	ds_read_b128 v[160:163], v44 offset:11280
	v_add_f32_dpp v48, v48, v48 quad_perm:[1,0,3,2] row_mask:0xf bank_mask:0xf bound_ctrl:1
	v_add_f32_dpp v49, v49, v49 quad_perm:[1,0,3,2] row_mask:0xf bank_mask:0xf bound_ctrl:1
	v_add_f32_dpp v50, v50, v50 quad_perm:[1,0,3,2] row_mask:0xf bank_mask:0xf bound_ctrl:1
	v_add_f32_dpp v51, v51, v51 quad_perm:[1,0,3,2] row_mask:0xf bank_mask:0xf bound_ctrl:1
	v_pk_fma_f32 v[96:97], v[146:147], v[70:71], v[96:97] op_sel:[0,0,0] op_sel_hi:[1,0,1]
	v_pk_fma_f32 v[98:99], v[146:147], v[70:71], v[98:99] op_sel:[0,1,0] op_sel_hi:[1,1,1]
	v_pk_fma_f32 v[100:101], v[146:147], v[72:73], v[100:101] op_sel:[0,0,0] op_sel_hi:[1,0,1]
	v_add_f32_dpp v48, v48, v48 quad_perm:[2,3,0,1] row_mask:0xf bank_mask:0xf bound_ctrl:1
	v_add_f32_dpp v49, v49, v49 quad_perm:[2,3,0,1] row_mask:0xf bank_mask:0xf bound_ctrl:1
	v_add_f32_dpp v50, v50, v50 quad_perm:[2,3,0,1] row_mask:0xf bank_mask:0xf bound_ctrl:1
	v_add_f32_dpp v51, v51, v51 quad_perm:[2,3,0,1] row_mask:0xf bank_mask:0xf bound_ctrl:1
	v_pk_fma_f32 v[102:103], v[146:147], v[72:73], v[102:103] op_sel:[0,1,0] op_sel_hi:[1,1,1]
	v_pk_fma_f32 v[104:105], v[146:147], v[74:75], v[104:105] op_sel:[0,0,0] op_sel_hi:[1,0,1]
	v_pk_fma_f32 v[106:107], v[146:147], v[74:75], v[106:107] op_sel:[0,1,0] op_sel_hi:[1,1,1]
	v_add_f32_dpp v48, v48, v48 row_half_mirror row_mask:0xf bank_mask:0xf bound_ctrl:1
	v_add_f32_dpp v49, v49, v49 row_half_mirror row_mask:0xf bank_mask:0xf bound_ctrl:1
	v_add_f32_dpp v50, v50, v50 row_half_mirror row_mask:0xf bank_mask:0xf bound_ctrl:1
	v_add_f32_dpp v51, v51, v51 row_half_mirror row_mask:0xf bank_mask:0xf bound_ctrl:1
	v_pk_fma_f32 v[108:109], v[146:147], v[76:77], v[108:109] op_sel:[0,0,0] op_sel_hi:[1,0,1]
	s_mov_b64 exec, s[10:11]
	ds_write_b64 v45, v[48:49] offset:768
	s_mov_b64 exec, s[0:1]
	v_pk_fma_f32 v[110:111], v[146:147], v[76:77], v[110:111] op_sel:[0,1,0] op_sel_hi:[1,1,1]
	s_nop 0
	v_pk_fma_f32 v[96:97], v[50:51], v[78:79], v[96:97] op_sel:[0,0,0] op_sel_hi:[1,0,1]
	v_pk_fma_f32 v[98:99], v[50:51], v[78:79], v[98:99] op_sel:[0,1,0] op_sel_hi:[1,1,1]
	v_pk_fma_f32 v[100:101], v[50:51], v[80:81], v[100:101] op_sel:[0,0,0] op_sel_hi:[1,0,1]
	v_pk_fma_f32 v[102:103], v[50:51], v[80:81], v[102:103] op_sel:[0,1,0] op_sel_hi:[1,1,1]
	v_pk_fma_f32 v[104:105], v[50:51], v[82:83], v[104:105] op_sel:[0,0,0] op_sel_hi:[1,0,1]
	v_pk_fma_f32 v[106:107], v[50:51], v[82:83], v[106:107] op_sel:[0,1,0] op_sel_hi:[1,1,1]
	v_pk_fma_f32 v[108:109], v[50:51], v[84:85], v[108:109] op_sel:[0,0,0] op_sel_hi:[1,0,1]
	v_pk_fma_f32 v[110:111], v[50:51], v[84:85], v[110:111] op_sel:[0,1,0] op_sel_hi:[1,1,1]
	v_pk_mul_f32 v[14:15], v[96:97], v[86:87] op_sel:[0,0] op_sel_hi:[1,0]
	v_pk_mul_f32 v[18:19], v[96:97], v[62:63] op_sel:[0,0] op_sel_hi:[1,0]
	v_pk_mul_f32 v[16:17], v[98:99], v[86:87] op_sel:[0,1] op_sel_hi:[1,1]
	v_pk_mul_f32 v[20:21], v[98:99], v[62:63] op_sel:[0,1] op_sel_hi:[1,1]
	v_pk_fma_f32 v[14:15], v[100:101], v[88:89], v[14:15] op_sel:[0,0,0] op_sel_hi:[1,0,1]
	v_pk_fma_f32 v[18:19], v[100:101], v[64:65], v[18:19] op_sel:[0,0,0] op_sel_hi:[1,0,1]
	v_pk_fma_f32 v[16:17], v[102:103], v[88:89], v[16:17] op_sel:[0,1,0] op_sel_hi:[1,1,1]
	v_pk_fma_f32 v[20:21], v[102:103], v[64:65], v[20:21] op_sel:[0,1,0] op_sel_hi:[1,1,1]
	v_pk_fma_f32 v[14:15], v[104:105], v[90:91], v[14:15] op_sel:[0,0,0] op_sel_hi:[1,0,1]
	v_pk_fma_f32 v[18:19], v[104:105], v[66:67], v[18:19] op_sel:[0,0,0] op_sel_hi:[1,0,1]
	v_pk_fma_f32 v[16:17], v[106:107], v[90:91], v[16:17] op_sel:[0,1,0] op_sel_hi:[1,1,1]
	v_pk_fma_f32 v[20:21], v[106:107], v[66:67], v[20:21] op_sel:[0,1,0] op_sel_hi:[1,1,1]
	v_pk_fma_f32 v[14:15], v[108:109], v[92:93], v[14:15] op_sel:[0,0,0] op_sel_hi:[1,0,1]
	v_pk_fma_f32 v[18:19], v[108:109], v[68:69], v[18:19] op_sel:[0,0,0] op_sel_hi:[1,0,1]
	v_pk_fma_f32 v[16:17], v[110:111], v[92:93], v[16:17] op_sel:[0,1,0] op_sel_hi:[1,1,1]
	v_pk_fma_f32 v[20:21], v[110:111], v[68:69], v[20:21] op_sel:[0,1,0] op_sel_hi:[1,1,1]
	v_pk_add_f32 v[48:49], v[14:15], v[16:17]
	v_pk_add_f32 v[50:51], v[18:19], v[20:21]
	s_waitcnt lgkmcnt(11)
; #define LAS __attribute__((address_space(3)))
; __device__ __forceinline__ float red8(float x) { x += dpp_mov<0xB1>(x); x += dpp_mov<0x4E>(x); x += dpp_mov<0x141>(x); return x; }
; __device__ __forceinline__ void scan_phase(const KP& P, LAS unsigned char* lds, const int tid, const int bx, const int G) {
;     ...
;             for (int s = 0; s < 32; ++s) {
;                 const LAS float* p = cb + s * 384;
;                 const f32x4 w0 = *(const LAS f32x4*)(p), w1 = *(const LAS f32x4*)(p + 4);
;                 const f32x4 k0 = *(const LAS f32x4*)(p + 64), k1 = *(const LAS f32x4*)(p + 68);
;                 const f32x4 a0 = *(const LAS f32x4*)(p + 128), a1 = *(const LAS f32x4*)(p + 132);
;                 const f32x4 b0 = *(const LAS f32x4*)(p + 192), b1 = *(const LAS f32x4*)(p + 196);
;                 const f32x4 r0 = *(const LAS f32x4*)(p + 256), r1 = *(const LAS f32x4*)(p + 260);
;                 const float vv = buf[(c & 1) * 12288 + s * 384 + 320 + v];
;                 f32x2 sa2 = S[0] * (f32x2){a0.x, a0.y};
;                 sa2 += S[1] * (f32x2){a0.z, a0.w}; sa2 += S[2] * (f32x2){a1.x, a1.y}; sa2 += S[3] * (f32x2){a1.z, a1.w};
;                 const float sa = red8(sa2.x + sa2.y);
;                 const f32x2 sav = {sa, sa}, vv2 = {vv, vv};
;                 S[0] = S[0] * (f32x2){w0.x, w0.y} + sav * (f32x2){b0.x, b0.y} + vv2 * (f32x2){k0.x, k0.y};
;                 S[1] = S[1] * (f32x2){w0.z, w0.w} + sav * (f32x2){b0.z, b0.w} + vv2 * (f32x2){k0.z, k0.w};
;                 S[2] = S[2] * (f32x2){w1.x, w1.y} + sav * (f32x2){b1.x, b1.y} + vv2 * (f32x2){k1.x, k1.y};
;                 S[3] = S[3] * (f32x2){w1.z, w1.w} + sav * (f32x2){b1.z, b1.w} + vv2 * (f32x2){k1.z, k1.w};
;                 f32x2 y2 = S[0] * (f32x2){r0.x, r0.y};
;                 y2 += S[1] * (f32x2){r0.z, r0.w}; y2 += S[2] * (f32x2){r1.x, r1.y}; y2 += S[3] * (f32x2){r1.z, r1.w};
;                 const float y = red8(y2.x + y2.y);
;                 if (kc == 0) ybuf[s * 64 + v] = y;
	ds_read_b128 v[70:73], v44 offset:11008
	ds_read_b128 v[74:77], v44 offset:11024
	ds_read_b128 v[78:81], v44 offset:11520
	ds_read_b128 v[82:85], v44 offset:11536
	ds_read_b128 v[86:89], v44 offset:11776
	ds_read_b128 v[90:93], v44 offset:11792
	ds_read_b64 v[146:147], v46 offset:10752
	ds_read_b128 v[62:65], v44 offset:12800
	ds_read_b128 v[66:69], v44 offset:12816
	v_add_f32_dpp v48, v48, v48 quad_perm:[1,0,3,2] row_mask:0xf bank_mask:0xf bound_ctrl:1
	v_add_f32_dpp v49, v49, v49 quad_perm:[1,0,3,2] row_mask:0xf bank_mask:0xf bound_ctrl:1
	v_add_f32_dpp v50, v50, v50 quad_perm:[1,0,3,2] row_mask:0xf bank_mask:0xf bound_ctrl:1
	v_add_f32_dpp v51, v51, v51 quad_perm:[1,0,3,2] row_mask:0xf bank_mask:0xf bound_ctrl:1
	v_pk_fma_f32 v[96:97], v[192:193], v[168:169], v[96:97] op_sel:[0,0,0] op_sel_hi:[1,0,1]
	v_pk_fma_f32 v[98:99], v[192:193], v[168:169], v[98:99] op_sel:[0,1,0] op_sel_hi:[1,1,1]
	v_pk_fma_f32 v[100:101], v[192:193], v[170:171], v[100:101] op_sel:[0,0,0] op_sel_hi:[1,0,1]
	v_add_f32_dpp v48, v48, v48 quad_perm:[2,3,0,1] row_mask:0xf bank_mask:0xf bound_ctrl:1
	v_add_f32_dpp v49, v49, v49 quad_perm:[2,3,0,1] row_mask:0xf bank_mask:0xf bound_ctrl:1
	v_add_f32_dpp v50, v50, v50 quad_perm:[2,3,0,1] row_mask:0xf bank_mask:0xf bound_ctrl:1
	v_add_f32_dpp v51, v51, v51 quad_perm:[2,3,0,1] row_mask:0xf bank_mask:0xf bound_ctrl:1
	v_pk_fma_f32 v[102:103], v[192:193], v[170:171], v[102:103] op_sel:[0,1,0] op_sel_hi:[1,1,1]
	v_pk_fma_f32 v[104:105], v[192:193], v[172:173], v[104:105] op_sel:[0,0,0] op_sel_hi:[1,0,1]
	v_pk_fma_f32 v[106:107], v[192:193], v[172:173], v[106:107] op_sel:[0,1,0] op_sel_hi:[1,1,1]
	v_add_f32_dpp v48, v48, v48 row_half_mirror row_mask:0xf bank_mask:0xf bound_ctrl:1
	v_add_f32_dpp v49, v49, v49 row_half_mirror row_mask:0xf bank_mask:0xf bound_ctrl:1
	v_add_f32_dpp v50, v50, v50 row_half_mirror row_mask:0xf bank_mask:0xf bound_ctrl:1
	v_add_f32_dpp v51, v51, v51 row_half_mirror row_mask:0xf bank_mask:0xf bound_ctrl:1
	v_pk_fma_f32 v[108:109], v[192:193], v[174:175], v[108:109] op_sel:[0,0,0] op_sel_hi:[1,0,1]
	s_mov_b64 exec, s[10:11]
	ds_write_b64 v45, v[48:49] offset:1024
	s_mov_b64 exec, s[0:1]
	v_pk_fma_f32 v[110:111], v[192:193], v[174:175], v[110:111] op_sel:[0,1,0] op_sel_hi:[1,1,1]
	s_nop 0
	v_pk_fma_f32 v[96:97], v[50:51], v[176:177], v[96:97] op_sel:[0,0,0] op_sel_hi:[1,0,1]
	v_pk_fma_f32 v[98:99], v[50:51], v[176:177], v[98:99] op_sel:[0,1,0] op_sel_hi:[1,1,1]
	v_pk_fma_f32 v[100:101], v[50:51], v[178:179], v[100:101] op_sel:[0,0,0] op_sel_hi:[1,0,1]
	v_pk_fma_f32 v[102:103], v[50:51], v[178:179], v[102:103] op_sel:[0,1,0] op_sel_hi:[1,1,1]
	v_pk_fma_f32 v[104:105], v[50:51], v[180:181], v[104:105] op_sel:[0,0,0] op_sel_hi:[1,0,1]
	v_pk_fma_f32 v[106:107], v[50:51], v[180:181], v[106:107] op_sel:[0,1,0] op_sel_hi:[1,1,1]
	v_pk_fma_f32 v[108:109], v[50:51], v[182:183], v[108:109] op_sel:[0,0,0] op_sel_hi:[1,0,1]
	v_pk_fma_f32 v[110:111], v[50:51], v[182:183], v[110:111] op_sel:[0,1,0] op_sel_hi:[1,1,1]
	v_pk_mul_f32 v[14:15], v[96:97], v[184:185] op_sel:[0,0] op_sel_hi:[1,0]
	v_pk_mul_f32 v[18:19], v[96:97], v[148:149] op_sel:[0,0] op_sel_hi:[1,0]
	v_pk_mul_f32 v[16:17], v[98:99], v[184:185] op_sel:[0,1] op_sel_hi:[1,1]
	v_pk_mul_f32 v[20:21], v[98:99], v[148:149] op_sel:[0,1] op_sel_hi:[1,1]
	v_pk_fma_f32 v[14:15], v[100:101], v[186:187], v[14:15] op_sel:[0,0,0] op_sel_hi:[1,0,1]
	v_pk_fma_f32 v[18:19], v[100:101], v[150:151], v[18:19] op_sel:[0,0,0] op_sel_hi:[1,0,1]
	v_pk_fma_f32 v[16:17], v[102:103], v[186:187], v[16:17] op_sel:[0,1,0] op_sel_hi:[1,1,1]
	v_pk_fma_f32 v[20:21], v[102:103], v[150:151], v[20:21] op_sel:[0,1,0] op_sel_hi:[1,1,1]
	v_pk_fma_f32 v[14:15], v[104:105], v[188:189], v[14:15] op_sel:[0,0,0] op_sel_hi:[1,0,1]
	v_pk_fma_f32 v[18:19], v[104:105], v[152:153], v[18:19] op_sel:[0,0,0] op_sel_hi:[1,0,1]
	v_pk_fma_f32 v[16:17], v[106:107], v[188:189], v[16:17] op_sel:[0,1,0] op_sel_hi:[1,1,1]
	v_pk_fma_f32 v[20:21], v[106:107], v[152:153], v[20:21] op_sel:[0,1,0] op_sel_hi:[1,1,1]
	v_pk_fma_f32 v[14:15], v[108:109], v[190:191], v[14:15] op_sel:[0,0,0] op_sel_hi:[1,0,1]
	v_pk_fma_f32 v[18:19], v[108:109], v[154:155], v[18:19] op_sel:[0,0,0] op_sel_hi:[1,0,1]
	v_pk_fma_f32 v[16:17], v[110:111], v[190:191], v[16:17] op_sel:[0,1,0] op_sel_hi:[1,1,1]
	v_pk_fma_f32 v[20:21], v[110:111], v[154:155], v[20:21] op_sel:[0,1,0] op_sel_hi:[1,1,1]
	v_pk_add_f32 v[48:49], v[14:15], v[16:17]
	v_pk_add_f32 v[50:51], v[18:19], v[20:21]
	s_waitcnt lgkmcnt(11)
; #define LAS __attribute__((address_space(3)))
; __device__ __forceinline__ float red8(float x) { x += dpp_mov<0xB1>(x); x += dpp_mov<0x4E>(x); x += dpp_mov<0x141>(x); return x; }
; __device__ __forceinline__ void scan_phase(const KP& P, LAS unsigned char* lds, const int tid, const int bx, const int G) {
;     ...
;             for (int s = 0; s < 32; ++s) {
;                 const LAS float* p = cb + s * 384;
;                 const f32x4 w0 = *(const LAS f32x4*)(p), w1 = *(const LAS f32x4*)(p + 4);
;                 const f32x4 k0 = *(const LAS f32x4*)(p + 64), k1 = *(const LAS f32x4*)(p + 68);
;                 const f32x4 a0 = *(const LAS f32x4*)(p + 128), a1 = *(const LAS f32x4*)(p + 132);
;                 const f32x4 b0 = *(const LAS f32x4*)(p + 192), b1 = *(const LAS f32x4*)(p + 196);
;                 const f32x4 r0 = *(const LAS f32x4*)(p + 256), r1 = *(const LAS f32x4*)(p + 260);
;                 const float vv = buf[(c & 1) * 12288 + s * 384 + 320 + v];
;                 f32x2 sa2 = S[0] * (f32x2){a0.x, a0.y};
;                 sa2 += S[1] * (f32x2){a0.z, a0.w}; sa2 += S[2] * (f32x2){a1.x, a1.y}; sa2 += S[3] * (f32x2){a1.z, a1.w};
;                 const float sa = red8(sa2.x + sa2.y);
;                 const f32x2 sav = {sa, sa}, vv2 = {vv, vv};
;                 S[0] = S[0] * (f32x2){w0.x, w0.y} + sav * (f32x2){b0.x, b0.y} + vv2 * (f32x2){k0.x, k0.y};
;                 S[1] = S[1] * (f32x2){w0.z, w0.w} + sav * (f32x2){b0.z, b0.w} + vv2 * (f32x2){k0.z, k0.w};
;                 S[2] = S[2] * (f32x2){w1.x, w1.y} + sav * (f32x2){b1.x, b1.y} + vv2 * (f32x2){k1.x, k1.y};
;                 S[3] = S[3] * (f32x2){w1.z, w1.w} + sav * (f32x2){b1.z, b1.w} + vv2 * (f32x2){k1.z, k1.w};
;                 f32x2 y2 = S[0] * (f32x2){r0.x, r0.y};
;                 y2 += S[1] * (f32x2){r0.z, r0.w}; y2 += S[2] * (f32x2){r1.x, r1.y}; y2 += S[3] * (f32x2){r1.z, r1.w};
;                 const float y = red8(y2.x + y2.y);
;                 if (kc == 0) ybuf[s * 64 + v] = y;
	ds_read_b128 v[168:171], v44 offset:12544
	ds_read_b128 v[172:175], v44 offset:12560
	ds_read_b128 v[176:179], v44 offset:13056
	ds_read_b128 v[180:183], v44 offset:13072
	ds_read_b128 v[184:187], v44 offset:13312
	ds_read_b128 v[188:191], v44 offset:13328
	ds_read_b64 v[192:193], v46 offset:12288
	ds_read_b128 v[148:151], v44 offset:14336
	ds_read_b128 v[152:155], v44 offset:14352
	v_add_f32_dpp v48, v48, v48 quad_perm:[1,0,3,2] row_mask:0xf bank_mask:0xf bound_ctrl:1
	v_add_f32_dpp v49, v49, v49 quad_perm:[1,0,3,2] row_mask:0xf bank_mask:0xf bound_ctrl:1
	v_add_f32_dpp v50, v50, v50 quad_perm:[1,0,3,2] row_mask:0xf bank_mask:0xf bound_ctrl:1
	v_add_f32_dpp v51, v51, v51 quad_perm:[1,0,3,2] row_mask:0xf bank_mask:0xf bound_ctrl:1
	v_pk_fma_f32 v[96:97], v[144:145], v[120:121], v[96:97] op_sel:[0,0,0] op_sel_hi:[1,0,1]
	v_pk_fma_f32 v[98:99], v[144:145], v[120:121], v[98:99] op_sel:[0,1,0] op_sel_hi:[1,1,1]
	v_pk_fma_f32 v[100:101], v[144:145], v[122:123], v[100:101] op_sel:[0,0,0] op_sel_hi:[1,0,1]
	v_add_f32_dpp v48, v48, v48 quad_perm:[2,3,0,1] row_mask:0xf bank_mask:0xf bound_ctrl:1
	v_add_f32_dpp v49, v49, v49 quad_perm:[2,3,0,1] row_mask:0xf bank_mask:0xf bound_ctrl:1
	v_add_f32_dpp v50, v50, v50 quad_perm:[2,3,0,1] row_mask:0xf bank_mask:0xf bound_ctrl:1
	v_add_f32_dpp v51, v51, v51 quad_perm:[2,3,0,1] row_mask:0xf bank_mask:0xf bound_ctrl:1
	v_pk_fma_f32 v[102:103], v[144:145], v[122:123], v[102:103] op_sel:[0,1,0] op_sel_hi:[1,1,1]
	v_pk_fma_f32 v[104:105], v[144:145], v[124:125], v[104:105] op_sel:[0,0,0] op_sel_hi:[1,0,1]
	v_pk_fma_f32 v[106:107], v[144:145], v[124:125], v[106:107] op_sel:[0,1,0] op_sel_hi:[1,1,1]
	v_add_f32_dpp v48, v48, v48 row_half_mirror row_mask:0xf bank_mask:0xf bound_ctrl:1
	v_add_f32_dpp v49, v49, v49 row_half_mirror row_mask:0xf bank_mask:0xf bound_ctrl:1
	v_add_f32_dpp v50, v50, v50 row_half_mirror row_mask:0xf bank_mask:0xf bound_ctrl:1
	v_add_f32_dpp v51, v51, v51 row_half_mirror row_mask:0xf bank_mask:0xf bound_ctrl:1
	v_pk_fma_f32 v[108:109], v[144:145], v[126:127], v[108:109] op_sel:[0,0,0] op_sel_hi:[1,0,1]
	s_mov_b64 exec, s[10:11]
	ds_write_b64 v45, v[48:49] offset:1280
	s_mov_b64 exec, s[0:1]
	v_pk_fma_f32 v[110:111], v[144:145], v[126:127], v[110:111] op_sel:[0,1,0] op_sel_hi:[1,1,1]
	s_nop 0
	v_pk_fma_f32 v[96:97], v[50:51], v[128:129], v[96:97] op_sel:[0,0,0] op_sel_hi:[1,0,1]
	v_pk_fma_f32 v[98:99], v[50:51], v[128:129], v[98:99] op_sel:[0,1,0] op_sel_hi:[1,1,1]
	v_pk_fma_f32 v[100:101], v[50:51], v[130:131], v[100:101] op_sel:[0,0,0] op_sel_hi:[1,0,1]
	v_pk_fma_f32 v[102:103], v[50:51], v[130:131], v[102:103] op_sel:[0,1,0] op_sel_hi:[1,1,1]
	v_pk_fma_f32 v[104:105], v[50:51], v[132:133], v[104:105] op_sel:[0,0,0] op_sel_hi:[1,0,1]
	v_pk_fma_f32 v[106:107], v[50:51], v[132:133], v[106:107] op_sel:[0,1,0] op_sel_hi:[1,1,1]
	v_pk_fma_f32 v[108:109], v[50:51], v[134:135], v[108:109] op_sel:[0,0,0] op_sel_hi:[1,0,1]
	v_pk_fma_f32 v[110:111], v[50:51], v[134:135], v[110:111] op_sel:[0,1,0] op_sel_hi:[1,1,1]
	v_pk_mul_f32 v[14:15], v[96:97], v[136:137] op_sel:[0,0] op_sel_hi:[1,0]
	v_pk_mul_f32 v[18:19], v[96:97], v[156:157] op_sel:[0,0] op_sel_hi:[1,0]
	v_pk_mul_f32 v[16:17], v[98:99], v[136:137] op_sel:[0,1] op_sel_hi:[1,1]
	v_pk_mul_f32 v[20:21], v[98:99], v[156:157] op_sel:[0,1] op_sel_hi:[1,1]
	v_pk_fma_f32 v[14:15], v[100:101], v[138:139], v[14:15] op_sel:[0,0,0] op_sel_hi:[1,0,1]
	v_pk_fma_f32 v[18:19], v[100:101], v[158:159], v[18:19] op_sel:[0,0,0] op_sel_hi:[1,0,1]
	v_pk_fma_f32 v[16:17], v[102:103], v[138:139], v[16:17] op_sel:[0,1,0] op_sel_hi:[1,1,1]
	v_pk_fma_f32 v[20:21], v[102:103], v[158:159], v[20:21] op_sel:[0,1,0] op_sel_hi:[1,1,1]
	v_pk_fma_f32 v[14:15], v[104:105], v[140:141], v[14:15] op_sel:[0,0,0] op_sel_hi:[1,0,1]
	v_pk_fma_f32 v[18:19], v[104:105], v[160:161], v[18:19] op_sel:[0,0,0] op_sel_hi:[1,0,1]
	v_pk_fma_f32 v[16:17], v[106:107], v[140:141], v[16:17] op_sel:[0,1,0] op_sel_hi:[1,1,1]
	v_pk_fma_f32 v[20:21], v[106:107], v[160:161], v[20:21] op_sel:[0,1,0] op_sel_hi:[1,1,1]
	v_pk_fma_f32 v[14:15], v[108:109], v[142:143], v[14:15] op_sel:[0,0,0] op_sel_hi:[1,0,1]
	v_pk_fma_f32 v[18:19], v[108:109], v[162:163], v[18:19] op_sel:[0,0,0] op_sel_hi:[1,0,1]
	v_pk_fma_f32 v[16:17], v[110:111], v[142:143], v[16:17] op_sel:[0,1,0] op_sel_hi:[1,1,1]
	v_pk_fma_f32 v[20:21], v[110:111], v[162:163], v[20:21] op_sel:[0,1,0] op_sel_hi:[1,1,1]
	v_pk_add_f32 v[48:49], v[14:15], v[16:17]
	v_pk_add_f32 v[50:51], v[18:19], v[20:21]
	s_waitcnt lgkmcnt(11)
; #define LAS __attribute__((address_space(3)))
; __device__ __forceinline__ float red8(float x) { x += dpp_mov<0xB1>(x); x += dpp_mov<0x4E>(x); x += dpp_mov<0x141>(x); return x; }
; __device__ __forceinline__ void scan_phase(const KP& P, LAS unsigned char* lds, const int tid, const int bx, const int G) {
;     ...
;             for (int s = 0; s < 32; ++s) {
;                 const LAS float* p = cb + s * 384;
;                 const f32x4 w0 = *(const LAS f32x4*)(p), w1 = *(const LAS f32x4*)(p + 4);
;                 const f32x4 k0 = *(const LAS f32x4*)(p + 64), k1 = *(const LAS f32x4*)(p + 68);
;                 const f32x4 a0 = *(const LAS f32x4*)(p + 128), a1 = *(const LAS f32x4*)(p + 132);
;                 const f32x4 b0 = *(const LAS f32x4*)(p + 192), b1 = *(const LAS f32x4*)(p + 196);
;                 const f32x4 r0 = *(const LAS f32x4*)(p + 256), r1 = *(const LAS f32x4*)(p + 260);
;                 const float vv = buf[(c & 1) * 12288 + s * 384 + 320 + v];
;                 f32x2 sa2 = S[0] * (f32x2){a0.x, a0.y};
;                 sa2 += S[1] * (f32x2){a0.z, a0.w}; sa2 += S[2] * (f32x2){a1.x, a1.y}; sa2 += S[3] * (f32x2){a1.z, a1.w};
;                 const float sa = red8(sa2.x + sa2.y);
;                 const f32x2 sav = {sa, sa}, vv2 = {vv, vv};
;                 S[0] = S[0] * (f32x2){w0.x, w0.y} + sav * (f32x2){b0.x, b0.y} + vv2 * (f32x2){k0.x, k0.y};
;                 S[1] = S[1] * (f32x2){w0.z, w0.w} + sav * (f32x2){b0.z, b0.w} + vv2 * (f32x2){k0.z, k0.w};
;                 S[2] = S[2] * (f32x2){w1.x, w1.y} + sav * (f32x2){b1.x, b1.y} + vv2 * (f32x2){k1.x, k1.y};
;                 S[3] = S[3] * (f32x2){w1.z, w1.w} + sav * (f32x2){b1.z, b1.w} + vv2 * (f32x2){k1.z, k1.w};
;                 f32x2 y2 = S[0] * (f32x2){r0.x, r0.y};
;                 y2 += S[1] * (f32x2){r0.z, r0.w}; y2 += S[2] * (f32x2){r1.x, r1.y}; y2 += S[3] * (f32x2){r1.z, r1.w};
;                 const float y = red8(y2.x + y2.y);
;                 if (kc == 0) ybuf[s * 64 + v] = y;
	ds_read_b128 v[120:123], v44 offset:14080
	ds_read_b128 v[124:127], v44 offset:14096
	ds_read_b128 v[128:131], v44 offset:14592
	ds_read_b128 v[132:135], v44 offset:14608
	ds_read_b128 v[136:139], v44 offset:14848
	ds_read_b128 v[140:143], v44 offset:14864
	ds_read_b64 v[144:145], v46 offset:13824
	ds_read_b128 v[156:159], v44 offset:15872
	ds_read_b128 v[160:163], v44 offset:15888
	v_add_f32_dpp v48, v48, v48 quad_perm:[1,0,3,2] row_mask:0xf bank_mask:0xf bound_ctrl:1
	v_add_f32_dpp v49, v49, v49 quad_perm:[1,0,3,2] row_mask:0xf bank_mask:0xf bound_ctrl:1
	v_add_f32_dpp v50, v50, v50 quad_perm:[1,0,3,2] row_mask:0xf bank_mask:0xf bound_ctrl:1
	v_add_f32_dpp v51, v51, v51 quad_perm:[1,0,3,2] row_mask:0xf bank_mask:0xf bound_ctrl:1
	v_pk_fma_f32 v[96:97], v[146:147], v[70:71], v[96:97] op_sel:[0,0,0] op_sel_hi:[1,0,1]
	v_pk_fma_f32 v[98:99], v[146:147], v[70:71], v[98:99] op_sel:[0,1,0] op_sel_hi:[1,1,1]
	v_pk_fma_f32 v[100:101], v[146:147], v[72:73], v[100:101] op_sel:[0,0,0] op_sel_hi:[1,0,1]
	v_add_f32_dpp v48, v48, v48 quad_perm:[2,3,0,1] row_mask:0xf bank_mask:0xf bound_ctrl:1
	v_add_f32_dpp v49, v49, v49 quad_perm:[2,3,0,1] row_mask:0xf bank_mask:0xf bound_ctrl:1
	v_add_f32_dpp v50, v50, v50 quad_perm:[2,3,0,1] row_mask:0xf bank_mask:0xf bound_ctrl:1
	v_add_f32_dpp v51, v51, v51 quad_perm:[2,3,0,1] row_mask:0xf bank_mask:0xf bound_ctrl:1
	v_pk_fma_f32 v[102:103], v[146:147], v[72:73], v[102:103] op_sel:[0,1,0] op_sel_hi:[1,1,1]
	v_pk_fma_f32 v[104:105], v[146:147], v[74:75], v[104:105] op_sel:[0,0,0] op_sel_hi:[1,0,1]
	v_pk_fma_f32 v[106:107], v[146:147], v[74:75], v[106:107] op_sel:[0,1,0] op_sel_hi:[1,1,1]
	v_add_f32_dpp v48, v48, v48 row_half_mirror row_mask:0xf bank_mask:0xf bound_ctrl:1
	v_add_f32_dpp v49, v49, v49 row_half_mirror row_mask:0xf bank_mask:0xf bound_ctrl:1
	v_add_f32_dpp v50, v50, v50 row_half_mirror row_mask:0xf bank_mask:0xf bound_ctrl:1
	v_add_f32_dpp v51, v51, v51 row_half_mirror row_mask:0xf bank_mask:0xf bound_ctrl:1
	v_pk_fma_f32 v[108:109], v[146:147], v[76:77], v[108:109] op_sel:[0,0,0] op_sel_hi:[1,0,1]
	s_mov_b64 exec, s[10:11]
	ds_write_b64 v45, v[48:49] offset:1536
	s_mov_b64 exec, s[0:1]
	v_pk_fma_f32 v[110:111], v[146:147], v[76:77], v[110:111] op_sel:[0,1,0] op_sel_hi:[1,1,1]
	s_nop 0
	v_pk_fma_f32 v[96:97], v[50:51], v[78:79], v[96:97] op_sel:[0,0,0] op_sel_hi:[1,0,1]
	v_pk_fma_f32 v[98:99], v[50:51], v[78:79], v[98:99] op_sel:[0,1,0] op_sel_hi:[1,1,1]
	v_pk_fma_f32 v[100:101], v[50:51], v[80:81], v[100:101] op_sel:[0,0,0] op_sel_hi:[1,0,1]
	v_pk_fma_f32 v[102:103], v[50:51], v[80:81], v[102:103] op_sel:[0,1,0] op_sel_hi:[1,1,1]
	v_pk_fma_f32 v[104:105], v[50:51], v[82:83], v[104:105] op_sel:[0,0,0] op_sel_hi:[1,0,1]
	v_pk_fma_f32 v[106:107], v[50:51], v[82:83], v[106:107] op_sel:[0,1,0] op_sel_hi:[1,1,1]
	v_pk_fma_f32 v[108:109], v[50:51], v[84:85], v[108:109] op_sel:[0,0,0] op_sel_hi:[1,0,1]
	v_pk_fma_f32 v[110:111], v[50:51], v[84:85], v[110:111] op_sel:[0,1,0] op_sel_hi:[1,1,1]
	v_pk_mul_f32 v[14:15], v[96:97], v[86:87] op_sel:[0,0] op_sel_hi:[1,0]
	v_pk_mul_f32 v[18:19], v[96:97], v[62:63] op_sel:[0,0] op_sel_hi:[1,0]
	v_pk_mul_f32 v[16:17], v[98:99], v[86:87] op_sel:[0,1] op_sel_hi:[1,1]
	v_pk_mul_f32 v[20:21], v[98:99], v[62:63] op_sel:[0,1] op_sel_hi:[1,1]
	v_pk_fma_f32 v[14:15], v[100:101], v[88:89], v[14:15] op_sel:[0,0,0] op_sel_hi:[1,0,1]
	v_pk_fma_f32 v[18:19], v[100:101], v[64:65], v[18:19] op_sel:[0,0,0] op_sel_hi:[1,0,1]
	v_pk_fma_f32 v[16:17], v[102:103], v[88:89], v[16:17] op_sel:[0,1,0] op_sel_hi:[1,1,1]
	v_pk_fma_f32 v[20:21], v[102:103], v[64:65], v[20:21] op_sel:[0,1,0] op_sel_hi:[1,1,1]
	v_pk_fma_f32 v[14:15], v[104:105], v[90:91], v[14:15] op_sel:[0,0,0] op_sel_hi:[1,0,1]
	v_pk_fma_f32 v[18:19], v[104:105], v[66:67], v[18:19] op_sel:[0,0,0] op_sel_hi:[1,0,1]
	v_pk_fma_f32 v[16:17], v[106:107], v[90:91], v[16:17] op_sel:[0,1,0] op_sel_hi:[1,1,1]
	v_pk_fma_f32 v[20:21], v[106:107], v[66:67], v[20:21] op_sel:[0,1,0] op_sel_hi:[1,1,1]
	v_pk_fma_f32 v[14:15], v[108:109], v[92:93], v[14:15] op_sel:[0,0,0] op_sel_hi:[1,0,1]
	v_pk_fma_f32 v[18:19], v[108:109], v[68:69], v[18:19] op_sel:[0,0,0] op_sel_hi:[1,0,1]
	v_pk_fma_f32 v[16:17], v[110:111], v[92:93], v[16:17] op_sel:[0,1,0] op_sel_hi:[1,1,1]
	v_pk_fma_f32 v[20:21], v[110:111], v[68:69], v[20:21] op_sel:[0,1,0] op_sel_hi:[1,1,1]
	v_pk_add_f32 v[48:49], v[14:15], v[16:17]
	v_pk_add_f32 v[50:51], v[18:19], v[20:21]
	s_waitcnt lgkmcnt(11)
; #define LAS __attribute__((address_space(3)))
; __device__ __forceinline__ float red8(float x) { x += dpp_mov<0xB1>(x); x += dpp_mov<0x4E>(x); x += dpp_mov<0x141>(x); return x; }
; __device__ __forceinline__ void scan_phase(const KP& P, LAS unsigned char* lds, const int tid, const int bx, const int G) {
;     ...
;             for (int s = 0; s < 32; ++s) {
;                 const LAS float* p = cb + s * 384;
;                 const f32x4 w0 = *(const LAS f32x4*)(p), w1 = *(const LAS f32x4*)(p + 4);
;                 const f32x4 k0 = *(const LAS f32x4*)(p + 64), k1 = *(const LAS f32x4*)(p + 68);
;                 const f32x4 a0 = *(const LAS f32x4*)(p + 128), a1 = *(const LAS f32x4*)(p + 132);
;                 const f32x4 b0 = *(const LAS f32x4*)(p + 192), b1 = *(const LAS f32x4*)(p + 196);
;                 const f32x4 r0 = *(const LAS f32x4*)(p + 256), r1 = *(const LAS f32x4*)(p + 260);
;                 const float vv = buf[(c & 1) * 12288 + s * 384 + 320 + v];
;                 f32x2 sa2 = S[0] * (f32x2){a0.x, a0.y};
;                 sa2 += S[1] * (f32x2){a0.z, a0.w}; sa2 += S[2] * (f32x2){a1.x, a1.y}; sa2 += S[3] * (f32x2){a1.z, a1.w};
;                 const float sa = red8(sa2.x + sa2.y);
;                 const f32x2 sav = {sa, sa}, vv2 = {vv, vv};
;                 S[0] = S[0] * (f32x2){w0.x, w0.y} + sav * (f32x2){b0.x, b0.y} + vv2 * (f32x2){k0.x, k0.y};
;                 S[1] = S[1] * (f32x2){w0.z, w0.w} + sav * (f32x2){b0.z, b0.w} + vv2 * (f32x2){k0.z, k0.w};
;                 S[2] = S[2] * (f32x2){w1.x, w1.y} + sav * (f32x2){b1.x, b1.y} + vv2 * (f32x2){k1.x, k1.y};
;                 S[3] = S[3] * (f32x2){w1.z, w1.w} + sav * (f32x2){b1.z, b1.w} + vv2 * (f32x2){k1.z, k1.w};
;                 f32x2 y2 = S[0] * (f32x2){r0.x, r0.y};
;                 y2 += S[1] * (f32x2){r0.z, r0.w}; y2 += S[2] * (f32x2){r1.x, r1.y}; y2 += S[3] * (f32x2){r1.z, r1.w};
;                 const float y = red8(y2.x + y2.y);
;                 if (kc == 0) ybuf[s * 64 + v] = y;
	ds_read_b128 v[70:73], v44 offset:15616
	ds_read_b128 v[74:77], v44 offset:15632
	ds_read_b128 v[78:81], v44 offset:16128
	ds_read_b128 v[82:85], v44 offset:16144
	ds_read_b128 v[86:89], v44 offset:16384
	ds_read_b128 v[90:93], v44 offset:16400
	ds_read_b64 v[146:147], v46 offset:15360
	ds_read_b128 v[62:65], v44 offset:17408
	ds_read_b128 v[66:69], v44 offset:17424
	v_add_f32_dpp v48, v48, v48 quad_perm:[1,0,3,2] row_mask:0xf bank_mask:0xf bound_ctrl:1
	v_add_f32_dpp v49, v49, v49 quad_perm:[1,0,3,2] row_mask:0xf bank_mask:0xf bound_ctrl:1
	v_add_f32_dpp v50, v50, v50 quad_perm:[1,0,3,2] row_mask:0xf bank_mask:0xf bound_ctrl:1
	v_add_f32_dpp v51, v51, v51 quad_perm:[1,0,3,2] row_mask:0xf bank_mask:0xf bound_ctrl:1
	v_pk_fma_f32 v[96:97], v[192:193], v[168:169], v[96:97] op_sel:[0,0,0] op_sel_hi:[1,0,1]
	v_pk_fma_f32 v[98:99], v[192:193], v[168:169], v[98:99] op_sel:[0,1,0] op_sel_hi:[1,1,1]
	v_pk_fma_f32 v[100:101], v[192:193], v[170:171], v[100:101] op_sel:[0,0,0] op_sel_hi:[1,0,1]
	v_add_f32_dpp v48, v48, v48 quad_perm:[2,3,0,1] row_mask:0xf bank_mask:0xf bound_ctrl:1
	v_add_f32_dpp v49, v49, v49 quad_perm:[2,3,0,1] row_mask:0xf bank_mask:0xf bound_ctrl:1
	v_add_f32_dpp v50, v50, v50 quad_perm:[2,3,0,1] row_mask:0xf bank_mask:0xf bound_ctrl:1
	v_add_f32_dpp v51, v51, v51 quad_perm:[2,3,0,1] row_mask:0xf bank_mask:0xf bound_ctrl:1
	v_pk_fma_f32 v[102:103], v[192:193], v[170:171], v[102:103] op_sel:[0,1,0] op_sel_hi:[1,1,1]
	v_pk_fma_f32 v[104:105], v[192:193], v[172:173], v[104:105] op_sel:[0,0,0] op_sel_hi:[1,0,1]
	v_pk_fma_f32 v[106:107], v[192:193], v[172:173], v[106:107] op_sel:[0,1,0] op_sel_hi:[1,1,1]
	v_add_f32_dpp v48, v48, v48 row_half_mirror row_mask:0xf bank_mask:0xf bound_ctrl:1
	v_add_f32_dpp v49, v49, v49 row_half_mirror row_mask:0xf bank_mask:0xf bound_ctrl:1
	v_add_f32_dpp v50, v50, v50 row_half_mirror row_mask:0xf bank_mask:0xf bound_ctrl:1
	v_add_f32_dpp v51, v51, v51 row_half_mirror row_mask:0xf bank_mask:0xf bound_ctrl:1
	v_pk_fma_f32 v[108:109], v[192:193], v[174:175], v[108:109] op_sel:[0,0,0] op_sel_hi:[1,0,1]
	s_mov_b64 exec, s[10:11]
	ds_write_b64 v45, v[48:49] offset:1792
	s_mov_b64 exec, s[0:1]
	v_pk_fma_f32 v[110:111], v[192:193], v[174:175], v[110:111] op_sel:[0,1,0] op_sel_hi:[1,1,1]
	s_nop 0
	v_pk_fma_f32 v[96:97], v[50:51], v[176:177], v[96:97] op_sel:[0,0,0] op_sel_hi:[1,0,1]
	v_pk_fma_f32 v[98:99], v[50:51], v[176:177], v[98:99] op_sel:[0,1,0] op_sel_hi:[1,1,1]
	v_pk_fma_f32 v[100:101], v[50:51], v[178:179], v[100:101] op_sel:[0,0,0] op_sel_hi:[1,0,1]
	v_pk_fma_f32 v[102:103], v[50:51], v[178:179], v[102:103] op_sel:[0,1,0] op_sel_hi:[1,1,1]
	v_pk_fma_f32 v[104:105], v[50:51], v[180:181], v[104:105] op_sel:[0,0,0] op_sel_hi:[1,0,1]
	v_pk_fma_f32 v[106:107], v[50:51], v[180:181], v[106:107] op_sel:[0,1,0] op_sel_hi:[1,1,1]
	v_pk_fma_f32 v[108:109], v[50:51], v[182:183], v[108:109] op_sel:[0,0,0] op_sel_hi:[1,0,1]
	v_pk_fma_f32 v[110:111], v[50:51], v[182:183], v[110:111] op_sel:[0,1,0] op_sel_hi:[1,1,1]
	v_pk_mul_f32 v[14:15], v[96:97], v[184:185] op_sel:[0,0] op_sel_hi:[1,0]
	v_pk_mul_f32 v[18:19], v[96:97], v[148:149] op_sel:[0,0] op_sel_hi:[1,0]
	v_pk_mul_f32 v[16:17], v[98:99], v[184:185] op_sel:[0,1] op_sel_hi:[1,1]
	v_pk_mul_f32 v[20:21], v[98:99], v[148:149] op_sel:[0,1] op_sel_hi:[1,1]
	v_pk_fma_f32 v[14:15], v[100:101], v[186:187], v[14:15] op_sel:[0,0,0] op_sel_hi:[1,0,1]
	v_pk_fma_f32 v[18:19], v[100:101], v[150:151], v[18:19] op_sel:[0,0,0] op_sel_hi:[1,0,1]
	v_pk_fma_f32 v[16:17], v[102:103], v[186:187], v[16:17] op_sel:[0,1,0] op_sel_hi:[1,1,1]
	v_pk_fma_f32 v[20:21], v[102:103], v[150:151], v[20:21] op_sel:[0,1,0] op_sel_hi:[1,1,1]
	v_pk_fma_f32 v[14:15], v[104:105], v[188:189], v[14:15] op_sel:[0,0,0] op_sel_hi:[1,0,1]
	v_pk_fma_f32 v[18:19], v[104:105], v[152:153], v[18:19] op_sel:[0,0,0] op_sel_hi:[1,0,1]
	v_pk_fma_f32 v[16:17], v[106:107], v[188:189], v[16:17] op_sel:[0,1,0] op_sel_hi:[1,1,1]
	v_pk_fma_f32 v[20:21], v[106:107], v[152:153], v[20:21] op_sel:[0,1,0] op_sel_hi:[1,1,1]
	v_pk_fma_f32 v[14:15], v[108:109], v[190:191], v[14:15] op_sel:[0,0,0] op_sel_hi:[1,0,1]
	v_pk_fma_f32 v[18:19], v[108:109], v[154:155], v[18:19] op_sel:[0,0,0] op_sel_hi:[1,0,1]
	v_pk_fma_f32 v[16:17], v[110:111], v[190:191], v[16:17] op_sel:[0,1,0] op_sel_hi:[1,1,1]
	v_pk_fma_f32 v[20:21], v[110:111], v[154:155], v[20:21] op_sel:[0,1,0] op_sel_hi:[1,1,1]
	v_pk_add_f32 v[48:49], v[14:15], v[16:17]
	v_pk_add_f32 v[50:51], v[18:19], v[20:21]
	s_waitcnt lgkmcnt(11)
; #define LAS __attribute__((address_space(3)))
; __device__ __forceinline__ float red8(float x) { x += dpp_mov<0xB1>(x); x += dpp_mov<0x4E>(x); x += dpp_mov<0x141>(x); return x; }
; __device__ __forceinline__ void scan_phase(const KP& P, LAS unsigned char* lds, const int tid, const int bx, const int G) {
;     ...
;             for (int s = 0; s < 32; ++s) {
;                 const LAS float* p = cb + s * 384;
;                 const f32x4 w0 = *(const LAS f32x4*)(p), w1 = *(const LAS f32x4*)(p + 4);
;                 const f32x4 k0 = *(const LAS f32x4*)(p + 64), k1 = *(const LAS f32x4*)(p + 68);
;                 const f32x4 a0 = *(const LAS f32x4*)(p + 128), a1 = *(const LAS f32x4*)(p + 132);
;                 const f32x4 b0 = *(const LAS f32x4*)(p + 192), b1 = *(const LAS f32x4*)(p + 196);
;                 const f32x4 r0 = *(const LAS f32x4*)(p + 256), r1 = *(const LAS f32x4*)(p + 260);
;                 const float vv = buf[(c & 1) * 12288 + s * 384 + 320 + v];
;                 f32x2 sa2 = S[0] * (f32x2){a0.x, a0.y};
;                 sa2 += S[1] * (f32x2){a0.z, a0.w}; sa2 += S[2] * (f32x2){a1.x, a1.y}; sa2 += S[3] * (f32x2){a1.z, a1.w};
;                 const float sa = red8(sa2.x + sa2.y);
;                 const f32x2 sav = {sa, sa}, vv2 = {vv, vv};
;                 S[0] = S[0] * (f32x2){w0.x, w0.y} + sav * (f32x2){b0.x, b0.y} + vv2 * (f32x2){k0.x, k0.y};
;                 S[1] = S[1] * (f32x2){w0.z, w0.w} + sav * (f32x2){b0.z, b0.w} + vv2 * (f32x2){k0.z, k0.w};
;                 S[2] = S[2] * (f32x2){w1.x, w1.y} + sav * (f32x2){b1.x, b1.y} + vv2 * (f32x2){k1.x, k1.y};
;                 S[3] = S[3] * (f32x2){w1.z, w1.w} + sav * (f32x2){b1.z, b1.w} + vv2 * (f32x2){k1.z, k1.w};
;                 f32x2 y2 = S[0] * (f32x2){r0.x, r0.y};
;                 y2 += S[1] * (f32x2){r0.z, r0.w}; y2 += S[2] * (f32x2){r1.x, r1.y}; y2 += S[3] * (f32x2){r1.z, r1.w};
;                 const float y = red8(y2.x + y2.y);
;                 if (kc == 0) ybuf[s * 64 + v] = y;
	ds_read_b128 v[168:171], v44 offset:17152
	ds_read_b128 v[172:175], v44 offset:17168
	ds_read_b128 v[176:179], v44 offset:17664
	ds_read_b128 v[180:183], v44 offset:17680
	ds_read_b128 v[184:187], v44 offset:17920
	ds_read_b128 v[188:191], v44 offset:17936
	ds_read_b64 v[192:193], v46 offset:16896
	ds_read_b128 v[148:151], v44 offset:18944
	ds_read_b128 v[152:155], v44 offset:18960
	v_add_f32_dpp v48, v48, v48 quad_perm:[1,0,3,2] row_mask:0xf bank_mask:0xf bound_ctrl:1
	v_add_f32_dpp v49, v49, v49 quad_perm:[1,0,3,2] row_mask:0xf bank_mask:0xf bound_ctrl:1
	v_add_f32_dpp v50, v50, v50 quad_perm:[1,0,3,2] row_mask:0xf bank_mask:0xf bound_ctrl:1
	v_add_f32_dpp v51, v51, v51 quad_perm:[1,0,3,2] row_mask:0xf bank_mask:0xf bound_ctrl:1
	v_pk_fma_f32 v[96:97], v[144:145], v[120:121], v[96:97] op_sel:[0,0,0] op_sel_hi:[1,0,1]
	v_pk_fma_f32 v[98:99], v[144:145], v[120:121], v[98:99] op_sel:[0,1,0] op_sel_hi:[1,1,1]
	v_pk_fma_f32 v[100:101], v[144:145], v[122:123], v[100:101] op_sel:[0,0,0] op_sel_hi:[1,0,1]
	v_add_f32_dpp v48, v48, v48 quad_perm:[2,3,0,1] row_mask:0xf bank_mask:0xf bound_ctrl:1
	v_add_f32_dpp v49, v49, v49 quad_perm:[2,3,0,1] row_mask:0xf bank_mask:0xf bound_ctrl:1
	v_add_f32_dpp v50, v50, v50 quad_perm:[2,3,0,1] row_mask:0xf bank_mask:0xf bound_ctrl:1
	v_add_f32_dpp v51, v51, v51 quad_perm:[2,3,0,1] row_mask:0xf bank_mask:0xf bound_ctrl:1
	v_pk_fma_f32 v[102:103], v[144:145], v[122:123], v[102:103] op_sel:[0,1,0] op_sel_hi:[1,1,1]
	v_pk_fma_f32 v[104:105], v[144:145], v[124:125], v[104:105] op_sel:[0,0,0] op_sel_hi:[1,0,1]
	v_pk_fma_f32 v[106:107], v[144:145], v[124:125], v[106:107] op_sel:[0,1,0] op_sel_hi:[1,1,1]
	v_add_f32_dpp v48, v48, v48 row_half_mirror row_mask:0xf bank_mask:0xf bound_ctrl:1
	v_add_f32_dpp v49, v49, v49 row_half_mirror row_mask:0xf bank_mask:0xf bound_ctrl:1
	v_add_f32_dpp v50, v50, v50 row_half_mirror row_mask:0xf bank_mask:0xf bound_ctrl:1
	v_add_f32_dpp v51, v51, v51 row_half_mirror row_mask:0xf bank_mask:0xf bound_ctrl:1
	v_pk_fma_f32 v[108:109], v[144:145], v[126:127], v[108:109] op_sel:[0,0,0] op_sel_hi:[1,0,1]
	s_mov_b64 exec, s[10:11]
	ds_write_b64 v45, v[48:49] offset:2048
	s_mov_b64 exec, s[0:1]
	v_pk_fma_f32 v[110:111], v[144:145], v[126:127], v[110:111] op_sel:[0,1,0] op_sel_hi:[1,1,1]
	s_nop 0
	v_pk_fma_f32 v[96:97], v[50:51], v[128:129], v[96:97] op_sel:[0,0,0] op_sel_hi:[1,0,1]
	v_pk_fma_f32 v[98:99], v[50:51], v[128:129], v[98:99] op_sel:[0,1,0] op_sel_hi:[1,1,1]
	v_pk_fma_f32 v[100:101], v[50:51], v[130:131], v[100:101] op_sel:[0,0,0] op_sel_hi:[1,0,1]
	v_pk_fma_f32 v[102:103], v[50:51], v[130:131], v[102:103] op_sel:[0,1,0] op_sel_hi:[1,1,1]
	v_pk_fma_f32 v[104:105], v[50:51], v[132:133], v[104:105] op_sel:[0,0,0] op_sel_hi:[1,0,1]
	v_pk_fma_f32 v[106:107], v[50:51], v[132:133], v[106:107] op_sel:[0,1,0] op_sel_hi:[1,1,1]
	v_pk_fma_f32 v[108:109], v[50:51], v[134:135], v[108:109] op_sel:[0,0,0] op_sel_hi:[1,0,1]
	v_pk_fma_f32 v[110:111], v[50:51], v[134:135], v[110:111] op_sel:[0,1,0] op_sel_hi:[1,1,1]
	v_pk_mul_f32 v[14:15], v[96:97], v[136:137] op_sel:[0,0] op_sel_hi:[1,0]
	v_pk_mul_f32 v[18:19], v[96:97], v[156:157] op_sel:[0,0] op_sel_hi:[1,0]
	v_pk_mul_f32 v[16:17], v[98:99], v[136:137] op_sel:[0,1] op_sel_hi:[1,1]
	v_pk_mul_f32 v[20:21], v[98:99], v[156:157] op_sel:[0,1] op_sel_hi:[1,1]
	v_pk_fma_f32 v[14:15], v[100:101], v[138:139], v[14:15] op_sel:[0,0,0] op_sel_hi:[1,0,1]
	v_pk_fma_f32 v[18:19], v[100:101], v[158:159], v[18:19] op_sel:[0,0,0] op_sel_hi:[1,0,1]
	v_pk_fma_f32 v[16:17], v[102:103], v[138:139], v[16:17] op_sel:[0,1,0] op_sel_hi:[1,1,1]
	v_pk_fma_f32 v[20:21], v[102:103], v[158:159], v[20:21] op_sel:[0,1,0] op_sel_hi:[1,1,1]
	v_pk_fma_f32 v[14:15], v[104:105], v[140:141], v[14:15] op_sel:[0,0,0] op_sel_hi:[1,0,1]
	v_pk_fma_f32 v[18:19], v[104:105], v[160:161], v[18:19] op_sel:[0,0,0] op_sel_hi:[1,0,1]
	v_pk_fma_f32 v[16:17], v[106:107], v[140:141], v[16:17] op_sel:[0,1,0] op_sel_hi:[1,1,1]
	v_pk_fma_f32 v[20:21], v[106:107], v[160:161], v[20:21] op_sel:[0,1,0] op_sel_hi:[1,1,1]
	v_pk_fma_f32 v[14:15], v[108:109], v[142:143], v[14:15] op_sel:[0,0,0] op_sel_hi:[1,0,1]
	v_pk_fma_f32 v[18:19], v[108:109], v[162:163], v[18:19] op_sel:[0,0,0] op_sel_hi:[1,0,1]
	v_pk_fma_f32 v[16:17], v[110:111], v[142:143], v[16:17] op_sel:[0,1,0] op_sel_hi:[1,1,1]
	v_pk_fma_f32 v[20:21], v[110:111], v[162:163], v[20:21] op_sel:[0,1,0] op_sel_hi:[1,1,1]
	v_pk_add_f32 v[48:49], v[14:15], v[16:17]
	v_pk_add_f32 v[50:51], v[18:19], v[20:21]
	s_waitcnt lgkmcnt(11)
; #define LAS __attribute__((address_space(3)))
; __device__ __forceinline__ float red8(float x) { x += dpp_mov<0xB1>(x); x += dpp_mov<0x4E>(x); x += dpp_mov<0x141>(x); return x; }
; __device__ __forceinline__ void scan_phase(const KP& P, LAS unsigned char* lds, const int tid, const int bx, const int G) {
;     ...
;             for (int s = 0; s < 32; ++s) {
;                 const LAS float* p = cb + s * 384;
;                 const f32x4 w0 = *(const LAS f32x4*)(p), w1 = *(const LAS f32x4*)(p + 4);
;                 const f32x4 k0 = *(const LAS f32x4*)(p + 64), k1 = *(const LAS f32x4*)(p + 68);
;                 const f32x4 a0 = *(const LAS f32x4*)(p + 128), a1 = *(const LAS f32x4*)(p + 132);
;                 const f32x4 b0 = *(const LAS f32x4*)(p + 192), b1 = *(const LAS f32x4*)(p + 196);
;                 const f32x4 r0 = *(const LAS f32x4*)(p + 256), r1 = *(const LAS f32x4*)(p + 260);
;                 const float vv = buf[(c & 1) * 12288 + s * 384 + 320 + v];
;                 f32x2 sa2 = S[0] * (f32x2){a0.x, a0.y};
;                 sa2 += S[1] * (f32x2){a0.z, a0.w}; sa2 += S[2] * (f32x2){a1.x, a1.y}; sa2 += S[3] * (f32x2){a1.z, a1.w};
;                 const float sa = red8(sa2.x + sa2.y);
;                 const f32x2 sav = {sa, sa}, vv2 = {vv, vv};
;                 S[0] = S[0] * (f32x2){w0.x, w0.y} + sav * (f32x2){b0.x, b0.y} + vv2 * (f32x2){k0.x, k0.y};
;                 S[1] = S[1] * (f32x2){w0.z, w0.w} + sav * (f32x2){b0.z, b0.w} + vv2 * (f32x2){k0.z, k0.w};
;                 S[2] = S[2] * (f32x2){w1.x, w1.y} + sav * (f32x2){b1.x, b1.y} + vv2 * (f32x2){k1.x, k1.y};
;                 S[3] = S[3] * (f32x2){w1.z, w1.w} + sav * (f32x2){b1.z, b1.w} + vv2 * (f32x2){k1.z, k1.w};
;                 f32x2 y2 = S[0] * (f32x2){r0.x, r0.y};
;                 y2 += S[1] * (f32x2){r0.z, r0.w}; y2 += S[2] * (f32x2){r1.x, r1.y}; y2 += S[3] * (f32x2){r1.z, r1.w};
;                 const float y = red8(y2.x + y2.y);
;                 if (kc == 0) ybuf[s * 64 + v] = y;
	ds_read_b128 v[120:123], v44 offset:18688
	ds_read_b128 v[124:127], v44 offset:18704
	ds_read_b128 v[128:131], v44 offset:19200
	ds_read_b128 v[132:135], v44 offset:19216
	ds_read_b128 v[136:139], v44 offset:19456
	ds_read_b128 v[140:143], v44 offset:19472
	ds_read_b64 v[144:145], v46 offset:18432
	ds_read_b128 v[156:159], v44 offset:20480
	ds_read_b128 v[160:163], v44 offset:20496
	v_add_f32_dpp v48, v48, v48 quad_perm:[1,0,3,2] row_mask:0xf bank_mask:0xf bound_ctrl:1
	v_add_f32_dpp v49, v49, v49 quad_perm:[1,0,3,2] row_mask:0xf bank_mask:0xf bound_ctrl:1
	v_add_f32_dpp v50, v50, v50 quad_perm:[1,0,3,2] row_mask:0xf bank_mask:0xf bound_ctrl:1
	v_add_f32_dpp v51, v51, v51 quad_perm:[1,0,3,2] row_mask:0xf bank_mask:0xf bound_ctrl:1
	v_pk_fma_f32 v[96:97], v[146:147], v[70:71], v[96:97] op_sel:[0,0,0] op_sel_hi:[1,0,1]
	v_pk_fma_f32 v[98:99], v[146:147], v[70:71], v[98:99] op_sel:[0,1,0] op_sel_hi:[1,1,1]
	v_pk_fma_f32 v[100:101], v[146:147], v[72:73], v[100:101] op_sel:[0,0,0] op_sel_hi:[1,0,1]
	v_add_f32_dpp v48, v48, v48 quad_perm:[2,3,0,1] row_mask:0xf bank_mask:0xf bound_ctrl:1
	v_add_f32_dpp v49, v49, v49 quad_perm:[2,3,0,1] row_mask:0xf bank_mask:0xf bound_ctrl:1
	v_add_f32_dpp v50, v50, v50 quad_perm:[2,3,0,1] row_mask:0xf bank_mask:0xf bound_ctrl:1
	v_add_f32_dpp v51, v51, v51 quad_perm:[2,3,0,1] row_mask:0xf bank_mask:0xf bound_ctrl:1
	v_pk_fma_f32 v[102:103], v[146:147], v[72:73], v[102:103] op_sel:[0,1,0] op_sel_hi:[1,1,1]
	v_pk_fma_f32 v[104:105], v[146:147], v[74:75], v[104:105] op_sel:[0,0,0] op_sel_hi:[1,0,1]
	v_pk_fma_f32 v[106:107], v[146:147], v[74:75], v[106:107] op_sel:[0,1,0] op_sel_hi:[1,1,1]
	v_add_f32_dpp v48, v48, v48 row_half_mirror row_mask:0xf bank_mask:0xf bound_ctrl:1
	v_add_f32_dpp v49, v49, v49 row_half_mirror row_mask:0xf bank_mask:0xf bound_ctrl:1
	v_add_f32_dpp v50, v50, v50 row_half_mirror row_mask:0xf bank_mask:0xf bound_ctrl:1
	v_add_f32_dpp v51, v51, v51 row_half_mirror row_mask:0xf bank_mask:0xf bound_ctrl:1
	v_pk_fma_f32 v[108:109], v[146:147], v[76:77], v[108:109] op_sel:[0,0,0] op_sel_hi:[1,0,1]
	s_mov_b64 exec, s[10:11]
	ds_write_b64 v45, v[48:49] offset:2304
	s_mov_b64 exec, s[0:1]
	v_pk_fma_f32 v[110:111], v[146:147], v[76:77], v[110:111] op_sel:[0,1,0] op_sel_hi:[1,1,1]
	s_nop 0
	v_pk_fma_f32 v[96:97], v[50:51], v[78:79], v[96:97] op_sel:[0,0,0] op_sel_hi:[1,0,1]
	v_pk_fma_f32 v[98:99], v[50:51], v[78:79], v[98:99] op_sel:[0,1,0] op_sel_hi:[1,1,1]
	v_pk_fma_f32 v[100:101], v[50:51], v[80:81], v[100:101] op_sel:[0,0,0] op_sel_hi:[1,0,1]
	v_pk_fma_f32 v[102:103], v[50:51], v[80:81], v[102:103] op_sel:[0,1,0] op_sel_hi:[1,1,1]
	v_pk_fma_f32 v[104:105], v[50:51], v[82:83], v[104:105] op_sel:[0,0,0] op_sel_hi:[1,0,1]
	v_pk_fma_f32 v[106:107], v[50:51], v[82:83], v[106:107] op_sel:[0,1,0] op_sel_hi:[1,1,1]
	v_pk_fma_f32 v[108:109], v[50:51], v[84:85], v[108:109] op_sel:[0,0,0] op_sel_hi:[1,0,1]
	v_pk_fma_f32 v[110:111], v[50:51], v[84:85], v[110:111] op_sel:[0,1,0] op_sel_hi:[1,1,1]
	v_pk_mul_f32 v[14:15], v[96:97], v[86:87] op_sel:[0,0] op_sel_hi:[1,0]
	v_pk_mul_f32 v[18:19], v[96:97], v[62:63] op_sel:[0,0] op_sel_hi:[1,0]
	v_pk_mul_f32 v[16:17], v[98:99], v[86:87] op_sel:[0,1] op_sel_hi:[1,1]
	v_pk_mul_f32 v[20:21], v[98:99], v[62:63] op_sel:[0,1] op_sel_hi:[1,1]
	v_pk_fma_f32 v[14:15], v[100:101], v[88:89], v[14:15] op_sel:[0,0,0] op_sel_hi:[1,0,1]
	v_pk_fma_f32 v[18:19], v[100:101], v[64:65], v[18:19] op_sel:[0,0,0] op_sel_hi:[1,0,1]
	v_pk_fma_f32 v[16:17], v[102:103], v[88:89], v[16:17] op_sel:[0,1,0] op_sel_hi:[1,1,1]
	v_pk_fma_f32 v[20:21], v[102:103], v[64:65], v[20:21] op_sel:[0,1,0] op_sel_hi:[1,1,1]
	v_pk_fma_f32 v[14:15], v[104:105], v[90:91], v[14:15] op_sel:[0,0,0] op_sel_hi:[1,0,1]
	v_pk_fma_f32 v[18:19], v[104:105], v[66:67], v[18:19] op_sel:[0,0,0] op_sel_hi:[1,0,1]
	v_pk_fma_f32 v[16:17], v[106:107], v[90:91], v[16:17] op_sel:[0,1,0] op_sel_hi:[1,1,1]
	v_pk_fma_f32 v[20:21], v[106:107], v[66:67], v[20:21] op_sel:[0,1,0] op_sel_hi:[1,1,1]
	v_pk_fma_f32 v[14:15], v[108:109], v[92:93], v[14:15] op_sel:[0,0,0] op_sel_hi:[1,0,1]
	v_pk_fma_f32 v[18:19], v[108:109], v[68:69], v[18:19] op_sel:[0,0,0] op_sel_hi:[1,0,1]
	v_pk_fma_f32 v[16:17], v[110:111], v[92:93], v[16:17] op_sel:[0,1,0] op_sel_hi:[1,1,1]
	v_pk_fma_f32 v[20:21], v[110:111], v[68:69], v[20:21] op_sel:[0,1,0] op_sel_hi:[1,1,1]
	v_pk_add_f32 v[48:49], v[14:15], v[16:17]
	v_pk_add_f32 v[50:51], v[18:19], v[20:21]
	s_waitcnt lgkmcnt(11)
; #define LAS __attribute__((address_space(3)))
; __device__ __forceinline__ float red8(float x) { x += dpp_mov<0xB1>(x); x += dpp_mov<0x4E>(x); x += dpp_mov<0x141>(x); return x; }
; __device__ __forceinline__ void scan_phase(const KP& P, LAS unsigned char* lds, const int tid, const int bx, const int G) {
;     ...
;             for (int s = 0; s < 32; ++s) {
;                 const LAS float* p = cb + s * 384;
;                 const f32x4 w0 = *(const LAS f32x4*)(p), w1 = *(const LAS f32x4*)(p + 4);
;                 const f32x4 k0 = *(const LAS f32x4*)(p + 64), k1 = *(const LAS f32x4*)(p + 68);
;                 const f32x4 a0 = *(const LAS f32x4*)(p + 128), a1 = *(const LAS f32x4*)(p + 132);
;                 const f32x4 b0 = *(const LAS f32x4*)(p + 192), b1 = *(const LAS f32x4*)(p + 196);
;                 const f32x4 r0 = *(const LAS f32x4*)(p + 256), r1 = *(const LAS f32x4*)(p + 260);
;                 const float vv = buf[(c & 1) * 12288 + s * 384 + 320 + v];
;                 f32x2 sa2 = S[0] * (f32x2){a0.x, a0.y};
;                 sa2 += S[1] * (f32x2){a0.z, a0.w}; sa2 += S[2] * (f32x2){a1.x, a1.y}; sa2 += S[3] * (f32x2){a1.z, a1.w};
;                 const float sa = red8(sa2.x + sa2.y);
;                 const f32x2 sav = {sa, sa}, vv2 = {vv, vv};
;                 S[0] = S[0] * (f32x2){w0.x, w0.y} + sav * (f32x2){b0.x, b0.y} + vv2 * (f32x2){k0.x, k0.y};
;                 S[1] = S[1] * (f32x2){w0.z, w0.w} + sav * (f32x2){b0.z, b0.w} + vv2 * (f32x2){k0.z, k0.w};
;                 S[2] = S[2] * (f32x2){w1.x, w1.y} + sav * (f32x2){b1.x, b1.y} + vv2 * (f32x2){k1.x, k1.y};
;                 S[3] = S[3] * (f32x2){w1.z, w1.w} + sav * (f32x2){b1.z, b1.w} + vv2 * (f32x2){k1.z, k1.w};
;                 f32x2 y2 = S[0] * (f32x2){r0.x, r0.y};
;                 y2 += S[1] * (f32x2){r0.z, r0.w}; y2 += S[2] * (f32x2){r1.x, r1.y}; y2 += S[3] * (f32x2){r1.z, r1.w};
;                 const float y = red8(y2.x + y2.y);
;                 if (kc == 0) ybuf[s * 64 + v] = y;
	ds_read_b128 v[70:73], v44 offset:20224
	ds_read_b128 v[74:77], v44 offset:20240
	ds_read_b128 v[78:81], v44 offset:20736
	ds_read_b128 v[82:85], v44 offset:20752
	ds_read_b128 v[86:89], v44 offset:20992
	ds_read_b128 v[90:93], v44 offset:21008
	ds_read_b64 v[146:147], v46 offset:19968
	ds_read_b128 v[62:65], v44 offset:22016
	ds_read_b128 v[66:69], v44 offset:22032
	v_add_f32_dpp v48, v48, v48 quad_perm:[1,0,3,2] row_mask:0xf bank_mask:0xf bound_ctrl:1
	v_add_f32_dpp v49, v49, v49 quad_perm:[1,0,3,2] row_mask:0xf bank_mask:0xf bound_ctrl:1
	v_add_f32_dpp v50, v50, v50 quad_perm:[1,0,3,2] row_mask:0xf bank_mask:0xf bound_ctrl:1
	v_add_f32_dpp v51, v51, v51 quad_perm:[1,0,3,2] row_mask:0xf bank_mask:0xf bound_ctrl:1
	v_pk_fma_f32 v[96:97], v[192:193], v[168:169], v[96:97] op_sel:[0,0,0] op_sel_hi:[1,0,1]
	v_pk_fma_f32 v[98:99], v[192:193], v[168:169], v[98:99] op_sel:[0,1,0] op_sel_hi:[1,1,1]
	v_pk_fma_f32 v[100:101], v[192:193], v[170:171], v[100:101] op_sel:[0,0,0] op_sel_hi:[1,0,1]
	v_add_f32_dpp v48, v48, v48 quad_perm:[2,3,0,1] row_mask:0xf bank_mask:0xf bound_ctrl:1
	v_add_f32_dpp v49, v49, v49 quad_perm:[2,3,0,1] row_mask:0xf bank_mask:0xf bound_ctrl:1
	v_add_f32_dpp v50, v50, v50 quad_perm:[2,3,0,1] row_mask:0xf bank_mask:0xf bound_ctrl:1
	v_add_f32_dpp v51, v51, v51 quad_perm:[2,3,0,1] row_mask:0xf bank_mask:0xf bound_ctrl:1
	v_pk_fma_f32 v[102:103], v[192:193], v[170:171], v[102:103] op_sel:[0,1,0] op_sel_hi:[1,1,1]
	v_pk_fma_f32 v[104:105], v[192:193], v[172:173], v[104:105] op_sel:[0,0,0] op_sel_hi:[1,0,1]
	v_pk_fma_f32 v[106:107], v[192:193], v[172:173], v[106:107] op_sel:[0,1,0] op_sel_hi:[1,1,1]
	v_add_f32_dpp v48, v48, v48 row_half_mirror row_mask:0xf bank_mask:0xf bound_ctrl:1
	v_add_f32_dpp v49, v49, v49 row_half_mirror row_mask:0xf bank_mask:0xf bound_ctrl:1
	v_add_f32_dpp v50, v50, v50 row_half_mirror row_mask:0xf bank_mask:0xf bound_ctrl:1
	v_add_f32_dpp v51, v51, v51 row_half_mirror row_mask:0xf bank_mask:0xf bound_ctrl:1
	v_pk_fma_f32 v[108:109], v[192:193], v[174:175], v[108:109] op_sel:[0,0,0] op_sel_hi:[1,0,1]
	s_mov_b64 exec, s[10:11]
	ds_write_b64 v45, v[48:49] offset:2560
	s_mov_b64 exec, s[0:1]
	v_pk_fma_f32 v[110:111], v[192:193], v[174:175], v[110:111] op_sel:[0,1,0] op_sel_hi:[1,1,1]
	s_nop 0
	v_pk_fma_f32 v[96:97], v[50:51], v[176:177], v[96:97] op_sel:[0,0,0] op_sel_hi:[1,0,1]
	v_pk_fma_f32 v[98:99], v[50:51], v[176:177], v[98:99] op_sel:[0,1,0] op_sel_hi:[1,1,1]
	v_pk_fma_f32 v[100:101], v[50:51], v[178:179], v[100:101] op_sel:[0,0,0] op_sel_hi:[1,0,1]
	v_pk_fma_f32 v[102:103], v[50:51], v[178:179], v[102:103] op_sel:[0,1,0] op_sel_hi:[1,1,1]
	v_pk_fma_f32 v[104:105], v[50:51], v[180:181], v[104:105] op_sel:[0,0,0] op_sel_hi:[1,0,1]
	v_pk_fma_f32 v[106:107], v[50:51], v[180:181], v[106:107] op_sel:[0,1,0] op_sel_hi:[1,1,1]
	v_pk_fma_f32 v[108:109], v[50:51], v[182:183], v[108:109] op_sel:[0,0,0] op_sel_hi:[1,0,1]
	v_pk_fma_f32 v[110:111], v[50:51], v[182:183], v[110:111] op_sel:[0,1,0] op_sel_hi:[1,1,1]
	v_pk_mul_f32 v[14:15], v[96:97], v[184:185] op_sel:[0,0] op_sel_hi:[1,0]
	v_pk_mul_f32 v[18:19], v[96:97], v[148:149] op_sel:[0,0] op_sel_hi:[1,0]
	v_pk_mul_f32 v[16:17], v[98:99], v[184:185] op_sel:[0,1] op_sel_hi:[1,1]
	v_pk_mul_f32 v[20:21], v[98:99], v[148:149] op_sel:[0,1] op_sel_hi:[1,1]
	v_pk_fma_f32 v[14:15], v[100:101], v[186:187], v[14:15] op_sel:[0,0,0] op_sel_hi:[1,0,1]
	v_pk_fma_f32 v[18:19], v[100:101], v[150:151], v[18:19] op_sel:[0,0,0] op_sel_hi:[1,0,1]
	v_pk_fma_f32 v[16:17], v[102:103], v[186:187], v[16:17] op_sel:[0,1,0] op_sel_hi:[1,1,1]
	v_pk_fma_f32 v[20:21], v[102:103], v[150:151], v[20:21] op_sel:[0,1,0] op_sel_hi:[1,1,1]
	v_pk_fma_f32 v[14:15], v[104:105], v[188:189], v[14:15] op_sel:[0,0,0] op_sel_hi:[1,0,1]
	v_pk_fma_f32 v[18:19], v[104:105], v[152:153], v[18:19] op_sel:[0,0,0] op_sel_hi:[1,0,1]
	v_pk_fma_f32 v[16:17], v[106:107], v[188:189], v[16:17] op_sel:[0,1,0] op_sel_hi:[1,1,1]
	v_pk_fma_f32 v[20:21], v[106:107], v[152:153], v[20:21] op_sel:[0,1,0] op_sel_hi:[1,1,1]
	v_pk_fma_f32 v[14:15], v[108:109], v[190:191], v[14:15] op_sel:[0,0,0] op_sel_hi:[1,0,1]
	v_pk_fma_f32 v[18:19], v[108:109], v[154:155], v[18:19] op_sel:[0,0,0] op_sel_hi:[1,0,1]
	v_pk_fma_f32 v[16:17], v[110:111], v[190:191], v[16:17] op_sel:[0,1,0] op_sel_hi:[1,1,1]
	v_pk_fma_f32 v[20:21], v[110:111], v[154:155], v[20:21] op_sel:[0,1,0] op_sel_hi:[1,1,1]
	v_pk_add_f32 v[48:49], v[14:15], v[16:17]
	v_pk_add_f32 v[50:51], v[18:19], v[20:21]
	s_waitcnt lgkmcnt(11)
; #define LAS __attribute__((address_space(3)))
; __device__ __forceinline__ float red8(float x) { x += dpp_mov<0xB1>(x); x += dpp_mov<0x4E>(x); x += dpp_mov<0x141>(x); return x; }
; __device__ __forceinline__ void scan_phase(const KP& P, LAS unsigned char* lds, const int tid, const int bx, const int G) {
;     ...
;             for (int s = 0; s < 32; ++s) {
;                 const LAS float* p = cb + s * 384;
;                 const f32x4 w0 = *(const LAS f32x4*)(p), w1 = *(const LAS f32x4*)(p + 4);
;                 const f32x4 k0 = *(const LAS f32x4*)(p + 64), k1 = *(const LAS f32x4*)(p + 68);
;                 const f32x4 a0 = *(const LAS f32x4*)(p + 128), a1 = *(const LAS f32x4*)(p + 132);
;                 const f32x4 b0 = *(const LAS f32x4*)(p + 192), b1 = *(const LAS f32x4*)(p + 196);
;                 const f32x4 r0 = *(const LAS f32x4*)(p + 256), r1 = *(const LAS f32x4*)(p + 260);
;                 const float vv = buf[(c & 1) * 12288 + s * 384 + 320 + v];
;                 f32x2 sa2 = S[0] * (f32x2){a0.x, a0.y};
;                 sa2 += S[1] * (f32x2){a0.z, a0.w}; sa2 += S[2] * (f32x2){a1.x, a1.y}; sa2 += S[3] * (f32x2){a1.z, a1.w};
;                 const float sa = red8(sa2.x + sa2.y);
;                 const f32x2 sav = {sa, sa}, vv2 = {vv, vv};
;                 S[0] = S[0] * (f32x2){w0.x, w0.y} + sav * (f32x2){b0.x, b0.y} + vv2 * (f32x2){k0.x, k0.y};
;                 S[1] = S[1] * (f32x2){w0.z, w0.w} + sav * (f32x2){b0.z, b0.w} + vv2 * (f32x2){k0.z, k0.w};
;                 S[2] = S[2] * (f32x2){w1.x, w1.y} + sav * (f32x2){b1.x, b1.y} + vv2 * (f32x2){k1.x, k1.y};
;                 S[3] = S[3] * (f32x2){w1.z, w1.w} + sav * (f32x2){b1.z, b1.w} + vv2 * (f32x2){k1.z, k1.w};
;                 f32x2 y2 = S[0] * (f32x2){r0.x, r0.y};
;                 y2 += S[1] * (f32x2){r0.z, r0.w}; y2 += S[2] * (f32x2){r1.x, r1.y}; y2 += S[3] * (f32x2){r1.z, r1.w};
;                 const float y = red8(y2.x + y2.y);
;                 if (kc == 0) ybuf[s * 64 + v] = y;
	ds_read_b128 v[168:171], v44 offset:21760
	ds_read_b128 v[172:175], v44 offset:21776
	ds_read_b128 v[176:179], v44 offset:22272
	ds_read_b128 v[180:183], v44 offset:22288
	ds_read_b128 v[184:187], v44 offset:22528
	ds_read_b128 v[188:191], v44 offset:22544
	ds_read_b64 v[192:193], v46 offset:21504
	ds_read_b128 v[148:151], v44 offset:23552
	ds_read_b128 v[152:155], v44 offset:23568
	v_add_f32_dpp v48, v48, v48 quad_perm:[1,0,3,2] row_mask:0xf bank_mask:0xf bound_ctrl:1
	v_add_f32_dpp v49, v49, v49 quad_perm:[1,0,3,2] row_mask:0xf bank_mask:0xf bound_ctrl:1
	v_add_f32_dpp v50, v50, v50 quad_perm:[1,0,3,2] row_mask:0xf bank_mask:0xf bound_ctrl:1
	v_add_f32_dpp v51, v51, v51 quad_perm:[1,0,3,2] row_mask:0xf bank_mask:0xf bound_ctrl:1
	v_pk_fma_f32 v[96:97], v[144:145], v[120:121], v[96:97] op_sel:[0,0,0] op_sel_hi:[1,0,1]
	v_pk_fma_f32 v[98:99], v[144:145], v[120:121], v[98:99] op_sel:[0,1,0] op_sel_hi:[1,1,1]
	v_pk_fma_f32 v[100:101], v[144:145], v[122:123], v[100:101] op_sel:[0,0,0] op_sel_hi:[1,0,1]
	v_add_f32_dpp v48, v48, v48 quad_perm:[2,3,0,1] row_mask:0xf bank_mask:0xf bound_ctrl:1
	v_add_f32_dpp v49, v49, v49 quad_perm:[2,3,0,1] row_mask:0xf bank_mask:0xf bound_ctrl:1
	v_add_f32_dpp v50, v50, v50 quad_perm:[2,3,0,1] row_mask:0xf bank_mask:0xf bound_ctrl:1
	v_add_f32_dpp v51, v51, v51 quad_perm:[2,3,0,1] row_mask:0xf bank_mask:0xf bound_ctrl:1
	v_pk_fma_f32 v[102:103], v[144:145], v[122:123], v[102:103] op_sel:[0,1,0] op_sel_hi:[1,1,1]
	v_pk_fma_f32 v[104:105], v[144:145], v[124:125], v[104:105] op_sel:[0,0,0] op_sel_hi:[1,0,1]
	v_pk_fma_f32 v[106:107], v[144:145], v[124:125], v[106:107] op_sel:[0,1,0] op_sel_hi:[1,1,1]
	v_add_f32_dpp v48, v48, v48 row_half_mirror row_mask:0xf bank_mask:0xf bound_ctrl:1
	v_add_f32_dpp v49, v49, v49 row_half_mirror row_mask:0xf bank_mask:0xf bound_ctrl:1
	v_add_f32_dpp v50, v50, v50 row_half_mirror row_mask:0xf bank_mask:0xf bound_ctrl:1
	v_add_f32_dpp v51, v51, v51 row_half_mirror row_mask:0xf bank_mask:0xf bound_ctrl:1
	v_pk_fma_f32 v[108:109], v[144:145], v[126:127], v[108:109] op_sel:[0,0,0] op_sel_hi:[1,0,1]
	s_mov_b64 exec, s[10:11]
	ds_write_b64 v45, v[48:49] offset:2816
	s_mov_b64 exec, s[0:1]
	v_pk_fma_f32 v[110:111], v[144:145], v[126:127], v[110:111] op_sel:[0,1,0] op_sel_hi:[1,1,1]
	s_nop 0
	v_pk_fma_f32 v[96:97], v[50:51], v[128:129], v[96:97] op_sel:[0,0,0] op_sel_hi:[1,0,1]
	v_pk_fma_f32 v[98:99], v[50:51], v[128:129], v[98:99] op_sel:[0,1,0] op_sel_hi:[1,1,1]
	v_pk_fma_f32 v[100:101], v[50:51], v[130:131], v[100:101] op_sel:[0,0,0] op_sel_hi:[1,0,1]
	v_pk_fma_f32 v[102:103], v[50:51], v[130:131], v[102:103] op_sel:[0,1,0] op_sel_hi:[1,1,1]
	v_pk_fma_f32 v[104:105], v[50:51], v[132:133], v[104:105] op_sel:[0,0,0] op_sel_hi:[1,0,1]
	v_pk_fma_f32 v[106:107], v[50:51], v[132:133], v[106:107] op_sel:[0,1,0] op_sel_hi:[1,1,1]
	v_pk_fma_f32 v[108:109], v[50:51], v[134:135], v[108:109] op_sel:[0,0,0] op_sel_hi:[1,0,1]
	v_pk_fma_f32 v[110:111], v[50:51], v[134:135], v[110:111] op_sel:[0,1,0] op_sel_hi:[1,1,1]
	v_pk_mul_f32 v[14:15], v[96:97], v[136:137] op_sel:[0,0] op_sel_hi:[1,0]
	v_pk_mul_f32 v[18:19], v[96:97], v[156:157] op_sel:[0,0] op_sel_hi:[1,0]
	v_pk_mul_f32 v[16:17], v[98:99], v[136:137] op_sel:[0,1] op_sel_hi:[1,1]
	v_pk_mul_f32 v[20:21], v[98:99], v[156:157] op_sel:[0,1] op_sel_hi:[1,1]
	v_pk_fma_f32 v[14:15], v[100:101], v[138:139], v[14:15] op_sel:[0,0,0] op_sel_hi:[1,0,1]
	v_pk_fma_f32 v[18:19], v[100:101], v[158:159], v[18:19] op_sel:[0,0,0] op_sel_hi:[1,0,1]
	v_pk_fma_f32 v[16:17], v[102:103], v[138:139], v[16:17] op_sel:[0,1,0] op_sel_hi:[1,1,1]
	v_pk_fma_f32 v[20:21], v[102:103], v[158:159], v[20:21] op_sel:[0,1,0] op_sel_hi:[1,1,1]
	v_pk_fma_f32 v[14:15], v[104:105], v[140:141], v[14:15] op_sel:[0,0,0] op_sel_hi:[1,0,1]
	v_pk_fma_f32 v[18:19], v[104:105], v[160:161], v[18:19] op_sel:[0,0,0] op_sel_hi:[1,0,1]
	v_pk_fma_f32 v[16:17], v[106:107], v[140:141], v[16:17] op_sel:[0,1,0] op_sel_hi:[1,1,1]
	v_pk_fma_f32 v[20:21], v[106:107], v[160:161], v[20:21] op_sel:[0,1,0] op_sel_hi:[1,1,1]
	v_pk_fma_f32 v[14:15], v[108:109], v[142:143], v[14:15] op_sel:[0,0,0] op_sel_hi:[1,0,1]
	v_pk_fma_f32 v[18:19], v[108:109], v[162:163], v[18:19] op_sel:[0,0,0] op_sel_hi:[1,0,1]
	v_pk_fma_f32 v[16:17], v[110:111], v[142:143], v[16:17] op_sel:[0,1,0] op_sel_hi:[1,1,1]
	v_pk_fma_f32 v[20:21], v[110:111], v[162:163], v[20:21] op_sel:[0,1,0] op_sel_hi:[1,1,1]
	v_pk_add_f32 v[48:49], v[14:15], v[16:17]
	v_pk_add_f32 v[50:51], v[18:19], v[20:21]
	s_waitcnt lgkmcnt(11)
; #define LAS __attribute__((address_space(3)))
; __device__ __forceinline__ float red8(float x) { x += dpp_mov<0xB1>(x); x += dpp_mov<0x4E>(x); x += dpp_mov<0x141>(x); return x; }
; __device__ __forceinline__ void scan_phase(const KP& P, LAS unsigned char* lds, const int tid, const int bx, const int G) {
;     ...
;             for (int s = 0; s < 32; ++s) {
;                 const LAS float* p = cb + s * 384;
;                 const f32x4 w0 = *(const LAS f32x4*)(p), w1 = *(const LAS f32x4*)(p + 4);
;                 const f32x4 k0 = *(const LAS f32x4*)(p + 64), k1 = *(const LAS f32x4*)(p + 68);
;                 const f32x4 a0 = *(const LAS f32x4*)(p + 128), a1 = *(const LAS f32x4*)(p + 132);
;                 const f32x4 b0 = *(const LAS f32x4*)(p + 192), b1 = *(const LAS f32x4*)(p + 196);
;                 const f32x4 r0 = *(const LAS f32x4*)(p + 256), r1 = *(const LAS f32x4*)(p + 260);
;                 const float vv = buf[(c & 1) * 12288 + s * 384 + 320 + v];
;                 f32x2 sa2 = S[0] * (f32x2){a0.x, a0.y};
;                 sa2 += S[1] * (f32x2){a0.z, a0.w}; sa2 += S[2] * (f32x2){a1.x, a1.y}; sa2 += S[3] * (f32x2){a1.z, a1.w};
;                 const float sa = red8(sa2.x + sa2.y);
;                 const f32x2 sav = {sa, sa}, vv2 = {vv, vv};
;                 S[0] = S[0] * (f32x2){w0.x, w0.y} + sav * (f32x2){b0.x, b0.y} + vv2 * (f32x2){k0.x, k0.y};
;                 S[1] = S[1] * (f32x2){w0.z, w0.w} + sav * (f32x2){b0.z, b0.w} + vv2 * (f32x2){k0.z, k0.w};
;                 S[2] = S[2] * (f32x2){w1.x, w1.y} + sav * (f32x2){b1.x, b1.y} + vv2 * (f32x2){k1.x, k1.y};
;                 S[3] = S[3] * (f32x2){w1.z, w1.w} + sav * (f32x2){b1.z, b1.w} + vv2 * (f32x2){k1.z, k1.w};
;                 f32x2 y2 = S[0] * (f32x2){r0.x, r0.y};
;                 y2 += S[1] * (f32x2){r0.z, r0.w}; y2 += S[2] * (f32x2){r1.x, r1.y}; y2 += S[3] * (f32x2){r1.z, r1.w};
;                 const float y = red8(y2.x + y2.y);
;                 if (kc == 0) ybuf[s * 64 + v] = y;
	ds_read_b128 v[120:123], v44 offset:23296
	ds_read_b128 v[124:127], v44 offset:23312
	ds_read_b128 v[128:131], v44 offset:23808
	ds_read_b128 v[132:135], v44 offset:23824
	ds_read_b128 v[136:139], v44 offset:24064
	ds_read_b128 v[140:143], v44 offset:24080
	ds_read_b64 v[144:145], v46 offset:23040
	ds_read_b128 v[156:159], v44 offset:25088
	ds_read_b128 v[160:163], v44 offset:25104
	v_add_f32_dpp v48, v48, v48 quad_perm:[1,0,3,2] row_mask:0xf bank_mask:0xf bound_ctrl:1
	v_add_f32_dpp v49, v49, v49 quad_perm:[1,0,3,2] row_mask:0xf bank_mask:0xf bound_ctrl:1
	v_add_f32_dpp v50, v50, v50 quad_perm:[1,0,3,2] row_mask:0xf bank_mask:0xf bound_ctrl:1
	v_add_f32_dpp v51, v51, v51 quad_perm:[1,0,3,2] row_mask:0xf bank_mask:0xf bound_ctrl:1
	v_pk_fma_f32 v[96:97], v[146:147], v[70:71], v[96:97] op_sel:[0,0,0] op_sel_hi:[1,0,1]
	v_pk_fma_f32 v[98:99], v[146:147], v[70:71], v[98:99] op_sel:[0,1,0] op_sel_hi:[1,1,1]
	v_pk_fma_f32 v[100:101], v[146:147], v[72:73], v[100:101] op_sel:[0,0,0] op_sel_hi:[1,0,1]
	v_add_f32_dpp v48, v48, v48 quad_perm:[2,3,0,1] row_mask:0xf bank_mask:0xf bound_ctrl:1
	v_add_f32_dpp v49, v49, v49 quad_perm:[2,3,0,1] row_mask:0xf bank_mask:0xf bound_ctrl:1
	v_add_f32_dpp v50, v50, v50 quad_perm:[2,3,0,1] row_mask:0xf bank_mask:0xf bound_ctrl:1
	v_add_f32_dpp v51, v51, v51 quad_perm:[2,3,0,1] row_mask:0xf bank_mask:0xf bound_ctrl:1
	v_pk_fma_f32 v[102:103], v[146:147], v[72:73], v[102:103] op_sel:[0,1,0] op_sel_hi:[1,1,1]
	v_pk_fma_f32 v[104:105], v[146:147], v[74:75], v[104:105] op_sel:[0,0,0] op_sel_hi:[1,0,1]
	v_pk_fma_f32 v[106:107], v[146:147], v[74:75], v[106:107] op_sel:[0,1,0] op_sel_hi:[1,1,1]
	v_add_f32_dpp v48, v48, v48 row_half_mirror row_mask:0xf bank_mask:0xf bound_ctrl:1
	v_add_f32_dpp v49, v49, v49 row_half_mirror row_mask:0xf bank_mask:0xf bound_ctrl:1
	v_add_f32_dpp v50, v50, v50 row_half_mirror row_mask:0xf bank_mask:0xf bound_ctrl:1
	v_add_f32_dpp v51, v51, v51 row_half_mirror row_mask:0xf bank_mask:0xf bound_ctrl:1
	v_pk_fma_f32 v[108:109], v[146:147], v[76:77], v[108:109] op_sel:[0,0,0] op_sel_hi:[1,0,1]
	s_mov_b64 exec, s[10:11]
	ds_write_b64 v45, v[48:49] offset:3072
	s_mov_b64 exec, s[0:1]
	v_pk_fma_f32 v[110:111], v[146:147], v[76:77], v[110:111] op_sel:[0,1,0] op_sel_hi:[1,1,1]
	s_nop 0
	v_pk_fma_f32 v[96:97], v[50:51], v[78:79], v[96:97] op_sel:[0,0,0] op_sel_hi:[1,0,1]
	v_pk_fma_f32 v[98:99], v[50:51], v[78:79], v[98:99] op_sel:[0,1,0] op_sel_hi:[1,1,1]
	v_pk_fma_f32 v[100:101], v[50:51], v[80:81], v[100:101] op_sel:[0,0,0] op_sel_hi:[1,0,1]
	v_pk_fma_f32 v[102:103], v[50:51], v[80:81], v[102:103] op_sel:[0,1,0] op_sel_hi:[1,1,1]
	v_pk_fma_f32 v[104:105], v[50:51], v[82:83], v[104:105] op_sel:[0,0,0] op_sel_hi:[1,0,1]
	v_pk_fma_f32 v[106:107], v[50:51], v[82:83], v[106:107] op_sel:[0,1,0] op_sel_hi:[1,1,1]
	v_pk_fma_f32 v[108:109], v[50:51], v[84:85], v[108:109] op_sel:[0,0,0] op_sel_hi:[1,0,1]
	v_pk_fma_f32 v[110:111], v[50:51], v[84:85], v[110:111] op_sel:[0,1,0] op_sel_hi:[1,1,1]
	v_pk_mul_f32 v[14:15], v[96:97], v[86:87] op_sel:[0,0] op_sel_hi:[1,0]
	v_pk_mul_f32 v[18:19], v[96:97], v[62:63] op_sel:[0,0] op_sel_hi:[1,0]
	v_pk_mul_f32 v[16:17], v[98:99], v[86:87] op_sel:[0,1] op_sel_hi:[1,1]
	v_pk_mul_f32 v[20:21], v[98:99], v[62:63] op_sel:[0,1] op_sel_hi:[1,1]
	v_pk_fma_f32 v[14:15], v[100:101], v[88:89], v[14:15] op_sel:[0,0,0] op_sel_hi:[1,0,1]
	v_pk_fma_f32 v[18:19], v[100:101], v[64:65], v[18:19] op_sel:[0,0,0] op_sel_hi:[1,0,1]
	v_pk_fma_f32 v[16:17], v[102:103], v[88:89], v[16:17] op_sel:[0,1,0] op_sel_hi:[1,1,1]
	v_pk_fma_f32 v[20:21], v[102:103], v[64:65], v[20:21] op_sel:[0,1,0] op_sel_hi:[1,1,1]
	v_pk_fma_f32 v[14:15], v[104:105], v[90:91], v[14:15] op_sel:[0,0,0] op_sel_hi:[1,0,1]
	v_pk_fma_f32 v[18:19], v[104:105], v[66:67], v[18:19] op_sel:[0,0,0] op_sel_hi:[1,0,1]
	v_pk_fma_f32 v[16:17], v[106:107], v[90:91], v[16:17] op_sel:[0,1,0] op_sel_hi:[1,1,1]
	v_pk_fma_f32 v[20:21], v[106:107], v[66:67], v[20:21] op_sel:[0,1,0] op_sel_hi:[1,1,1]
	v_pk_fma_f32 v[14:15], v[108:109], v[92:93], v[14:15] op_sel:[0,0,0] op_sel_hi:[1,0,1]
	v_pk_fma_f32 v[18:19], v[108:109], v[68:69], v[18:19] op_sel:[0,0,0] op_sel_hi:[1,0,1]
	v_pk_fma_f32 v[16:17], v[110:111], v[92:93], v[16:17] op_sel:[0,1,0] op_sel_hi:[1,1,1]
	v_pk_fma_f32 v[20:21], v[110:111], v[68:69], v[20:21] op_sel:[0,1,0] op_sel_hi:[1,1,1]
	v_pk_add_f32 v[48:49], v[14:15], v[16:17]
	v_pk_add_f32 v[50:51], v[18:19], v[20:21]
	s_waitcnt lgkmcnt(11)
; #define LAS __attribute__((address_space(3)))
; template <int CTRL> __device__ __forceinline__ float dpp_mov(float x) { return __int_as_float(__builtin_amdgcn_update_dpp(0, __float_as_int(x), CTRL, 0xF, 0xF, true)); }
; __device__ __forceinline__ float red8(float x) { x += dpp_mov<0xB1>(x); x += dpp_mov<0x4E>(x); x += dpp_mov<0x141>(x); return x; }
; __device__ __forceinline__ void scan_phase(const KP& P, LAS unsigned char* lds, const int tid, const int bx, const int G) {
;     ...
;             for (int s = 0; s < 32; ++s) {
;                 const LAS float* p = cb + s * 384;
;                 const f32x4 w0 = *(const LAS f32x4*)(p), w1 = *(const LAS f32x4*)(p + 4);
;                 const f32x4 k0 = *(const LAS f32x4*)(p + 64), k1 = *(const LAS f32x4*)(p + 68);
;                 const f32x4 a0 = *(const LAS f32x4*)(p + 128), a1 = *(const LAS f32x4*)(p + 132);
;                 const f32x4 b0 = *(const LAS f32x4*)(p + 192), b1 = *(const LAS f32x4*)(p + 196);
;                 const f32x4 r0 = *(const LAS f32x4*)(p + 256), r1 = *(const LAS f32x4*)(p + 260);
;                 const float vv = buf[(c & 1) * 12288 + s * 384 + 320 + v];
;                 f32x2 sa2 = S[0] * (f32x2){a0.x, a0.y};
;                 sa2 += S[1] * (f32x2){a0.z, a0.w}; sa2 += S[2] * (f32x2){a1.x, a1.y}; sa2 += S[3] * (f32x2){a1.z, a1.w};
;                 const float sa = red8(sa2.x + sa2.y);
;                 const f32x2 sav = {sa, sa}, vv2 = {vv, vv};
;                 S[0] = S[0] * (f32x2){w0.x, w0.y} + sav * (f32x2){b0.x, b0.y} + vv2 * (f32x2){k0.x, k0.y};
;                 S[1] = S[1] * (f32x2){w0.z, w0.w} + sav * (f32x2){b0.z, b0.w} + vv2 * (f32x2){k0.z, k0.w};
;                 S[2] = S[2] * (f32x2){w1.x, w1.y} + sav * (f32x2){b1.x, b1.y} + vv2 * (f32x2){k1.x, k1.y};
;                 S[3] = S[3] * (f32x2){w1.z, w1.w} + sav * (f32x2){b1.z, b1.w} + vv2 * (f32x2){k1.z, k1.w};
;                 f32x2 y2 = S[0] * (f32x2){r0.x, r0.y};
;                 y2 += S[1] * (f32x2){r0.z, r0.w}; y2 += S[2] * (f32x2){r1.x, r1.y}; y2 += S[3] * (f32x2){r1.z, r1.w};
;                 const float y = red8(y2.x + y2.y);
;                 if (kc == 0) ybuf[s * 64 + v] = y;
	ds_read_b128 v[70:73], v44 offset:24832
	ds_read_b128 v[74:77], v44 offset:24848
	ds_read_b128 v[78:81], v44 offset:25344
	ds_read_b128 v[82:85], v44 offset:25360
	ds_read_b128 v[86:89], v44 offset:25600
	ds_read_b128 v[90:93], v44 offset:25616
	ds_read_b64 v[146:147], v46 offset:24576
	ds_read_b128 v[62:65], v44 offset:26624
	ds_read_b128 v[66:69], v44 offset:26640
	v_add_f32_dpp v48, v48, v48 quad_perm:[1,0,3,2] row_mask:0xf bank_mask:0xf bound_ctrl:1
	v_add_f32_dpp v49, v49, v49 quad_perm:[1,0,3,2] row_mask:0xf bank_mask:0xf bound_ctrl:1
	v_add_f32_dpp v50, v50, v50 quad_perm:[1,0,3,2] row_mask:0xf bank_mask:0xf bound_ctrl:1
	v_add_f32_dpp v51, v51, v51 quad_perm:[1,0,3,2] row_mask:0xf bank_mask:0xf bound_ctrl:1
	v_pk_fma_f32 v[96:97], v[192:193], v[168:169], v[96:97] op_sel:[0,0,0] op_sel_hi:[1,0,1]
	v_pk_fma_f32 v[98:99], v[192:193], v[168:169], v[98:99] op_sel:[0,1,0] op_sel_hi:[1,1,1]
	v_pk_fma_f32 v[100:101], v[192:193], v[170:171], v[100:101] op_sel:[0,0,0] op_sel_hi:[1,0,1]
	v_add_f32_dpp v48, v48, v48 quad_perm:[2,3,0,1] row_mask:0xf bank_mask:0xf bound_ctrl:1
	v_add_f32_dpp v49, v49, v49 quad_perm:[2,3,0,1] row_mask:0xf bank_mask:0xf bound_ctrl:1
	v_add_f32_dpp v50, v50, v50 quad_perm:[2,3,0,1] row_mask:0xf bank_mask:0xf bound_ctrl:1
	v_add_f32_dpp v51, v51, v51 quad_perm:[2,3,0,1] row_mask:0xf bank_mask:0xf bound_ctrl:1
	v_pk_fma_f32 v[102:103], v[192:193], v[170:171], v[102:103] op_sel:[0,1,0] op_sel_hi:[1,1,1]
	v_pk_fma_f32 v[104:105], v[192:193], v[172:173], v[104:105] op_sel:[0,0,0] op_sel_hi:[1,0,1]
	v_pk_fma_f32 v[106:107], v[192:193], v[172:173], v[106:107] op_sel:[0,1,0] op_sel_hi:[1,1,1]
	v_add_f32_dpp v48, v48, v48 row_half_mirror row_mask:0xf bank_mask:0xf bound_ctrl:1
	v_add_f32_dpp v49, v49, v49 row_half_mirror row_mask:0xf bank_mask:0xf bound_ctrl:1
	v_add_f32_dpp v50, v50, v50 row_half_mirror row_mask:0xf bank_mask:0xf bound_ctrl:1
	v_add_f32_dpp v51, v51, v51 row_half_mirror row_mask:0xf bank_mask:0xf bound_ctrl:1
	v_pk_fma_f32 v[108:109], v[192:193], v[174:175], v[108:109] op_sel:[0,0,0] op_sel_hi:[1,0,1]
	s_mov_b64 exec, s[10:11]
	ds_write_b64 v45, v[48:49] offset:3328
	s_mov_b64 exec, s[0:1]
	v_pk_fma_f32 v[110:111], v[192:193], v[174:175], v[110:111] op_sel:[0,1,0] op_sel_hi:[1,1,1]
	s_nop 0
	v_pk_fma_f32 v[96:97], v[50:51], v[176:177], v[96:97] op_sel:[0,0,0] op_sel_hi:[1,0,1]
	v_pk_fma_f32 v[98:99], v[50:51], v[176:177], v[98:99] op_sel:[0,1,0] op_sel_hi:[1,1,1]
	v_pk_fma_f32 v[100:101], v[50:51], v[178:179], v[100:101] op_sel:[0,0,0] op_sel_hi:[1,0,1]
	v_pk_fma_f32 v[102:103], v[50:51], v[178:179], v[102:103] op_sel:[0,1,0] op_sel_hi:[1,1,1]
	v_pk_fma_f32 v[104:105], v[50:51], v[180:181], v[104:105] op_sel:[0,0,0] op_sel_hi:[1,0,1]
	v_pk_fma_f32 v[106:107], v[50:51], v[180:181], v[106:107] op_sel:[0,1,0] op_sel_hi:[1,1,1]
	v_pk_fma_f32 v[108:109], v[50:51], v[182:183], v[108:109] op_sel:[0,0,0] op_sel_hi:[1,0,1]
	v_pk_fma_f32 v[110:111], v[50:51], v[182:183], v[110:111] op_sel:[0,1,0] op_sel_hi:[1,1,1]
	v_pk_mul_f32 v[14:15], v[96:97], v[184:185] op_sel:[0,0] op_sel_hi:[1,0]
	v_pk_mul_f32 v[18:19], v[96:97], v[148:149] op_sel:[0,0] op_sel_hi:[1,0]
	v_pk_mul_f32 v[16:17], v[98:99], v[184:185] op_sel:[0,1] op_sel_hi:[1,1]
	v_pk_mul_f32 v[20:21], v[98:99], v[148:149] op_sel:[0,1] op_sel_hi:[1,1]
	v_pk_fma_f32 v[14:15], v[100:101], v[186:187], v[14:15] op_sel:[0,0,0] op_sel_hi:[1,0,1]
	v_pk_fma_f32 v[18:19], v[100:101], v[150:151], v[18:19] op_sel:[0,0,0] op_sel_hi:[1,0,1]
	v_pk_fma_f32 v[16:17], v[102:103], v[186:187], v[16:17] op_sel:[0,1,0] op_sel_hi:[1,1,1]
	v_pk_fma_f32 v[20:21], v[102:103], v[150:151], v[20:21] op_sel:[0,1,0] op_sel_hi:[1,1,1]
	v_pk_fma_f32 v[14:15], v[104:105], v[188:189], v[14:15] op_sel:[0,0,0] op_sel_hi:[1,0,1]
	v_pk_fma_f32 v[18:19], v[104:105], v[152:153], v[18:19] op_sel:[0,0,0] op_sel_hi:[1,0,1]
	v_pk_fma_f32 v[16:17], v[106:107], v[188:189], v[16:17] op_sel:[0,1,0] op_sel_hi:[1,1,1]
	v_pk_fma_f32 v[20:21], v[106:107], v[152:153], v[20:21] op_sel:[0,1,0] op_sel_hi:[1,1,1]
	v_pk_fma_f32 v[14:15], v[108:109], v[190:191], v[14:15] op_sel:[0,0,0] op_sel_hi:[1,0,1]
	v_pk_fma_f32 v[18:19], v[108:109], v[154:155], v[18:19] op_sel:[0,0,0] op_sel_hi:[1,0,1]
	v_pk_fma_f32 v[16:17], v[110:111], v[190:191], v[16:17] op_sel:[0,1,0] op_sel_hi:[1,1,1]
	v_pk_fma_f32 v[20:21], v[110:111], v[154:155], v[20:21] op_sel:[0,1,0] op_sel_hi:[1,1,1]
	v_pk_add_f32 v[48:49], v[14:15], v[16:17]
	v_pk_add_f32 v[50:51], v[18:19], v[20:21]
	s_waitcnt lgkmcnt(11)
; #define LAS __attribute__((address_space(3)))
; template <int CTRL> __device__ __forceinline__ float dpp_mov(float x) { return __int_as_float(__builtin_amdgcn_update_dpp(0, __float_as_int(x), CTRL, 0xF, 0xF, true)); }
; __device__ __forceinline__ float red8(float x) { x += dpp_mov<0xB1>(x); x += dpp_mov<0x4E>(x); x += dpp_mov<0x141>(x); return x; }
; __device__ __forceinline__ void scan_phase(const KP& P, LAS unsigned char* lds, const int tid, const int bx, const int G) {
;     ...
;             for (int s = 0; s < 32; ++s) {
;                 const LAS float* p = cb + s * 384;
;                 const f32x4 w0 = *(const LAS f32x4*)(p), w1 = *(const LAS f32x4*)(p + 4);
;                 const f32x4 k0 = *(const LAS f32x4*)(p + 64), k1 = *(const LAS f32x4*)(p + 68);
;                 const f32x4 a0 = *(const LAS f32x4*)(p + 128), a1 = *(const LAS f32x4*)(p + 132);
;                 const f32x4 b0 = *(const LAS f32x4*)(p + 192), b1 = *(const LAS f32x4*)(p + 196);
;                 const f32x4 r0 = *(const LAS f32x4*)(p + 256), r1 = *(const LAS f32x4*)(p + 260);
;                 const float vv = buf[(c & 1) * 12288 + s * 384 + 320 + v];
;                 f32x2 sa2 = S[0] * (f32x2){a0.x, a0.y};
;                 sa2 += S[1] * (f32x2){a0.z, a0.w}; sa2 += S[2] * (f32x2){a1.x, a1.y}; sa2 += S[3] * (f32x2){a1.z, a1.w};
;                 const float sa = red8(sa2.x + sa2.y);
;                 const f32x2 sav = {sa, sa}, vv2 = {vv, vv};
;                 S[0] = S[0] * (f32x2){w0.x, w0.y} + sav * (f32x2){b0.x, b0.y} + vv2 * (f32x2){k0.x, k0.y};
;                 S[1] = S[1] * (f32x2){w0.z, w0.w} + sav * (f32x2){b0.z, b0.w} + vv2 * (f32x2){k0.z, k0.w};
;                 S[2] = S[2] * (f32x2){w1.x, w1.y} + sav * (f32x2){b1.x, b1.y} + vv2 * (f32x2){k1.x, k1.y};
;                 S[3] = S[3] * (f32x2){w1.z, w1.w} + sav * (f32x2){b1.z, b1.w} + vv2 * (f32x2){k1.z, k1.w};
;                 f32x2 y2 = S[0] * (f32x2){r0.x, r0.y};
;                 y2 += S[1] * (f32x2){r0.z, r0.w}; y2 += S[2] * (f32x2){r1.x, r1.y}; y2 += S[3] * (f32x2){r1.z, r1.w};
;                 const float y = red8(y2.x + y2.y);
;                 if (kc == 0) ybuf[s * 64 + v] = y;
	ds_read_b128 v[168:171], v44 offset:26368
	ds_read_b128 v[172:175], v44 offset:26384
	ds_read_b128 v[176:179], v44 offset:26880
	ds_read_b128 v[180:183], v44 offset:26896
	ds_read_b128 v[184:187], v44 offset:27136
	ds_read_b128 v[188:191], v44 offset:27152
	ds_read_b64 v[192:193], v46 offset:26112
	ds_read_b128 v[148:151], v44 offset:28160
	ds_read_b128 v[152:155], v44 offset:28176
	v_add_f32_dpp v48, v48, v48 quad_perm:[1,0,3,2] row_mask:0xf bank_mask:0xf bound_ctrl:1
	v_add_f32_dpp v49, v49, v49 quad_perm:[1,0,3,2] row_mask:0xf bank_mask:0xf bound_ctrl:1
	v_add_f32_dpp v50, v50, v50 quad_perm:[1,0,3,2] row_mask:0xf bank_mask:0xf bound_ctrl:1
	v_add_f32_dpp v51, v51, v51 quad_perm:[1,0,3,2] row_mask:0xf bank_mask:0xf bound_ctrl:1
	v_pk_fma_f32 v[96:97], v[144:145], v[120:121], v[96:97] op_sel:[0,0,0] op_sel_hi:[1,0,1]
	v_pk_fma_f32 v[98:99], v[144:145], v[120:121], v[98:99] op_sel:[0,1,0] op_sel_hi:[1,1,1]
	v_pk_fma_f32 v[100:101], v[144:145], v[122:123], v[100:101] op_sel:[0,0,0] op_sel_hi:[1,0,1]
	v_add_f32_dpp v48, v48, v48 quad_perm:[2,3,0,1] row_mask:0xf bank_mask:0xf bound_ctrl:1
	v_add_f32_dpp v49, v49, v49 quad_perm:[2,3,0,1] row_mask:0xf bank_mask:0xf bound_ctrl:1
	v_add_f32_dpp v50, v50, v50 quad_perm:[2,3,0,1] row_mask:0xf bank_mask:0xf bound_ctrl:1
	v_add_f32_dpp v51, v51, v51 quad_perm:[2,3,0,1] row_mask:0xf bank_mask:0xf bound_ctrl:1
	v_pk_fma_f32 v[102:103], v[144:145], v[122:123], v[102:103] op_sel:[0,1,0] op_sel_hi:[1,1,1]
	v_pk_fma_f32 v[104:105], v[144:145], v[124:125], v[104:105] op_sel:[0,0,0] op_sel_hi:[1,0,1]
	v_pk_fma_f32 v[106:107], v[144:145], v[124:125], v[106:107] op_sel:[0,1,0] op_sel_hi:[1,1,1]
	v_add_f32_dpp v48, v48, v48 row_half_mirror row_mask:0xf bank_mask:0xf bound_ctrl:1
	v_add_f32_dpp v49, v49, v49 row_half_mirror row_mask:0xf bank_mask:0xf bound_ctrl:1
	v_add_f32_dpp v50, v50, v50 row_half_mirror row_mask:0xf bank_mask:0xf bound_ctrl:1
	v_add_f32_dpp v51, v51, v51 row_half_mirror row_mask:0xf bank_mask:0xf bound_ctrl:1
	v_pk_fma_f32 v[108:109], v[144:145], v[126:127], v[108:109] op_sel:[0,0,0] op_sel_hi:[1,0,1]
	s_mov_b64 exec, s[10:11]
	ds_write_b64 v45, v[48:49] offset:3584
	s_mov_b64 exec, s[0:1]
	v_pk_fma_f32 v[110:111], v[144:145], v[126:127], v[110:111] op_sel:[0,1,0] op_sel_hi:[1,1,1]
	s_nop 0
	v_pk_fma_f32 v[96:97], v[50:51], v[128:129], v[96:97] op_sel:[0,0,0] op_sel_hi:[1,0,1]
	v_pk_fma_f32 v[98:99], v[50:51], v[128:129], v[98:99] op_sel:[0,1,0] op_sel_hi:[1,1,1]
	v_pk_fma_f32 v[100:101], v[50:51], v[130:131], v[100:101] op_sel:[0,0,0] op_sel_hi:[1,0,1]
	v_pk_fma_f32 v[102:103], v[50:51], v[130:131], v[102:103] op_sel:[0,1,0] op_sel_hi:[1,1,1]
	v_pk_fma_f32 v[104:105], v[50:51], v[132:133], v[104:105] op_sel:[0,0,0] op_sel_hi:[1,0,1]
	v_pk_fma_f32 v[106:107], v[50:51], v[132:133], v[106:107] op_sel:[0,1,0] op_sel_hi:[1,1,1]
	v_pk_fma_f32 v[108:109], v[50:51], v[134:135], v[108:109] op_sel:[0,0,0] op_sel_hi:[1,0,1]
	v_pk_fma_f32 v[110:111], v[50:51], v[134:135], v[110:111] op_sel:[0,1,0] op_sel_hi:[1,1,1]
	v_pk_mul_f32 v[14:15], v[96:97], v[136:137] op_sel:[0,0] op_sel_hi:[1,0]
	v_pk_mul_f32 v[18:19], v[96:97], v[156:157] op_sel:[0,0] op_sel_hi:[1,0]
	v_pk_mul_f32 v[16:17], v[98:99], v[136:137] op_sel:[0,1] op_sel_hi:[1,1]
	v_pk_mul_f32 v[20:21], v[98:99], v[156:157] op_sel:[0,1] op_sel_hi:[1,1]
	v_pk_fma_f32 v[14:15], v[100:101], v[138:139], v[14:15] op_sel:[0,0,0] op_sel_hi:[1,0,1]
	v_pk_fma_f32 v[18:19], v[100:101], v[158:159], v[18:19] op_sel:[0,0,0] op_sel_hi:[1,0,1]
	v_pk_fma_f32 v[16:17], v[102:103], v[138:139], v[16:17] op_sel:[0,1,0] op_sel_hi:[1,1,1]
	v_pk_fma_f32 v[20:21], v[102:103], v[158:159], v[20:21] op_sel:[0,1,0] op_sel_hi:[1,1,1]
	v_pk_fma_f32 v[14:15], v[104:105], v[140:141], v[14:15] op_sel:[0,0,0] op_sel_hi:[1,0,1]
	v_pk_fma_f32 v[18:19], v[104:105], v[160:161], v[18:19] op_sel:[0,0,0] op_sel_hi:[1,0,1]
	v_pk_fma_f32 v[16:17], v[106:107], v[140:141], v[16:17] op_sel:[0,1,0] op_sel_hi:[1,1,1]
	v_pk_fma_f32 v[20:21], v[106:107], v[160:161], v[20:21] op_sel:[0,1,0] op_sel_hi:[1,1,1]
	v_pk_fma_f32 v[14:15], v[108:109], v[142:143], v[14:15] op_sel:[0,0,0] op_sel_hi:[1,0,1]
	v_pk_fma_f32 v[18:19], v[108:109], v[162:163], v[18:19] op_sel:[0,0,0] op_sel_hi:[1,0,1]
	v_pk_fma_f32 v[16:17], v[110:111], v[142:143], v[16:17] op_sel:[0,1,0] op_sel_hi:[1,1,1]
	v_pk_fma_f32 v[20:21], v[110:111], v[162:163], v[20:21] op_sel:[0,1,0] op_sel_hi:[1,1,1]
	v_pk_add_f32 v[48:49], v[14:15], v[16:17]
	v_pk_add_f32 v[50:51], v[18:19], v[20:21]
	s_waitcnt lgkmcnt(11)
; #define LAS __attribute__((address_space(3)))
; template <int CTRL> __device__ __forceinline__ float dpp_mov(float x) { return __int_as_float(__builtin_amdgcn_update_dpp(0, __float_as_int(x), CTRL, 0xF, 0xF, true)); }
; __device__ __forceinline__ float red8(float x) { x += dpp_mov<0xB1>(x); x += dpp_mov<0x4E>(x); x += dpp_mov<0x141>(x); return x; }
; __device__ __forceinline__ void scan_phase(const KP& P, LAS unsigned char* lds, const int tid, const int bx, const int G) {
;     ...
;             for (int s = 0; s < 32; ++s) {
;                 const LAS float* p = cb + s * 384;
;                 const f32x4 w0 = *(const LAS f32x4*)(p), w1 = *(const LAS f32x4*)(p + 4);
;                 const f32x4 k0 = *(const LAS f32x4*)(p + 64), k1 = *(const LAS f32x4*)(p + 68);
;                 const f32x4 a0 = *(const LAS f32x4*)(p + 128), a1 = *(const LAS f32x4*)(p + 132);
;                 const f32x4 b0 = *(const LAS f32x4*)(p + 192), b1 = *(const LAS f32x4*)(p + 196);
;                 const f32x4 r0 = *(const LAS f32x4*)(p + 256), r1 = *(const LAS f32x4*)(p + 260);
;                 const float vv = buf[(c & 1) * 12288 + s * 384 + 320 + v];
;                 f32x2 sa2 = S[0] * (f32x2){a0.x, a0.y};
;                 sa2 += S[1] * (f32x2){a0.z, a0.w}; sa2 += S[2] * (f32x2){a1.x, a1.y}; sa2 += S[3] * (f32x2){a1.z, a1.w};
;                 const float sa = red8(sa2.x + sa2.y);
;                 const f32x2 sav = {sa, sa}, vv2 = {vv, vv};
;                 S[0] = S[0] * (f32x2){w0.x, w0.y} + sav * (f32x2){b0.x, b0.y} + vv2 * (f32x2){k0.x, k0.y};
;                 S[1] = S[1] * (f32x2){w0.z, w0.w} + sav * (f32x2){b0.z, b0.w} + vv2 * (f32x2){k0.z, k0.w};
;                 S[2] = S[2] * (f32x2){w1.x, w1.y} + sav * (f32x2){b1.x, b1.y} + vv2 * (f32x2){k1.x, k1.y};
;                 S[3] = S[3] * (f32x2){w1.z, w1.w} + sav * (f32x2){b1.z, b1.w} + vv2 * (f32x2){k1.z, k1.w};
;                 f32x2 y2 = S[0] * (f32x2){r0.x, r0.y};
;                 y2 += S[1] * (f32x2){r0.z, r0.w}; y2 += S[2] * (f32x2){r1.x, r1.y}; y2 += S[3] * (f32x2){r1.z, r1.w};
;                 const float y = red8(y2.x + y2.y);
;                 if (kc == 0) ybuf[s * 64 + v] = y;
	ds_read_b128 v[120:123], v44 offset:27904
	ds_read_b128 v[124:127], v44 offset:27920
	ds_read_b128 v[128:131], v44 offset:28416
	ds_read_b128 v[132:135], v44 offset:28432
	ds_read_b128 v[136:139], v44 offset:28672
	ds_read_b128 v[140:143], v44 offset:28688
	ds_read_b64 v[144:145], v46 offset:27648
	ds_read_b128 v[156:159], v44 offset:29696
	ds_read_b128 v[160:163], v44 offset:29712
	v_add_f32_dpp v48, v48, v48 quad_perm:[1,0,3,2] row_mask:0xf bank_mask:0xf bound_ctrl:1
	v_add_f32_dpp v49, v49, v49 quad_perm:[1,0,3,2] row_mask:0xf bank_mask:0xf bound_ctrl:1
	v_add_f32_dpp v50, v50, v50 quad_perm:[1,0,3,2] row_mask:0xf bank_mask:0xf bound_ctrl:1
	v_add_f32_dpp v51, v51, v51 quad_perm:[1,0,3,2] row_mask:0xf bank_mask:0xf bound_ctrl:1
	v_pk_fma_f32 v[96:97], v[146:147], v[70:71], v[96:97] op_sel:[0,0,0] op_sel_hi:[1,0,1]
	v_pk_fma_f32 v[98:99], v[146:147], v[70:71], v[98:99] op_sel:[0,1,0] op_sel_hi:[1,1,1]
	v_pk_fma_f32 v[100:101], v[146:147], v[72:73], v[100:101] op_sel:[0,0,0] op_sel_hi:[1,0,1]
	v_add_f32_dpp v48, v48, v48 quad_perm:[2,3,0,1] row_mask:0xf bank_mask:0xf bound_ctrl:1
	v_add_f32_dpp v49, v49, v49 quad_perm:[2,3,0,1] row_mask:0xf bank_mask:0xf bound_ctrl:1
	v_add_f32_dpp v50, v50, v50 quad_perm:[2,3,0,1] row_mask:0xf bank_mask:0xf bound_ctrl:1
	v_add_f32_dpp v51, v51, v51 quad_perm:[2,3,0,1] row_mask:0xf bank_mask:0xf bound_ctrl:1
	v_pk_fma_f32 v[102:103], v[146:147], v[72:73], v[102:103] op_sel:[0,1,0] op_sel_hi:[1,1,1]
	v_pk_fma_f32 v[104:105], v[146:147], v[74:75], v[104:105] op_sel:[0,0,0] op_sel_hi:[1,0,1]
	v_pk_fma_f32 v[106:107], v[146:147], v[74:75], v[106:107] op_sel:[0,1,0] op_sel_hi:[1,1,1]
	v_add_f32_dpp v48, v48, v48 row_half_mirror row_mask:0xf bank_mask:0xf bound_ctrl:1
	v_add_f32_dpp v49, v49, v49 row_half_mirror row_mask:0xf bank_mask:0xf bound_ctrl:1
	v_add_f32_dpp v50, v50, v50 row_half_mirror row_mask:0xf bank_mask:0xf bound_ctrl:1
	v_add_f32_dpp v51, v51, v51 row_half_mirror row_mask:0xf bank_mask:0xf bound_ctrl:1
	v_pk_fma_f32 v[108:109], v[146:147], v[76:77], v[108:109] op_sel:[0,0,0] op_sel_hi:[1,0,1]
	s_mov_b64 exec, s[10:11]
	ds_write_b64 v45, v[48:49] offset:3840
	s_mov_b64 exec, s[0:1]
	v_pk_fma_f32 v[110:111], v[146:147], v[76:77], v[110:111] op_sel:[0,1,0] op_sel_hi:[1,1,1]
	s_nop 0
	v_pk_fma_f32 v[96:97], v[50:51], v[78:79], v[96:97] op_sel:[0,0,0] op_sel_hi:[1,0,1]
	v_pk_fma_f32 v[98:99], v[50:51], v[78:79], v[98:99] op_sel:[0,1,0] op_sel_hi:[1,1,1]
	v_pk_fma_f32 v[100:101], v[50:51], v[80:81], v[100:101] op_sel:[0,0,0] op_sel_hi:[1,0,1]
	v_pk_fma_f32 v[102:103], v[50:51], v[80:81], v[102:103] op_sel:[0,1,0] op_sel_hi:[1,1,1]
	v_pk_fma_f32 v[104:105], v[50:51], v[82:83], v[104:105] op_sel:[0,0,0] op_sel_hi:[1,0,1]
	v_pk_fma_f32 v[106:107], v[50:51], v[82:83], v[106:107] op_sel:[0,1,0] op_sel_hi:[1,1,1]
	v_pk_fma_f32 v[108:109], v[50:51], v[84:85], v[108:109] op_sel:[0,0,0] op_sel_hi:[1,0,1]
	v_pk_fma_f32 v[110:111], v[50:51], v[84:85], v[110:111] op_sel:[0,1,0] op_sel_hi:[1,1,1]
	v_pk_mul_f32 v[14:15], v[96:97], v[86:87] op_sel:[0,0] op_sel_hi:[1,0]
	v_pk_mul_f32 v[18:19], v[96:97], v[62:63] op_sel:[0,0] op_sel_hi:[1,0]
	v_pk_mul_f32 v[16:17], v[98:99], v[86:87] op_sel:[0,1] op_sel_hi:[1,1]
	v_pk_mul_f32 v[20:21], v[98:99], v[62:63] op_sel:[0,1] op_sel_hi:[1,1]
	v_pk_fma_f32 v[14:15], v[100:101], v[88:89], v[14:15] op_sel:[0,0,0] op_sel_hi:[1,0,1]
	v_pk_fma_f32 v[18:19], v[100:101], v[64:65], v[18:19] op_sel:[0,0,0] op_sel_hi:[1,0,1]
	v_pk_fma_f32 v[16:17], v[102:103], v[88:89], v[16:17] op_sel:[0,1,0] op_sel_hi:[1,1,1]
	v_pk_fma_f32 v[20:21], v[102:103], v[64:65], v[20:21] op_sel:[0,1,0] op_sel_hi:[1,1,1]
	v_pk_fma_f32 v[14:15], v[104:105], v[90:91], v[14:15] op_sel:[0,0,0] op_sel_hi:[1,0,1]
	v_pk_fma_f32 v[18:19], v[104:105], v[66:67], v[18:19] op_sel:[0,0,0] op_sel_hi:[1,0,1]
	v_pk_fma_f32 v[16:17], v[106:107], v[90:91], v[16:17] op_sel:[0,1,0] op_sel_hi:[1,1,1]
	v_pk_fma_f32 v[20:21], v[106:107], v[66:67], v[20:21] op_sel:[0,1,0] op_sel_hi:[1,1,1]
	v_pk_fma_f32 v[14:15], v[108:109], v[92:93], v[14:15] op_sel:[0,0,0] op_sel_hi:[1,0,1]
	v_pk_fma_f32 v[18:19], v[108:109], v[68:69], v[18:19] op_sel:[0,0,0] op_sel_hi:[1,0,1]
	v_pk_fma_f32 v[16:17], v[110:111], v[92:93], v[16:17] op_sel:[0,1,0] op_sel_hi:[1,1,1]
	v_pk_fma_f32 v[20:21], v[110:111], v[68:69], v[20:21] op_sel:[0,1,0] op_sel_hi:[1,1,1]
	v_pk_add_f32 v[48:49], v[14:15], v[16:17]
	v_pk_add_f32 v[50:51], v[18:19], v[20:21]
	s_waitcnt lgkmcnt(11)
; #define LAS __attribute__((address_space(3)))
; template <int CTRL> __device__ __forceinline__ float dpp_mov(float x) { return __int_as_float(__builtin_amdgcn_update_dpp(0, __float_as_int(x), CTRL, 0xF, 0xF, true)); }
; __device__ __forceinline__ float red8(float x) { x += dpp_mov<0xB1>(x); x += dpp_mov<0x4E>(x); x += dpp_mov<0x141>(x); return x; }
; __device__ __forceinline__ void scan_phase(const KP& P, LAS unsigned char* lds, const int tid, const int bx, const int G) {
;     ...
;             for (int s = 0; s < 32; ++s) {
;                 const LAS float* p = cb + s * 384;
;                 const f32x4 w0 = *(const LAS f32x4*)(p), w1 = *(const LAS f32x4*)(p + 4);
;                 const f32x4 k0 = *(const LAS f32x4*)(p + 64), k1 = *(const LAS f32x4*)(p + 68);
;                 const f32x4 a0 = *(const LAS f32x4*)(p + 128), a1 = *(const LAS f32x4*)(p + 132);
;                 const f32x4 b0 = *(const LAS f32x4*)(p + 192), b1 = *(const LAS f32x4*)(p + 196);
;                 const f32x4 r0 = *(const LAS f32x4*)(p + 256), r1 = *(const LAS f32x4*)(p + 260);
;                 const float vv = buf[(c & 1) * 12288 + s * 384 + 320 + v];
;                 f32x2 sa2 = S[0] * (f32x2){a0.x, a0.y};
;                 sa2 += S[1] * (f32x2){a0.z, a0.w}; sa2 += S[2] * (f32x2){a1.x, a1.y}; sa2 += S[3] * (f32x2){a1.z, a1.w};
;                 const float sa = red8(sa2.x + sa2.y);
;                 const f32x2 sav = {sa, sa}, vv2 = {vv, vv};
;                 S[0] = S[0] * (f32x2){w0.x, w0.y} + sav * (f32x2){b0.x, b0.y} + vv2 * (f32x2){k0.x, k0.y};
;                 S[1] = S[1] * (f32x2){w0.z, w0.w} + sav * (f32x2){b0.z, b0.w} + vv2 * (f32x2){k0.z, k0.w};
;                 S[2] = S[2] * (f32x2){w1.x, w1.y} + sav * (f32x2){b1.x, b1.y} + vv2 * (f32x2){k1.x, k1.y};
;                 S[3] = S[3] * (f32x2){w1.z, w1.w} + sav * (f32x2){b1.z, b1.w} + vv2 * (f32x2){k1.z, k1.w};
;                 f32x2 y2 = S[0] * (f32x2){r0.x, r0.y};
;                 y2 += S[1] * (f32x2){r0.z, r0.w}; y2 += S[2] * (f32x2){r1.x, r1.y}; y2 += S[3] * (f32x2){r1.z, r1.w};
;                 const float y = red8(y2.x + y2.y);
;                 if (kc == 0) ybuf[s * 64 + v] = y;
	ds_read_b128 v[70:73], v44 offset:29440
	ds_read_b128 v[74:77], v44 offset:29456
	ds_read_b128 v[78:81], v44 offset:29952
	ds_read_b128 v[82:85], v44 offset:29968
	ds_read_b128 v[86:89], v44 offset:30208
	ds_read_b128 v[90:93], v44 offset:30224
	ds_read_b64 v[146:147], v46 offset:29184
	ds_read_b128 v[62:65], v44 offset:31232
	ds_read_b128 v[66:69], v44 offset:31248
	v_add_f32_dpp v48, v48, v48 quad_perm:[1,0,3,2] row_mask:0xf bank_mask:0xf bound_ctrl:1
	v_add_f32_dpp v49, v49, v49 quad_perm:[1,0,3,2] row_mask:0xf bank_mask:0xf bound_ctrl:1
	v_add_f32_dpp v50, v50, v50 quad_perm:[1,0,3,2] row_mask:0xf bank_mask:0xf bound_ctrl:1
	v_add_f32_dpp v51, v51, v51 quad_perm:[1,0,3,2] row_mask:0xf bank_mask:0xf bound_ctrl:1
	v_pk_fma_f32 v[96:97], v[192:193], v[168:169], v[96:97] op_sel:[0,0,0] op_sel_hi:[1,0,1]
	v_pk_fma_f32 v[98:99], v[192:193], v[168:169], v[98:99] op_sel:[0,1,0] op_sel_hi:[1,1,1]
	v_pk_fma_f32 v[100:101], v[192:193], v[170:171], v[100:101] op_sel:[0,0,0] op_sel_hi:[1,0,1]
	v_add_f32_dpp v48, v48, v48 quad_perm:[2,3,0,1] row_mask:0xf bank_mask:0xf bound_ctrl:1
	v_add_f32_dpp v49, v49, v49 quad_perm:[2,3,0,1] row_mask:0xf bank_mask:0xf bound_ctrl:1
	v_add_f32_dpp v50, v50, v50 quad_perm:[2,3,0,1] row_mask:0xf bank_mask:0xf bound_ctrl:1
	v_add_f32_dpp v51, v51, v51 quad_perm:[2,3,0,1] row_mask:0xf bank_mask:0xf bound_ctrl:1
	v_pk_fma_f32 v[102:103], v[192:193], v[170:171], v[102:103] op_sel:[0,1,0] op_sel_hi:[1,1,1]
	v_pk_fma_f32 v[104:105], v[192:193], v[172:173], v[104:105] op_sel:[0,0,0] op_sel_hi:[1,0,1]
	v_pk_fma_f32 v[106:107], v[192:193], v[172:173], v[106:107] op_sel:[0,1,0] op_sel_hi:[1,1,1]
	v_add_f32_dpp v48, v48, v48 row_half_mirror row_mask:0xf bank_mask:0xf bound_ctrl:1
	v_add_f32_dpp v49, v49, v49 row_half_mirror row_mask:0xf bank_mask:0xf bound_ctrl:1
	v_add_f32_dpp v50, v50, v50 row_half_mirror row_mask:0xf bank_mask:0xf bound_ctrl:1
	v_add_f32_dpp v51, v51, v51 row_half_mirror row_mask:0xf bank_mask:0xf bound_ctrl:1
	v_pk_fma_f32 v[108:109], v[192:193], v[174:175], v[108:109] op_sel:[0,0,0] op_sel_hi:[1,0,1]
	s_mov_b64 exec, s[10:11]
	ds_write_b64 v45, v[48:49] offset:4096
	s_mov_b64 exec, s[0:1]
	v_pk_fma_f32 v[110:111], v[192:193], v[174:175], v[110:111] op_sel:[0,1,0] op_sel_hi:[1,1,1]
	s_nop 0
	v_pk_fma_f32 v[96:97], v[50:51], v[176:177], v[96:97] op_sel:[0,0,0] op_sel_hi:[1,0,1]
	v_pk_fma_f32 v[98:99], v[50:51], v[176:177], v[98:99] op_sel:[0,1,0] op_sel_hi:[1,1,1]
	v_pk_fma_f32 v[100:101], v[50:51], v[178:179], v[100:101] op_sel:[0,0,0] op_sel_hi:[1,0,1]
	v_pk_fma_f32 v[102:103], v[50:51], v[178:179], v[102:103] op_sel:[0,1,0] op_sel_hi:[1,1,1]
	v_pk_fma_f32 v[104:105], v[50:51], v[180:181], v[104:105] op_sel:[0,0,0] op_sel_hi:[1,0,1]
	v_pk_fma_f32 v[106:107], v[50:51], v[180:181], v[106:107] op_sel:[0,1,0] op_sel_hi:[1,1,1]
	v_pk_fma_f32 v[108:109], v[50:51], v[182:183], v[108:109] op_sel:[0,0,0] op_sel_hi:[1,0,1]
	v_pk_fma_f32 v[110:111], v[50:51], v[182:183], v[110:111] op_sel:[0,1,0] op_sel_hi:[1,1,1]
	v_pk_mul_f32 v[14:15], v[96:97], v[184:185] op_sel:[0,0] op_sel_hi:[1,0]
	v_pk_mul_f32 v[18:19], v[96:97], v[148:149] op_sel:[0,0] op_sel_hi:[1,0]
	v_pk_mul_f32 v[16:17], v[98:99], v[184:185] op_sel:[0,1] op_sel_hi:[1,1]
	v_pk_mul_f32 v[20:21], v[98:99], v[148:149] op_sel:[0,1] op_sel_hi:[1,1]
	v_pk_fma_f32 v[14:15], v[100:101], v[186:187], v[14:15] op_sel:[0,0,0] op_sel_hi:[1,0,1]
	v_pk_fma_f32 v[18:19], v[100:101], v[150:151], v[18:19] op_sel:[0,0,0] op_sel_hi:[1,0,1]
	v_pk_fma_f32 v[16:17], v[102:103], v[186:187], v[16:17] op_sel:[0,1,0] op_sel_hi:[1,1,1]
	v_pk_fma_f32 v[20:21], v[102:103], v[150:151], v[20:21] op_sel:[0,1,0] op_sel_hi:[1,1,1]
	v_pk_fma_f32 v[14:15], v[104:105], v[188:189], v[14:15] op_sel:[0,0,0] op_sel_hi:[1,0,1]
	v_pk_fma_f32 v[18:19], v[104:105], v[152:153], v[18:19] op_sel:[0,0,0] op_sel_hi:[1,0,1]
	v_pk_fma_f32 v[16:17], v[106:107], v[188:189], v[16:17] op_sel:[0,1,0] op_sel_hi:[1,1,1]
	v_pk_fma_f32 v[20:21], v[106:107], v[152:153], v[20:21] op_sel:[0,1,0] op_sel_hi:[1,1,1]
	v_pk_fma_f32 v[14:15], v[108:109], v[190:191], v[14:15] op_sel:[0,0,0] op_sel_hi:[1,0,1]
	v_pk_fma_f32 v[18:19], v[108:109], v[154:155], v[18:19] op_sel:[0,0,0] op_sel_hi:[1,0,1]
	v_pk_fma_f32 v[16:17], v[110:111], v[190:191], v[16:17] op_sel:[0,1,0] op_sel_hi:[1,1,1]
	v_pk_fma_f32 v[20:21], v[110:111], v[154:155], v[20:21] op_sel:[0,1,0] op_sel_hi:[1,1,1]
	v_pk_add_f32 v[48:49], v[14:15], v[16:17]
	v_pk_add_f32 v[50:51], v[18:19], v[20:21]
	s_waitcnt lgkmcnt(11)
; #define LAS __attribute__((address_space(3)))
; template <int CTRL> __device__ __forceinline__ float dpp_mov(float x) { return __int_as_float(__builtin_amdgcn_update_dpp(0, __float_as_int(x), CTRL, 0xF, 0xF, true)); }
; __device__ __forceinline__ float red8(float x) { x += dpp_mov<0xB1>(x); x += dpp_mov<0x4E>(x); x += dpp_mov<0x141>(x); return x; }
; __device__ __forceinline__ void scan_phase(const KP& P, LAS unsigned char* lds, const int tid, const int bx, const int G) {
;     ...
;             for (int s = 0; s < 32; ++s) {
;                 const LAS float* p = cb + s * 384;
;                 const f32x4 w0 = *(const LAS f32x4*)(p), w1 = *(const LAS f32x4*)(p + 4);
;                 const f32x4 k0 = *(const LAS f32x4*)(p + 64), k1 = *(const LAS f32x4*)(p + 68);
;                 const f32x4 a0 = *(const LAS f32x4*)(p + 128), a1 = *(const LAS f32x4*)(p + 132);
;                 const f32x4 b0 = *(const LAS f32x4*)(p + 192), b1 = *(const LAS f32x4*)(p + 196);
;                 const f32x4 r0 = *(const LAS f32x4*)(p + 256), r1 = *(const LAS f32x4*)(p + 260);
;                 const float vv = buf[(c & 1) * 12288 + s * 384 + 320 + v];
;                 f32x2 sa2 = S[0] * (f32x2){a0.x, a0.y};
;                 sa2 += S[1] * (f32x2){a0.z, a0.w}; sa2 += S[2] * (f32x2){a1.x, a1.y}; sa2 += S[3] * (f32x2){a1.z, a1.w};
;                 const float sa = red8(sa2.x + sa2.y);
;                 const f32x2 sav = {sa, sa}, vv2 = {vv, vv};
;                 S[0] = S[0] * (f32x2){w0.x, w0.y} + sav * (f32x2){b0.x, b0.y} + vv2 * (f32x2){k0.x, k0.y};
;                 S[1] = S[1] * (f32x2){w0.z, w0.w} + sav * (f32x2){b0.z, b0.w} + vv2 * (f32x2){k0.z, k0.w};
;                 S[2] = S[2] * (f32x2){w1.x, w1.y} + sav * (f32x2){b1.x, b1.y} + vv2 * (f32x2){k1.x, k1.y};
;                 S[3] = S[3] * (f32x2){w1.z, w1.w} + sav * (f32x2){b1.z, b1.w} + vv2 * (f32x2){k1.z, k1.w};
;                 f32x2 y2 = S[0] * (f32x2){r0.x, r0.y};
;                 y2 += S[1] * (f32x2){r0.z, r0.w}; y2 += S[2] * (f32x2){r1.x, r1.y}; y2 += S[3] * (f32x2){r1.z, r1.w};
;                 const float y = red8(y2.x + y2.y);
;                 if (kc == 0) ybuf[s * 64 + v] = y;
	ds_read_b128 v[168:171], v44 offset:30976
	ds_read_b128 v[172:175], v44 offset:30992
	ds_read_b128 v[176:179], v44 offset:31488
	ds_read_b128 v[180:183], v44 offset:31504
	ds_read_b128 v[184:187], v44 offset:31744
	ds_read_b128 v[188:191], v44 offset:31760
	ds_read_b64 v[192:193], v46 offset:30720
	ds_read_b128 v[148:151], v44 offset:32768
	ds_read_b128 v[152:155], v44 offset:32784
	v_add_f32_dpp v48, v48, v48 quad_perm:[1,0,3,2] row_mask:0xf bank_mask:0xf bound_ctrl:1
	v_add_f32_dpp v49, v49, v49 quad_perm:[1,0,3,2] row_mask:0xf bank_mask:0xf bound_ctrl:1
	v_add_f32_dpp v50, v50, v50 quad_perm:[1,0,3,2] row_mask:0xf bank_mask:0xf bound_ctrl:1
	v_add_f32_dpp v51, v51, v51 quad_perm:[1,0,3,2] row_mask:0xf bank_mask:0xf bound_ctrl:1
	v_pk_fma_f32 v[96:97], v[144:145], v[120:121], v[96:97] op_sel:[0,0,0] op_sel_hi:[1,0,1]
	v_pk_fma_f32 v[98:99], v[144:145], v[120:121], v[98:99] op_sel:[0,1,0] op_sel_hi:[1,1,1]
	v_pk_fma_f32 v[100:101], v[144:145], v[122:123], v[100:101] op_sel:[0,0,0] op_sel_hi:[1,0,1]
	v_add_f32_dpp v48, v48, v48 quad_perm:[2,3,0,1] row_mask:0xf bank_mask:0xf bound_ctrl:1
	v_add_f32_dpp v49, v49, v49 quad_perm:[2,3,0,1] row_mask:0xf bank_mask:0xf bound_ctrl:1
	v_add_f32_dpp v50, v50, v50 quad_perm:[2,3,0,1] row_mask:0xf bank_mask:0xf bound_ctrl:1
	v_add_f32_dpp v51, v51, v51 quad_perm:[2,3,0,1] row_mask:0xf bank_mask:0xf bound_ctrl:1
	v_pk_fma_f32 v[102:103], v[144:145], v[122:123], v[102:103] op_sel:[0,1,0] op_sel_hi:[1,1,1]
	v_pk_fma_f32 v[104:105], v[144:145], v[124:125], v[104:105] op_sel:[0,0,0] op_sel_hi:[1,0,1]
	v_pk_fma_f32 v[106:107], v[144:145], v[124:125], v[106:107] op_sel:[0,1,0] op_sel_hi:[1,1,1]
	v_add_f32_dpp v48, v48, v48 row_half_mirror row_mask:0xf bank_mask:0xf bound_ctrl:1
	v_add_f32_dpp v49, v49, v49 row_half_mirror row_mask:0xf bank_mask:0xf bound_ctrl:1
	v_add_f32_dpp v50, v50, v50 row_half_mirror row_mask:0xf bank_mask:0xf bound_ctrl:1
	v_add_f32_dpp v51, v51, v51 row_half_mirror row_mask:0xf bank_mask:0xf bound_ctrl:1
	v_pk_fma_f32 v[108:109], v[144:145], v[126:127], v[108:109] op_sel:[0,0,0] op_sel_hi:[1,0,1]
	s_mov_b64 exec, s[10:11]
	ds_write_b64 v45, v[48:49] offset:4352
	s_mov_b64 exec, s[0:1]
	v_pk_fma_f32 v[110:111], v[144:145], v[126:127], v[110:111] op_sel:[0,1,0] op_sel_hi:[1,1,1]
	s_nop 0
	v_pk_fma_f32 v[96:97], v[50:51], v[128:129], v[96:97] op_sel:[0,0,0] op_sel_hi:[1,0,1]
	v_pk_fma_f32 v[98:99], v[50:51], v[128:129], v[98:99] op_sel:[0,1,0] op_sel_hi:[1,1,1]
	v_pk_fma_f32 v[100:101], v[50:51], v[130:131], v[100:101] op_sel:[0,0,0] op_sel_hi:[1,0,1]
	v_pk_fma_f32 v[102:103], v[50:51], v[130:131], v[102:103] op_sel:[0,1,0] op_sel_hi:[1,1,1]
	v_pk_fma_f32 v[104:105], v[50:51], v[132:133], v[104:105] op_sel:[0,0,0] op_sel_hi:[1,0,1]
	v_pk_fma_f32 v[106:107], v[50:51], v[132:133], v[106:107] op_sel:[0,1,0] op_sel_hi:[1,1,1]
	v_pk_fma_f32 v[108:109], v[50:51], v[134:135], v[108:109] op_sel:[0,0,0] op_sel_hi:[1,0,1]
	v_pk_fma_f32 v[110:111], v[50:51], v[134:135], v[110:111] op_sel:[0,1,0] op_sel_hi:[1,1,1]
	v_pk_mul_f32 v[14:15], v[96:97], v[136:137] op_sel:[0,0] op_sel_hi:[1,0]
	v_pk_mul_f32 v[18:19], v[96:97], v[156:157] op_sel:[0,0] op_sel_hi:[1,0]
	v_pk_mul_f32 v[16:17], v[98:99], v[136:137] op_sel:[0,1] op_sel_hi:[1,1]
	v_pk_mul_f32 v[20:21], v[98:99], v[156:157] op_sel:[0,1] op_sel_hi:[1,1]
	v_pk_fma_f32 v[14:15], v[100:101], v[138:139], v[14:15] op_sel:[0,0,0] op_sel_hi:[1,0,1]
	v_pk_fma_f32 v[18:19], v[100:101], v[158:159], v[18:19] op_sel:[0,0,0] op_sel_hi:[1,0,1]
	v_pk_fma_f32 v[16:17], v[102:103], v[138:139], v[16:17] op_sel:[0,1,0] op_sel_hi:[1,1,1]
	v_pk_fma_f32 v[20:21], v[102:103], v[158:159], v[20:21] op_sel:[0,1,0] op_sel_hi:[1,1,1]
	v_pk_fma_f32 v[14:15], v[104:105], v[140:141], v[14:15] op_sel:[0,0,0] op_sel_hi:[1,0,1]
	v_pk_fma_f32 v[18:19], v[104:105], v[160:161], v[18:19] op_sel:[0,0,0] op_sel_hi:[1,0,1]
	v_pk_fma_f32 v[16:17], v[106:107], v[140:141], v[16:17] op_sel:[0,1,0] op_sel_hi:[1,1,1]
	v_pk_fma_f32 v[20:21], v[106:107], v[160:161], v[20:21] op_sel:[0,1,0] op_sel_hi:[1,1,1]
	v_pk_fma_f32 v[14:15], v[108:109], v[142:143], v[14:15] op_sel:[0,0,0] op_sel_hi:[1,0,1]
	v_pk_fma_f32 v[18:19], v[108:109], v[162:163], v[18:19] op_sel:[0,0,0] op_sel_hi:[1,0,1]
	v_pk_fma_f32 v[16:17], v[110:111], v[142:143], v[16:17] op_sel:[0,1,0] op_sel_hi:[1,1,1]
	v_pk_fma_f32 v[20:21], v[110:111], v[162:163], v[20:21] op_sel:[0,1,0] op_sel_hi:[1,1,1]
	v_pk_add_f32 v[48:49], v[14:15], v[16:17]
	v_pk_add_f32 v[50:51], v[18:19], v[20:21]
	s_waitcnt lgkmcnt(11)
; #define LAS __attribute__((address_space(3)))
; template <int CTRL> __device__ __forceinline__ float dpp_mov(float x) { return __int_as_float(__builtin_amdgcn_update_dpp(0, __float_as_int(x), CTRL, 0xF, 0xF, true)); }
; __device__ __forceinline__ float red8(float x) { x += dpp_mov<0xB1>(x); x += dpp_mov<0x4E>(x); x += dpp_mov<0x141>(x); return x; }
; __device__ __forceinline__ void scan_phase(const KP& P, LAS unsigned char* lds, const int tid, const int bx, const int G) {
;     ...
;             for (int s = 0; s < 32; ++s) {
;                 const LAS float* p = cb + s * 384;
;                 const f32x4 w0 = *(const LAS f32x4*)(p), w1 = *(const LAS f32x4*)(p + 4);
;                 const f32x4 k0 = *(const LAS f32x4*)(p + 64), k1 = *(const LAS f32x4*)(p + 68);
;                 const f32x4 a0 = *(const LAS f32x4*)(p + 128), a1 = *(const LAS f32x4*)(p + 132);
;                 const f32x4 b0 = *(const LAS f32x4*)(p + 192), b1 = *(const LAS f32x4*)(p + 196);
;                 const f32x4 r0 = *(const LAS f32x4*)(p + 256), r1 = *(const LAS f32x4*)(p + 260);
;                 const float vv = buf[(c & 1) * 12288 + s * 384 + 320 + v];
;                 f32x2 sa2 = S[0] * (f32x2){a0.x, a0.y};
;                 sa2 += S[1] * (f32x2){a0.z, a0.w}; sa2 += S[2] * (f32x2){a1.x, a1.y}; sa2 += S[3] * (f32x2){a1.z, a1.w};
;                 const float sa = red8(sa2.x + sa2.y);
;                 const f32x2 sav = {sa, sa}, vv2 = {vv, vv};
;                 S[0] = S[0] * (f32x2){w0.x, w0.y} + sav * (f32x2){b0.x, b0.y} + vv2 * (f32x2){k0.x, k0.y};
;                 S[1] = S[1] * (f32x2){w0.z, w0.w} + sav * (f32x2){b0.z, b0.w} + vv2 * (f32x2){k0.z, k0.w};
;                 S[2] = S[2] * (f32x2){w1.x, w1.y} + sav * (f32x2){b1.x, b1.y} + vv2 * (f32x2){k1.x, k1.y};
;                 S[3] = S[3] * (f32x2){w1.z, w1.w} + sav * (f32x2){b1.z, b1.w} + vv2 * (f32x2){k1.z, k1.w};
;                 f32x2 y2 = S[0] * (f32x2){r0.x, r0.y};
;                 y2 += S[1] * (f32x2){r0.z, r0.w}; y2 += S[2] * (f32x2){r1.x, r1.y}; y2 += S[3] * (f32x2){r1.z, r1.w};
;                 const float y = red8(y2.x + y2.y);
;                 if (kc == 0) ybuf[s * 64 + v] = y;
	ds_read_b128 v[120:123], v44 offset:32512
	ds_read_b128 v[124:127], v44 offset:32528
	ds_read_b128 v[128:131], v44 offset:33024
	ds_read_b128 v[132:135], v44 offset:33040
	ds_read_b128 v[136:139], v44 offset:33280
	ds_read_b128 v[140:143], v44 offset:33296
	ds_read_b64 v[144:145], v46 offset:32256
	ds_read_b128 v[156:159], v44 offset:34304
	ds_read_b128 v[160:163], v44 offset:34320
	v_add_f32_dpp v48, v48, v48 quad_perm:[1,0,3,2] row_mask:0xf bank_mask:0xf bound_ctrl:1
	v_add_f32_dpp v49, v49, v49 quad_perm:[1,0,3,2] row_mask:0xf bank_mask:0xf bound_ctrl:1
	v_add_f32_dpp v50, v50, v50 quad_perm:[1,0,3,2] row_mask:0xf bank_mask:0xf bound_ctrl:1
	v_add_f32_dpp v51, v51, v51 quad_perm:[1,0,3,2] row_mask:0xf bank_mask:0xf bound_ctrl:1
	v_pk_fma_f32 v[96:97], v[146:147], v[70:71], v[96:97] op_sel:[0,0,0] op_sel_hi:[1,0,1]
	v_pk_fma_f32 v[98:99], v[146:147], v[70:71], v[98:99] op_sel:[0,1,0] op_sel_hi:[1,1,1]
	v_pk_fma_f32 v[100:101], v[146:147], v[72:73], v[100:101] op_sel:[0,0,0] op_sel_hi:[1,0,1]
	v_add_f32_dpp v48, v48, v48 quad_perm:[2,3,0,1] row_mask:0xf bank_mask:0xf bound_ctrl:1
	v_add_f32_dpp v49, v49, v49 quad_perm:[2,3,0,1] row_mask:0xf bank_mask:0xf bound_ctrl:1
	v_add_f32_dpp v50, v50, v50 quad_perm:[2,3,0,1] row_mask:0xf bank_mask:0xf bound_ctrl:1
	v_add_f32_dpp v51, v51, v51 quad_perm:[2,3,0,1] row_mask:0xf bank_mask:0xf bound_ctrl:1
	v_pk_fma_f32 v[102:103], v[146:147], v[72:73], v[102:103] op_sel:[0,1,0] op_sel_hi:[1,1,1]
	v_pk_fma_f32 v[104:105], v[146:147], v[74:75], v[104:105] op_sel:[0,0,0] op_sel_hi:[1,0,1]
	v_pk_fma_f32 v[106:107], v[146:147], v[74:75], v[106:107] op_sel:[0,1,0] op_sel_hi:[1,1,1]
	v_add_f32_dpp v48, v48, v48 row_half_mirror row_mask:0xf bank_mask:0xf bound_ctrl:1
	v_add_f32_dpp v49, v49, v49 row_half_mirror row_mask:0xf bank_mask:0xf bound_ctrl:1
	v_add_f32_dpp v50, v50, v50 row_half_mirror row_mask:0xf bank_mask:0xf bound_ctrl:1
	v_add_f32_dpp v51, v51, v51 row_half_mirror row_mask:0xf bank_mask:0xf bound_ctrl:1
	v_pk_fma_f32 v[108:109], v[146:147], v[76:77], v[108:109] op_sel:[0,0,0] op_sel_hi:[1,0,1]
	s_mov_b64 exec, s[10:11]
	ds_write_b64 v45, v[48:49] offset:4608
	s_mov_b64 exec, s[0:1]
	v_pk_fma_f32 v[110:111], v[146:147], v[76:77], v[110:111] op_sel:[0,1,0] op_sel_hi:[1,1,1]
	s_nop 0
	v_pk_fma_f32 v[96:97], v[50:51], v[78:79], v[96:97] op_sel:[0,0,0] op_sel_hi:[1,0,1]
	v_pk_fma_f32 v[98:99], v[50:51], v[78:79], v[98:99] op_sel:[0,1,0] op_sel_hi:[1,1,1]
	v_pk_fma_f32 v[100:101], v[50:51], v[80:81], v[100:101] op_sel:[0,0,0] op_sel_hi:[1,0,1]
	v_pk_fma_f32 v[102:103], v[50:51], v[80:81], v[102:103] op_sel:[0,1,0] op_sel_hi:[1,1,1]
	v_pk_fma_f32 v[104:105], v[50:51], v[82:83], v[104:105] op_sel:[0,0,0] op_sel_hi:[1,0,1]
	v_pk_fma_f32 v[106:107], v[50:51], v[82:83], v[106:107] op_sel:[0,1,0] op_sel_hi:[1,1,1]
	v_pk_fma_f32 v[108:109], v[50:51], v[84:85], v[108:109] op_sel:[0,0,0] op_sel_hi:[1,0,1]
	v_pk_fma_f32 v[110:111], v[50:51], v[84:85], v[110:111] op_sel:[0,1,0] op_sel_hi:[1,1,1]
	v_pk_mul_f32 v[14:15], v[96:97], v[86:87] op_sel:[0,0] op_sel_hi:[1,0]
	v_pk_mul_f32 v[18:19], v[96:97], v[62:63] op_sel:[0,0] op_sel_hi:[1,0]
	v_pk_mul_f32 v[16:17], v[98:99], v[86:87] op_sel:[0,1] op_sel_hi:[1,1]
	v_pk_mul_f32 v[20:21], v[98:99], v[62:63] op_sel:[0,1] op_sel_hi:[1,1]
	v_pk_fma_f32 v[14:15], v[100:101], v[88:89], v[14:15] op_sel:[0,0,0] op_sel_hi:[1,0,1]
	v_pk_fma_f32 v[18:19], v[100:101], v[64:65], v[18:19] op_sel:[0,0,0] op_sel_hi:[1,0,1]
	v_pk_fma_f32 v[16:17], v[102:103], v[88:89], v[16:17] op_sel:[0,1,0] op_sel_hi:[1,1,1]
	v_pk_fma_f32 v[20:21], v[102:103], v[64:65], v[20:21] op_sel:[0,1,0] op_sel_hi:[1,1,1]
	v_pk_fma_f32 v[14:15], v[104:105], v[90:91], v[14:15] op_sel:[0,0,0] op_sel_hi:[1,0,1]
	v_pk_fma_f32 v[18:19], v[104:105], v[66:67], v[18:19] op_sel:[0,0,0] op_sel_hi:[1,0,1]
	v_pk_fma_f32 v[16:17], v[106:107], v[90:91], v[16:17] op_sel:[0,1,0] op_sel_hi:[1,1,1]
	v_pk_fma_f32 v[20:21], v[106:107], v[66:67], v[20:21] op_sel:[0,1,0] op_sel_hi:[1,1,1]
	v_pk_fma_f32 v[14:15], v[108:109], v[92:93], v[14:15] op_sel:[0,0,0] op_sel_hi:[1,0,1]
	v_pk_fma_f32 v[18:19], v[108:109], v[68:69], v[18:19] op_sel:[0,0,0] op_sel_hi:[1,0,1]
	v_pk_fma_f32 v[16:17], v[110:111], v[92:93], v[16:17] op_sel:[0,1,0] op_sel_hi:[1,1,1]
	v_pk_fma_f32 v[20:21], v[110:111], v[68:69], v[20:21] op_sel:[0,1,0] op_sel_hi:[1,1,1]
	v_pk_add_f32 v[48:49], v[14:15], v[16:17]
	v_pk_add_f32 v[50:51], v[18:19], v[20:21]
	s_waitcnt lgkmcnt(11)
; #define LAS __attribute__((address_space(3)))
; template <int CTRL> __device__ __forceinline__ float dpp_mov(float x) { return __int_as_float(__builtin_amdgcn_update_dpp(0, __float_as_int(x), CTRL, 0xF, 0xF, true)); }
; __device__ __forceinline__ float red8(float x) { x += dpp_mov<0xB1>(x); x += dpp_mov<0x4E>(x); x += dpp_mov<0x141>(x); return x; }
; __device__ __forceinline__ void scan_phase(const KP& P, LAS unsigned char* lds, const int tid, const int bx, const int G) {
;     ...
;             for (int s = 0; s < 32; ++s) {
;                 const LAS float* p = cb + s * 384;
;                 const f32x4 w0 = *(const LAS f32x4*)(p), w1 = *(const LAS f32x4*)(p + 4);
;                 const f32x4 k0 = *(const LAS f32x4*)(p + 64), k1 = *(const LAS f32x4*)(p + 68);
;                 const f32x4 a0 = *(const LAS f32x4*)(p + 128), a1 = *(const LAS f32x4*)(p + 132);
;                 const f32x4 b0 = *(const LAS f32x4*)(p + 192), b1 = *(const LAS f32x4*)(p + 196);
;                 const f32x4 r0 = *(const LAS f32x4*)(p + 256), r1 = *(const LAS f32x4*)(p + 260);
;                 const float vv = buf[(c & 1) * 12288 + s * 384 + 320 + v];
;                 f32x2 sa2 = S[0] * (f32x2){a0.x, a0.y};
;                 sa2 += S[1] * (f32x2){a0.z, a0.w}; sa2 += S[2] * (f32x2){a1.x, a1.y}; sa2 += S[3] * (f32x2){a1.z, a1.w};
;                 const float sa = red8(sa2.x + sa2.y);
;                 const f32x2 sav = {sa, sa}, vv2 = {vv, vv};
;                 S[0] = S[0] * (f32x2){w0.x, w0.y} + sav * (f32x2){b0.x, b0.y} + vv2 * (f32x2){k0.x, k0.y};
;                 S[1] = S[1] * (f32x2){w0.z, w0.w} + sav * (f32x2){b0.z, b0.w} + vv2 * (f32x2){k0.z, k0.w};
;                 S[2] = S[2] * (f32x2){w1.x, w1.y} + sav * (f32x2){b1.x, b1.y} + vv2 * (f32x2){k1.x, k1.y};
;                 S[3] = S[3] * (f32x2){w1.z, w1.w} + sav * (f32x2){b1.z, b1.w} + vv2 * (f32x2){k1.z, k1.w};
;                 f32x2 y2 = S[0] * (f32x2){r0.x, r0.y};
;                 y2 += S[1] * (f32x2){r0.z, r0.w}; y2 += S[2] * (f32x2){r1.x, r1.y}; y2 += S[3] * (f32x2){r1.z, r1.w};
;                 const float y = red8(y2.x + y2.y);
;                 if (kc == 0) ybuf[s * 64 + v] = y;
	ds_read_b128 v[70:73], v44 offset:34048
	ds_read_b128 v[74:77], v44 offset:34064
	ds_read_b128 v[78:81], v44 offset:34560
	ds_read_b128 v[82:85], v44 offset:34576
	ds_read_b128 v[86:89], v44 offset:34816
	ds_read_b128 v[90:93], v44 offset:34832
	ds_read_b64 v[146:147], v46 offset:33792
	ds_read_b128 v[62:65], v44 offset:35840
	ds_read_b128 v[66:69], v44 offset:35856
	v_add_f32_dpp v48, v48, v48 quad_perm:[1,0,3,2] row_mask:0xf bank_mask:0xf bound_ctrl:1
	v_add_f32_dpp v49, v49, v49 quad_perm:[1,0,3,2] row_mask:0xf bank_mask:0xf bound_ctrl:1
	v_add_f32_dpp v50, v50, v50 quad_perm:[1,0,3,2] row_mask:0xf bank_mask:0xf bound_ctrl:1
	v_add_f32_dpp v51, v51, v51 quad_perm:[1,0,3,2] row_mask:0xf bank_mask:0xf bound_ctrl:1
	v_pk_fma_f32 v[96:97], v[192:193], v[168:169], v[96:97] op_sel:[0,0,0] op_sel_hi:[1,0,1]
	v_pk_fma_f32 v[98:99], v[192:193], v[168:169], v[98:99] op_sel:[0,1,0] op_sel_hi:[1,1,1]
	v_pk_fma_f32 v[100:101], v[192:193], v[170:171], v[100:101] op_sel:[0,0,0] op_sel_hi:[1,0,1]
	v_add_f32_dpp v48, v48, v48 quad_perm:[2,3,0,1] row_mask:0xf bank_mask:0xf bound_ctrl:1
	v_add_f32_dpp v49, v49, v49 quad_perm:[2,3,0,1] row_mask:0xf bank_mask:0xf bound_ctrl:1
	v_add_f32_dpp v50, v50, v50 quad_perm:[2,3,0,1] row_mask:0xf bank_mask:0xf bound_ctrl:1
	v_add_f32_dpp v51, v51, v51 quad_perm:[2,3,0,1] row_mask:0xf bank_mask:0xf bound_ctrl:1
	v_pk_fma_f32 v[102:103], v[192:193], v[170:171], v[102:103] op_sel:[0,1,0] op_sel_hi:[1,1,1]
	v_pk_fma_f32 v[104:105], v[192:193], v[172:173], v[104:105] op_sel:[0,0,0] op_sel_hi:[1,0,1]
	v_pk_fma_f32 v[106:107], v[192:193], v[172:173], v[106:107] op_sel:[0,1,0] op_sel_hi:[1,1,1]
	v_add_f32_dpp v48, v48, v48 row_half_mirror row_mask:0xf bank_mask:0xf bound_ctrl:1
	v_add_f32_dpp v49, v49, v49 row_half_mirror row_mask:0xf bank_mask:0xf bound_ctrl:1
	v_add_f32_dpp v50, v50, v50 row_half_mirror row_mask:0xf bank_mask:0xf bound_ctrl:1
	v_add_f32_dpp v51, v51, v51 row_half_mirror row_mask:0xf bank_mask:0xf bound_ctrl:1
	v_pk_fma_f32 v[108:109], v[192:193], v[174:175], v[108:109] op_sel:[0,0,0] op_sel_hi:[1,0,1]
	s_mov_b64 exec, s[10:11]
	ds_write_b64 v45, v[48:49] offset:4864
	s_mov_b64 exec, s[0:1]
	v_pk_fma_f32 v[110:111], v[192:193], v[174:175], v[110:111] op_sel:[0,1,0] op_sel_hi:[1,1,1]
	s_nop 0
	v_pk_fma_f32 v[96:97], v[50:51], v[176:177], v[96:97] op_sel:[0,0,0] op_sel_hi:[1,0,1]
	v_pk_fma_f32 v[98:99], v[50:51], v[176:177], v[98:99] op_sel:[0,1,0] op_sel_hi:[1,1,1]
	v_pk_fma_f32 v[100:101], v[50:51], v[178:179], v[100:101] op_sel:[0,0,0] op_sel_hi:[1,0,1]
	v_pk_fma_f32 v[102:103], v[50:51], v[178:179], v[102:103] op_sel:[0,1,0] op_sel_hi:[1,1,1]
	v_pk_fma_f32 v[104:105], v[50:51], v[180:181], v[104:105] op_sel:[0,0,0] op_sel_hi:[1,0,1]
	v_pk_fma_f32 v[106:107], v[50:51], v[180:181], v[106:107] op_sel:[0,1,0] op_sel_hi:[1,1,1]
	v_pk_fma_f32 v[108:109], v[50:51], v[182:183], v[108:109] op_sel:[0,0,0] op_sel_hi:[1,0,1]
	v_pk_fma_f32 v[110:111], v[50:51], v[182:183], v[110:111] op_sel:[0,1,0] op_sel_hi:[1,1,1]
	v_pk_mul_f32 v[14:15], v[96:97], v[184:185] op_sel:[0,0] op_sel_hi:[1,0]
	v_pk_mul_f32 v[18:19], v[96:97], v[148:149] op_sel:[0,0] op_sel_hi:[1,0]
	v_pk_mul_f32 v[16:17], v[98:99], v[184:185] op_sel:[0,1] op_sel_hi:[1,1]
	v_pk_mul_f32 v[20:21], v[98:99], v[148:149] op_sel:[0,1] op_sel_hi:[1,1]
	v_pk_fma_f32 v[14:15], v[100:101], v[186:187], v[14:15] op_sel:[0,0,0] op_sel_hi:[1,0,1]
	v_pk_fma_f32 v[18:19], v[100:101], v[150:151], v[18:19] op_sel:[0,0,0] op_sel_hi:[1,0,1]
	v_pk_fma_f32 v[16:17], v[102:103], v[186:187], v[16:17] op_sel:[0,1,0] op_sel_hi:[1,1,1]
	v_pk_fma_f32 v[20:21], v[102:103], v[150:151], v[20:21] op_sel:[0,1,0] op_sel_hi:[1,1,1]
	v_pk_fma_f32 v[14:15], v[104:105], v[188:189], v[14:15] op_sel:[0,0,0] op_sel_hi:[1,0,1]
	v_pk_fma_f32 v[18:19], v[104:105], v[152:153], v[18:19] op_sel:[0,0,0] op_sel_hi:[1,0,1]
	v_pk_fma_f32 v[16:17], v[106:107], v[188:189], v[16:17] op_sel:[0,1,0] op_sel_hi:[1,1,1]
	v_pk_fma_f32 v[20:21], v[106:107], v[152:153], v[20:21] op_sel:[0,1,0] op_sel_hi:[1,1,1]
	v_pk_fma_f32 v[14:15], v[108:109], v[190:191], v[14:15] op_sel:[0,0,0] op_sel_hi:[1,0,1]
	v_pk_fma_f32 v[18:19], v[108:109], v[154:155], v[18:19] op_sel:[0,0,0] op_sel_hi:[1,0,1]
	v_pk_fma_f32 v[16:17], v[110:111], v[190:191], v[16:17] op_sel:[0,1,0] op_sel_hi:[1,1,1]
	v_pk_fma_f32 v[20:21], v[110:111], v[154:155], v[20:21] op_sel:[0,1,0] op_sel_hi:[1,1,1]
	v_pk_add_f32 v[48:49], v[14:15], v[16:17]
	v_pk_add_f32 v[50:51], v[18:19], v[20:21]
	s_waitcnt lgkmcnt(11)
; #define LAS __attribute__((address_space(3)))
; template <int CTRL> __device__ __forceinline__ float dpp_mov(float x) { return __int_as_float(__builtin_amdgcn_update_dpp(0, __float_as_int(x), CTRL, 0xF, 0xF, true)); }
; __device__ __forceinline__ float red8(float x) { x += dpp_mov<0xB1>(x); x += dpp_mov<0x4E>(x); x += dpp_mov<0x141>(x); return x; }
; __device__ __forceinline__ void scan_phase(const KP& P, LAS unsigned char* lds, const int tid, const int bx, const int G) {
;     ...
;             for (int s = 0; s < 32; ++s) {
;                 const LAS float* p = cb + s * 384;
;                 const f32x4 w0 = *(const LAS f32x4*)(p), w1 = *(const LAS f32x4*)(p + 4);
;                 const f32x4 k0 = *(const LAS f32x4*)(p + 64), k1 = *(const LAS f32x4*)(p + 68);
;                 const f32x4 a0 = *(const LAS f32x4*)(p + 128), a1 = *(const LAS f32x4*)(p + 132);
;                 const f32x4 b0 = *(const LAS f32x4*)(p + 192), b1 = *(const LAS f32x4*)(p + 196);
;                 const f32x4 r0 = *(const LAS f32x4*)(p + 256), r1 = *(const LAS f32x4*)(p + 260);
;                 const float vv = buf[(c & 1) * 12288 + s * 384 + 320 + v];
;                 f32x2 sa2 = S[0] * (f32x2){a0.x, a0.y};
;                 sa2 += S[1] * (f32x2){a0.z, a0.w}; sa2 += S[2] * (f32x2){a1.x, a1.y}; sa2 += S[3] * (f32x2){a1.z, a1.w};
;                 const float sa = red8(sa2.x + sa2.y);
;                 const f32x2 sav = {sa, sa}, vv2 = {vv, vv};
;                 S[0] = S[0] * (f32x2){w0.x, w0.y} + sav * (f32x2){b0.x, b0.y} + vv2 * (f32x2){k0.x, k0.y};
;                 S[1] = S[1] * (f32x2){w0.z, w0.w} + sav * (f32x2){b0.z, b0.w} + vv2 * (f32x2){k0.z, k0.w};
;                 S[2] = S[2] * (f32x2){w1.x, w1.y} + sav * (f32x2){b1.x, b1.y} + vv2 * (f32x2){k1.x, k1.y};
;                 S[3] = S[3] * (f32x2){w1.z, w1.w} + sav * (f32x2){b1.z, b1.w} + vv2 * (f32x2){k1.z, k1.w};
;                 f32x2 y2 = S[0] * (f32x2){r0.x, r0.y};
;                 y2 += S[1] * (f32x2){r0.z, r0.w}; y2 += S[2] * (f32x2){r1.x, r1.y}; y2 += S[3] * (f32x2){r1.z, r1.w};
;                 const float y = red8(y2.x + y2.y);
;                 if (kc == 0) ybuf[s * 64 + v] = y;
	ds_read_b128 v[168:171], v44 offset:35584
	ds_read_b128 v[172:175], v44 offset:35600
	ds_read_b128 v[176:179], v44 offset:36096
	ds_read_b128 v[180:183], v44 offset:36112
	ds_read_b128 v[184:187], v44 offset:36352
	ds_read_b128 v[188:191], v44 offset:36368
	ds_read_b64 v[192:193], v46 offset:35328
	ds_read_b128 v[148:151], v44 offset:37376
	ds_read_b128 v[152:155], v44 offset:37392
	v_add_f32_dpp v48, v48, v48 quad_perm:[1,0,3,2] row_mask:0xf bank_mask:0xf bound_ctrl:1
	v_add_f32_dpp v49, v49, v49 quad_perm:[1,0,3,2] row_mask:0xf bank_mask:0xf bound_ctrl:1
	v_add_f32_dpp v50, v50, v50 quad_perm:[1,0,3,2] row_mask:0xf bank_mask:0xf bound_ctrl:1
	v_add_f32_dpp v51, v51, v51 quad_perm:[1,0,3,2] row_mask:0xf bank_mask:0xf bound_ctrl:1
	v_pk_fma_f32 v[96:97], v[144:145], v[120:121], v[96:97] op_sel:[0,0,0] op_sel_hi:[1,0,1]
	v_pk_fma_f32 v[98:99], v[144:145], v[120:121], v[98:99] op_sel:[0,1,0] op_sel_hi:[1,1,1]
	v_pk_fma_f32 v[100:101], v[144:145], v[122:123], v[100:101] op_sel:[0,0,0] op_sel_hi:[1,0,1]
	v_add_f32_dpp v48, v48, v48 quad_perm:[2,3,0,1] row_mask:0xf bank_mask:0xf bound_ctrl:1
	v_add_f32_dpp v49, v49, v49 quad_perm:[2,3,0,1] row_mask:0xf bank_mask:0xf bound_ctrl:1
	v_add_f32_dpp v50, v50, v50 quad_perm:[2,3,0,1] row_mask:0xf bank_mask:0xf bound_ctrl:1
	v_add_f32_dpp v51, v51, v51 quad_perm:[2,3,0,1] row_mask:0xf bank_mask:0xf bound_ctrl:1
	v_pk_fma_f32 v[102:103], v[144:145], v[122:123], v[102:103] op_sel:[0,1,0] op_sel_hi:[1,1,1]
	v_pk_fma_f32 v[104:105], v[144:145], v[124:125], v[104:105] op_sel:[0,0,0] op_sel_hi:[1,0,1]
	v_pk_fma_f32 v[106:107], v[144:145], v[124:125], v[106:107] op_sel:[0,1,0] op_sel_hi:[1,1,1]
	v_add_f32_dpp v48, v48, v48 row_half_mirror row_mask:0xf bank_mask:0xf bound_ctrl:1
	v_add_f32_dpp v49, v49, v49 row_half_mirror row_mask:0xf bank_mask:0xf bound_ctrl:1
	v_add_f32_dpp v50, v50, v50 row_half_mirror row_mask:0xf bank_mask:0xf bound_ctrl:1
	v_add_f32_dpp v51, v51, v51 row_half_mirror row_mask:0xf bank_mask:0xf bound_ctrl:1
	v_pk_fma_f32 v[108:109], v[144:145], v[126:127], v[108:109] op_sel:[0,0,0] op_sel_hi:[1,0,1]
	s_mov_b64 exec, s[10:11]
	ds_write_b64 v45, v[48:49] offset:5120
	s_mov_b64 exec, s[0:1]
	v_pk_fma_f32 v[110:111], v[144:145], v[126:127], v[110:111] op_sel:[0,1,0] op_sel_hi:[1,1,1]
	s_nop 0
	v_pk_fma_f32 v[96:97], v[50:51], v[128:129], v[96:97] op_sel:[0,0,0] op_sel_hi:[1,0,1]
	v_pk_fma_f32 v[98:99], v[50:51], v[128:129], v[98:99] op_sel:[0,1,0] op_sel_hi:[1,1,1]
	v_pk_fma_f32 v[100:101], v[50:51], v[130:131], v[100:101] op_sel:[0,0,0] op_sel_hi:[1,0,1]
	v_pk_fma_f32 v[102:103], v[50:51], v[130:131], v[102:103] op_sel:[0,1,0] op_sel_hi:[1,1,1]
	v_pk_fma_f32 v[104:105], v[50:51], v[132:133], v[104:105] op_sel:[0,0,0] op_sel_hi:[1,0,1]
	v_pk_fma_f32 v[106:107], v[50:51], v[132:133], v[106:107] op_sel:[0,1,0] op_sel_hi:[1,1,1]
	v_pk_fma_f32 v[108:109], v[50:51], v[134:135], v[108:109] op_sel:[0,0,0] op_sel_hi:[1,0,1]
	v_pk_fma_f32 v[110:111], v[50:51], v[134:135], v[110:111] op_sel:[0,1,0] op_sel_hi:[1,1,1]
	v_pk_mul_f32 v[14:15], v[96:97], v[136:137] op_sel:[0,0] op_sel_hi:[1,0]
	v_pk_mul_f32 v[18:19], v[96:97], v[156:157] op_sel:[0,0] op_sel_hi:[1,0]
	v_pk_mul_f32 v[16:17], v[98:99], v[136:137] op_sel:[0,1] op_sel_hi:[1,1]
	v_pk_mul_f32 v[20:21], v[98:99], v[156:157] op_sel:[0,1] op_sel_hi:[1,1]
	v_pk_fma_f32 v[14:15], v[100:101], v[138:139], v[14:15] op_sel:[0,0,0] op_sel_hi:[1,0,1]
	v_pk_fma_f32 v[18:19], v[100:101], v[158:159], v[18:19] op_sel:[0,0,0] op_sel_hi:[1,0,1]
	v_pk_fma_f32 v[16:17], v[102:103], v[138:139], v[16:17] op_sel:[0,1,0] op_sel_hi:[1,1,1]
	v_pk_fma_f32 v[20:21], v[102:103], v[158:159], v[20:21] op_sel:[0,1,0] op_sel_hi:[1,1,1]
	v_pk_fma_f32 v[14:15], v[104:105], v[140:141], v[14:15] op_sel:[0,0,0] op_sel_hi:[1,0,1]
	v_pk_fma_f32 v[18:19], v[104:105], v[160:161], v[18:19] op_sel:[0,0,0] op_sel_hi:[1,0,1]
	v_pk_fma_f32 v[16:17], v[106:107], v[140:141], v[16:17] op_sel:[0,1,0] op_sel_hi:[1,1,1]
	v_pk_fma_f32 v[20:21], v[106:107], v[160:161], v[20:21] op_sel:[0,1,0] op_sel_hi:[1,1,1]
	v_pk_fma_f32 v[14:15], v[108:109], v[142:143], v[14:15] op_sel:[0,0,0] op_sel_hi:[1,0,1]
	v_pk_fma_f32 v[18:19], v[108:109], v[162:163], v[18:19] op_sel:[0,0,0] op_sel_hi:[1,0,1]
	v_pk_fma_f32 v[16:17], v[110:111], v[142:143], v[16:17] op_sel:[0,1,0] op_sel_hi:[1,1,1]
	v_pk_fma_f32 v[20:21], v[110:111], v[162:163], v[20:21] op_sel:[0,1,0] op_sel_hi:[1,1,1]
	v_pk_add_f32 v[48:49], v[14:15], v[16:17]
	v_pk_add_f32 v[50:51], v[18:19], v[20:21]
	s_waitcnt lgkmcnt(11)
; #define LAS __attribute__((address_space(3)))
; template <int CTRL> __device__ __forceinline__ float dpp_mov(float x) { return __int_as_float(__builtin_amdgcn_update_dpp(0, __float_as_int(x), CTRL, 0xF, 0xF, true)); }
; __device__ __forceinline__ float red8(float x) { x += dpp_mov<0xB1>(x); x += dpp_mov<0x4E>(x); x += dpp_mov<0x141>(x); return x; }
; __device__ __forceinline__ void scan_phase(const KP& P, LAS unsigned char* lds, const int tid, const int bx, const int G) {
;     ...
;             for (int s = 0; s < 32; ++s) {
;                 const LAS float* p = cb + s * 384;
;                 const f32x4 w0 = *(const LAS f32x4*)(p), w1 = *(const LAS f32x4*)(p + 4);
;                 const f32x4 k0 = *(const LAS f32x4*)(p + 64), k1 = *(const LAS f32x4*)(p + 68);
;                 const f32x4 a0 = *(const LAS f32x4*)(p + 128), a1 = *(const LAS f32x4*)(p + 132);
;                 const f32x4 b0 = *(const LAS f32x4*)(p + 192), b1 = *(const LAS f32x4*)(p + 196);
;                 const f32x4 r0 = *(const LAS f32x4*)(p + 256), r1 = *(const LAS f32x4*)(p + 260);
;                 const float vv = buf[(c & 1) * 12288 + s * 384 + 320 + v];
;                 f32x2 sa2 = S[0] * (f32x2){a0.x, a0.y};
;                 sa2 += S[1] * (f32x2){a0.z, a0.w}; sa2 += S[2] * (f32x2){a1.x, a1.y}; sa2 += S[3] * (f32x2){a1.z, a1.w};
;                 const float sa = red8(sa2.x + sa2.y);
;                 const f32x2 sav = {sa, sa}, vv2 = {vv, vv};
;                 S[0] = S[0] * (f32x2){w0.x, w0.y} + sav * (f32x2){b0.x, b0.y} + vv2 * (f32x2){k0.x, k0.y};
;                 S[1] = S[1] * (f32x2){w0.z, w0.w} + sav * (f32x2){b0.z, b0.w} + vv2 * (f32x2){k0.z, k0.w};
;                 S[2] = S[2] * (f32x2){w1.x, w1.y} + sav * (f32x2){b1.x, b1.y} + vv2 * (f32x2){k1.x, k1.y};
;                 S[3] = S[3] * (f32x2){w1.z, w1.w} + sav * (f32x2){b1.z, b1.w} + vv2 * (f32x2){k1.z, k1.w};
;                 f32x2 y2 = S[0] * (f32x2){r0.x, r0.y};
;                 y2 += S[1] * (f32x2){r0.z, r0.w}; y2 += S[2] * (f32x2){r1.x, r1.y}; y2 += S[3] * (f32x2){r1.z, r1.w};
;                 const float y = red8(y2.x + y2.y);
;                 if (kc == 0) ybuf[s * 64 + v] = y;
	ds_read_b128 v[120:123], v44 offset:37120
	ds_read_b128 v[124:127], v44 offset:37136
	ds_read_b128 v[128:131], v44 offset:37632
	ds_read_b128 v[132:135], v44 offset:37648
	ds_read_b128 v[136:139], v44 offset:37888
	ds_read_b128 v[140:143], v44 offset:37904
	ds_read_b64 v[144:145], v46 offset:36864
	ds_read_b128 v[156:159], v44 offset:38912
	ds_read_b128 v[160:163], v44 offset:38928
	v_add_f32_dpp v48, v48, v48 quad_perm:[1,0,3,2] row_mask:0xf bank_mask:0xf bound_ctrl:1
	v_add_f32_dpp v49, v49, v49 quad_perm:[1,0,3,2] row_mask:0xf bank_mask:0xf bound_ctrl:1
	v_add_f32_dpp v50, v50, v50 quad_perm:[1,0,3,2] row_mask:0xf bank_mask:0xf bound_ctrl:1
	v_add_f32_dpp v51, v51, v51 quad_perm:[1,0,3,2] row_mask:0xf bank_mask:0xf bound_ctrl:1
	v_pk_fma_f32 v[96:97], v[146:147], v[70:71], v[96:97] op_sel:[0,0,0] op_sel_hi:[1,0,1]
	v_pk_fma_f32 v[98:99], v[146:147], v[70:71], v[98:99] op_sel:[0,1,0] op_sel_hi:[1,1,1]
	v_pk_fma_f32 v[100:101], v[146:147], v[72:73], v[100:101] op_sel:[0,0,0] op_sel_hi:[1,0,1]
	v_add_f32_dpp v48, v48, v48 quad_perm:[2,3,0,1] row_mask:0xf bank_mask:0xf bound_ctrl:1
	v_add_f32_dpp v49, v49, v49 quad_perm:[2,3,0,1] row_mask:0xf bank_mask:0xf bound_ctrl:1
	v_add_f32_dpp v50, v50, v50 quad_perm:[2,3,0,1] row_mask:0xf bank_mask:0xf bound_ctrl:1
	v_add_f32_dpp v51, v51, v51 quad_perm:[2,3,0,1] row_mask:0xf bank_mask:0xf bound_ctrl:1
	v_pk_fma_f32 v[102:103], v[146:147], v[72:73], v[102:103] op_sel:[0,1,0] op_sel_hi:[1,1,1]
	v_pk_fma_f32 v[104:105], v[146:147], v[74:75], v[104:105] op_sel:[0,0,0] op_sel_hi:[1,0,1]
	v_pk_fma_f32 v[106:107], v[146:147], v[74:75], v[106:107] op_sel:[0,1,0] op_sel_hi:[1,1,1]
	v_add_f32_dpp v48, v48, v48 row_half_mirror row_mask:0xf bank_mask:0xf bound_ctrl:1
	v_add_f32_dpp v49, v49, v49 row_half_mirror row_mask:0xf bank_mask:0xf bound_ctrl:1
	v_add_f32_dpp v50, v50, v50 row_half_mirror row_mask:0xf bank_mask:0xf bound_ctrl:1
	v_add_f32_dpp v51, v51, v51 row_half_mirror row_mask:0xf bank_mask:0xf bound_ctrl:1
	v_pk_fma_f32 v[108:109], v[146:147], v[76:77], v[108:109] op_sel:[0,0,0] op_sel_hi:[1,0,1]
	s_mov_b64 exec, s[10:11]
	ds_write_b64 v45, v[48:49] offset:5376
	s_mov_b64 exec, s[0:1]
	v_pk_fma_f32 v[110:111], v[146:147], v[76:77], v[110:111] op_sel:[0,1,0] op_sel_hi:[1,1,1]
	s_nop 0
	v_pk_fma_f32 v[96:97], v[50:51], v[78:79], v[96:97] op_sel:[0,0,0] op_sel_hi:[1,0,1]
	v_pk_fma_f32 v[98:99], v[50:51], v[78:79], v[98:99] op_sel:[0,1,0] op_sel_hi:[1,1,1]
	v_pk_fma_f32 v[100:101], v[50:51], v[80:81], v[100:101] op_sel:[0,0,0] op_sel_hi:[1,0,1]
	v_pk_fma_f32 v[102:103], v[50:51], v[80:81], v[102:103] op_sel:[0,1,0] op_sel_hi:[1,1,1]
	v_pk_fma_f32 v[104:105], v[50:51], v[82:83], v[104:105] op_sel:[0,0,0] op_sel_hi:[1,0,1]
	v_pk_fma_f32 v[106:107], v[50:51], v[82:83], v[106:107] op_sel:[0,1,0] op_sel_hi:[1,1,1]
	v_pk_fma_f32 v[108:109], v[50:51], v[84:85], v[108:109] op_sel:[0,0,0] op_sel_hi:[1,0,1]
	v_pk_fma_f32 v[110:111], v[50:51], v[84:85], v[110:111] op_sel:[0,1,0] op_sel_hi:[1,1,1]
	v_pk_mul_f32 v[14:15], v[96:97], v[86:87] op_sel:[0,0] op_sel_hi:[1,0]
	v_pk_mul_f32 v[18:19], v[96:97], v[62:63] op_sel:[0,0] op_sel_hi:[1,0]
	v_pk_mul_f32 v[16:17], v[98:99], v[86:87] op_sel:[0,1] op_sel_hi:[1,1]
	v_pk_mul_f32 v[20:21], v[98:99], v[62:63] op_sel:[0,1] op_sel_hi:[1,1]
	v_pk_fma_f32 v[14:15], v[100:101], v[88:89], v[14:15] op_sel:[0,0,0] op_sel_hi:[1,0,1]
	v_pk_fma_f32 v[18:19], v[100:101], v[64:65], v[18:19] op_sel:[0,0,0] op_sel_hi:[1,0,1]
	v_pk_fma_f32 v[16:17], v[102:103], v[88:89], v[16:17] op_sel:[0,1,0] op_sel_hi:[1,1,1]
	v_pk_fma_f32 v[20:21], v[102:103], v[64:65], v[20:21] op_sel:[0,1,0] op_sel_hi:[1,1,1]
	v_pk_fma_f32 v[14:15], v[104:105], v[90:91], v[14:15] op_sel:[0,0,0] op_sel_hi:[1,0,1]
	v_pk_fma_f32 v[18:19], v[104:105], v[66:67], v[18:19] op_sel:[0,0,0] op_sel_hi:[1,0,1]
	v_pk_fma_f32 v[16:17], v[106:107], v[90:91], v[16:17] op_sel:[0,1,0] op_sel_hi:[1,1,1]
	v_pk_fma_f32 v[20:21], v[106:107], v[66:67], v[20:21] op_sel:[0,1,0] op_sel_hi:[1,1,1]
	v_pk_fma_f32 v[14:15], v[108:109], v[92:93], v[14:15] op_sel:[0,0,0] op_sel_hi:[1,0,1]
	v_pk_fma_f32 v[18:19], v[108:109], v[68:69], v[18:19] op_sel:[0,0,0] op_sel_hi:[1,0,1]
	v_pk_fma_f32 v[16:17], v[110:111], v[92:93], v[16:17] op_sel:[0,1,0] op_sel_hi:[1,1,1]
	v_pk_fma_f32 v[20:21], v[110:111], v[68:69], v[20:21] op_sel:[0,1,0] op_sel_hi:[1,1,1]
	v_pk_add_f32 v[48:49], v[14:15], v[16:17]
	v_pk_add_f32 v[50:51], v[18:19], v[20:21]
	s_waitcnt lgkmcnt(11)
; #define LAS __attribute__((address_space(3)))
; template <int CTRL> __device__ __forceinline__ float dpp_mov(float x) { return __int_as_float(__builtin_amdgcn_update_dpp(0, __float_as_int(x), CTRL, 0xF, 0xF, true)); }
; __device__ __forceinline__ float red8(float x) { x += dpp_mov<0xB1>(x); x += dpp_mov<0x4E>(x); x += dpp_mov<0x141>(x); return x; }
; __device__ __forceinline__ void scan_phase(const KP& P, LAS unsigned char* lds, const int tid, const int bx, const int G) {
;     ...
;             for (int s = 0; s < 32; ++s) {
;                 const LAS float* p = cb + s * 384;
;                 const f32x4 w0 = *(const LAS f32x4*)(p), w1 = *(const LAS f32x4*)(p + 4);
;                 const f32x4 k0 = *(const LAS f32x4*)(p + 64), k1 = *(const LAS f32x4*)(p + 68);
;                 const f32x4 a0 = *(const LAS f32x4*)(p + 128), a1 = *(const LAS f32x4*)(p + 132);
;                 const f32x4 b0 = *(const LAS f32x4*)(p + 192), b1 = *(const LAS f32x4*)(p + 196);
;                 const f32x4 r0 = *(const LAS f32x4*)(p + 256), r1 = *(const LAS f32x4*)(p + 260);
;                 const float vv = buf[(c & 1) * 12288 + s * 384 + 320 + v];
;                 f32x2 sa2 = S[0] * (f32x2){a0.x, a0.y};
;                 sa2 += S[1] * (f32x2){a0.z, a0.w}; sa2 += S[2] * (f32x2){a1.x, a1.y}; sa2 += S[3] * (f32x2){a1.z, a1.w};
;                 const float sa = red8(sa2.x + sa2.y);
;                 const f32x2 sav = {sa, sa}, vv2 = {vv, vv};
;                 S[0] = S[0] * (f32x2){w0.x, w0.y} + sav * (f32x2){b0.x, b0.y} + vv2 * (f32x2){k0.x, k0.y};
;                 S[1] = S[1] * (f32x2){w0.z, w0.w} + sav * (f32x2){b0.z, b0.w} + vv2 * (f32x2){k0.z, k0.w};
;                 S[2] = S[2] * (f32x2){w1.x, w1.y} + sav * (f32x2){b1.x, b1.y} + vv2 * (f32x2){k1.x, k1.y};
;                 S[3] = S[3] * (f32x2){w1.z, w1.w} + sav * (f32x2){b1.z, b1.w} + vv2 * (f32x2){k1.z, k1.w};
;                 f32x2 y2 = S[0] * (f32x2){r0.x, r0.y};
;                 y2 += S[1] * (f32x2){r0.z, r0.w}; y2 += S[2] * (f32x2){r1.x, r1.y}; y2 += S[3] * (f32x2){r1.z, r1.w};
;                 const float y = red8(y2.x + y2.y);
;                 if (kc == 0) ybuf[s * 64 + v] = y;
	ds_read_b128 v[70:73], v44 offset:38656
	ds_read_b128 v[74:77], v44 offset:38672
	ds_read_b128 v[78:81], v44 offset:39168
	ds_read_b128 v[82:85], v44 offset:39184
	ds_read_b128 v[86:89], v44 offset:39424
	ds_read_b128 v[90:93], v44 offset:39440
	ds_read_b64 v[146:147], v46 offset:38400
	ds_read_b128 v[62:65], v44 offset:40448
	ds_read_b128 v[66:69], v44 offset:40464
	v_add_f32_dpp v48, v48, v48 quad_perm:[1,0,3,2] row_mask:0xf bank_mask:0xf bound_ctrl:1
	v_add_f32_dpp v49, v49, v49 quad_perm:[1,0,3,2] row_mask:0xf bank_mask:0xf bound_ctrl:1
	v_add_f32_dpp v50, v50, v50 quad_perm:[1,0,3,2] row_mask:0xf bank_mask:0xf bound_ctrl:1
	v_add_f32_dpp v51, v51, v51 quad_perm:[1,0,3,2] row_mask:0xf bank_mask:0xf bound_ctrl:1
	v_pk_fma_f32 v[96:97], v[192:193], v[168:169], v[96:97] op_sel:[0,0,0] op_sel_hi:[1,0,1]
	v_pk_fma_f32 v[98:99], v[192:193], v[168:169], v[98:99] op_sel:[0,1,0] op_sel_hi:[1,1,1]
	v_pk_fma_f32 v[100:101], v[192:193], v[170:171], v[100:101] op_sel:[0,0,0] op_sel_hi:[1,0,1]
	v_add_f32_dpp v48, v48, v48 quad_perm:[2,3,0,1] row_mask:0xf bank_mask:0xf bound_ctrl:1
	v_add_f32_dpp v49, v49, v49 quad_perm:[2,3,0,1] row_mask:0xf bank_mask:0xf bound_ctrl:1
	v_add_f32_dpp v50, v50, v50 quad_perm:[2,3,0,1] row_mask:0xf bank_mask:0xf bound_ctrl:1
	v_add_f32_dpp v51, v51, v51 quad_perm:[2,3,0,1] row_mask:0xf bank_mask:0xf bound_ctrl:1
	v_pk_fma_f32 v[102:103], v[192:193], v[170:171], v[102:103] op_sel:[0,1,0] op_sel_hi:[1,1,1]
	v_pk_fma_f32 v[104:105], v[192:193], v[172:173], v[104:105] op_sel:[0,0,0] op_sel_hi:[1,0,1]
	v_pk_fma_f32 v[106:107], v[192:193], v[172:173], v[106:107] op_sel:[0,1,0] op_sel_hi:[1,1,1]
	v_add_f32_dpp v48, v48, v48 row_half_mirror row_mask:0xf bank_mask:0xf bound_ctrl:1
	v_add_f32_dpp v49, v49, v49 row_half_mirror row_mask:0xf bank_mask:0xf bound_ctrl:1
	v_add_f32_dpp v50, v50, v50 row_half_mirror row_mask:0xf bank_mask:0xf bound_ctrl:1
	v_add_f32_dpp v51, v51, v51 row_half_mirror row_mask:0xf bank_mask:0xf bound_ctrl:1
	v_pk_fma_f32 v[108:109], v[192:193], v[174:175], v[108:109] op_sel:[0,0,0] op_sel_hi:[1,0,1]
	s_mov_b64 exec, s[10:11]
	ds_write_b64 v45, v[48:49] offset:5632
	s_mov_b64 exec, s[0:1]
	v_pk_fma_f32 v[110:111], v[192:193], v[174:175], v[110:111] op_sel:[0,1,0] op_sel_hi:[1,1,1]
	s_nop 0
	v_pk_fma_f32 v[96:97], v[50:51], v[176:177], v[96:97] op_sel:[0,0,0] op_sel_hi:[1,0,1]
	v_pk_fma_f32 v[98:99], v[50:51], v[176:177], v[98:99] op_sel:[0,1,0] op_sel_hi:[1,1,1]
	v_pk_fma_f32 v[100:101], v[50:51], v[178:179], v[100:101] op_sel:[0,0,0] op_sel_hi:[1,0,1]
	v_pk_fma_f32 v[102:103], v[50:51], v[178:179], v[102:103] op_sel:[0,1,0] op_sel_hi:[1,1,1]
	v_pk_fma_f32 v[104:105], v[50:51], v[180:181], v[104:105] op_sel:[0,0,0] op_sel_hi:[1,0,1]
	v_pk_fma_f32 v[106:107], v[50:51], v[180:181], v[106:107] op_sel:[0,1,0] op_sel_hi:[1,1,1]
	v_pk_fma_f32 v[108:109], v[50:51], v[182:183], v[108:109] op_sel:[0,0,0] op_sel_hi:[1,0,1]
	v_pk_fma_f32 v[110:111], v[50:51], v[182:183], v[110:111] op_sel:[0,1,0] op_sel_hi:[1,1,1]
	v_pk_mul_f32 v[14:15], v[96:97], v[184:185] op_sel:[0,0] op_sel_hi:[1,0]
	v_pk_mul_f32 v[18:19], v[96:97], v[148:149] op_sel:[0,0] op_sel_hi:[1,0]
	v_pk_mul_f32 v[16:17], v[98:99], v[184:185] op_sel:[0,1] op_sel_hi:[1,1]
	v_pk_mul_f32 v[20:21], v[98:99], v[148:149] op_sel:[0,1] op_sel_hi:[1,1]
	v_pk_fma_f32 v[14:15], v[100:101], v[186:187], v[14:15] op_sel:[0,0,0] op_sel_hi:[1,0,1]
	v_pk_fma_f32 v[18:19], v[100:101], v[150:151], v[18:19] op_sel:[0,0,0] op_sel_hi:[1,0,1]
	v_pk_fma_f32 v[16:17], v[102:103], v[186:187], v[16:17] op_sel:[0,1,0] op_sel_hi:[1,1,1]
	v_pk_fma_f32 v[20:21], v[102:103], v[150:151], v[20:21] op_sel:[0,1,0] op_sel_hi:[1,1,1]
	v_pk_fma_f32 v[14:15], v[104:105], v[188:189], v[14:15] op_sel:[0,0,0] op_sel_hi:[1,0,1]
	v_pk_fma_f32 v[18:19], v[104:105], v[152:153], v[18:19] op_sel:[0,0,0] op_sel_hi:[1,0,1]
	v_pk_fma_f32 v[16:17], v[106:107], v[188:189], v[16:17] op_sel:[0,1,0] op_sel_hi:[1,1,1]
	v_pk_fma_f32 v[20:21], v[106:107], v[152:153], v[20:21] op_sel:[0,1,0] op_sel_hi:[1,1,1]
	v_pk_fma_f32 v[14:15], v[108:109], v[190:191], v[14:15] op_sel:[0,0,0] op_sel_hi:[1,0,1]
	v_pk_fma_f32 v[18:19], v[108:109], v[154:155], v[18:19] op_sel:[0,0,0] op_sel_hi:[1,0,1]
	v_pk_fma_f32 v[16:17], v[110:111], v[190:191], v[16:17] op_sel:[0,1,0] op_sel_hi:[1,1,1]
	v_pk_fma_f32 v[20:21], v[110:111], v[154:155], v[20:21] op_sel:[0,1,0] op_sel_hi:[1,1,1]
	v_pk_add_f32 v[48:49], v[14:15], v[16:17]
	v_pk_add_f32 v[50:51], v[18:19], v[20:21]
	s_waitcnt lgkmcnt(11)
; #define LAS __attribute__((address_space(3)))
; template <int CTRL> __device__ __forceinline__ float dpp_mov(float x) { return __int_as_float(__builtin_amdgcn_update_dpp(0, __float_as_int(x), CTRL, 0xF, 0xF, true)); }
; __device__ __forceinline__ float red8(float x) { x += dpp_mov<0xB1>(x); x += dpp_mov<0x4E>(x); x += dpp_mov<0x141>(x); return x; }
; __device__ __forceinline__ void scan_phase(const KP& P, LAS unsigned char* lds, const int tid, const int bx, const int G) {
;     ...
;             for (int s = 0; s < 32; ++s) {
;                 const LAS float* p = cb + s * 384;
;                 const f32x4 w0 = *(const LAS f32x4*)(p), w1 = *(const LAS f32x4*)(p + 4);
;                 const f32x4 k0 = *(const LAS f32x4*)(p + 64), k1 = *(const LAS f32x4*)(p + 68);
;                 const f32x4 a0 = *(const LAS f32x4*)(p + 128), a1 = *(const LAS f32x4*)(p + 132);
;                 const f32x4 b0 = *(const LAS f32x4*)(p + 192), b1 = *(const LAS f32x4*)(p + 196);
;                 const f32x4 r0 = *(const LAS f32x4*)(p + 256), r1 = *(const LAS f32x4*)(p + 260);
;                 const float vv = buf[(c & 1) * 12288 + s * 384 + 320 + v];
;                 f32x2 sa2 = S[0] * (f32x2){a0.x, a0.y};
;                 sa2 += S[1] * (f32x2){a0.z, a0.w}; sa2 += S[2] * (f32x2){a1.x, a1.y}; sa2 += S[3] * (f32x2){a1.z, a1.w};
;                 const float sa = red8(sa2.x + sa2.y);
;                 const f32x2 sav = {sa, sa}, vv2 = {vv, vv};
;                 S[0] = S[0] * (f32x2){w0.x, w0.y} + sav * (f32x2){b0.x, b0.y} + vv2 * (f32x2){k0.x, k0.y};
;                 S[1] = S[1] * (f32x2){w0.z, w0.w} + sav * (f32x2){b0.z, b0.w} + vv2 * (f32x2){k0.z, k0.w};
;                 S[2] = S[2] * (f32x2){w1.x, w1.y} + sav * (f32x2){b1.x, b1.y} + vv2 * (f32x2){k1.x, k1.y};
;                 S[3] = S[3] * (f32x2){w1.z, w1.w} + sav * (f32x2){b1.z, b1.w} + vv2 * (f32x2){k1.z, k1.w};
;                 f32x2 y2 = S[0] * (f32x2){r0.x, r0.y};
;                 y2 += S[1] * (f32x2){r0.z, r0.w}; y2 += S[2] * (f32x2){r1.x, r1.y}; y2 += S[3] * (f32x2){r1.z, r1.w};
;                 const float y = red8(y2.x + y2.y);
;                 if (kc == 0) ybuf[s * 64 + v] = y;
	ds_read_b128 v[168:171], v44 offset:40192
	ds_read_b128 v[172:175], v44 offset:40208
	ds_read_b128 v[176:179], v44 offset:40704
	ds_read_b128 v[180:183], v44 offset:40720
	ds_read_b128 v[184:187], v44 offset:40960
	ds_read_b128 v[188:191], v44 offset:40976
	ds_read_b64 v[192:193], v46 offset:39936
	ds_read_b128 v[148:151], v44 offset:41984
	ds_read_b128 v[152:155], v44 offset:42000
	v_add_f32_dpp v48, v48, v48 quad_perm:[1,0,3,2] row_mask:0xf bank_mask:0xf bound_ctrl:1
	v_add_f32_dpp v49, v49, v49 quad_perm:[1,0,3,2] row_mask:0xf bank_mask:0xf bound_ctrl:1
	v_add_f32_dpp v50, v50, v50 quad_perm:[1,0,3,2] row_mask:0xf bank_mask:0xf bound_ctrl:1
	v_add_f32_dpp v51, v51, v51 quad_perm:[1,0,3,2] row_mask:0xf bank_mask:0xf bound_ctrl:1
	v_pk_fma_f32 v[96:97], v[144:145], v[120:121], v[96:97] op_sel:[0,0,0] op_sel_hi:[1,0,1]
	v_pk_fma_f32 v[98:99], v[144:145], v[120:121], v[98:99] op_sel:[0,1,0] op_sel_hi:[1,1,1]
	v_pk_fma_f32 v[100:101], v[144:145], v[122:123], v[100:101] op_sel:[0,0,0] op_sel_hi:[1,0,1]
	v_add_f32_dpp v48, v48, v48 quad_perm:[2,3,0,1] row_mask:0xf bank_mask:0xf bound_ctrl:1
	v_add_f32_dpp v49, v49, v49 quad_perm:[2,3,0,1] row_mask:0xf bank_mask:0xf bound_ctrl:1
	v_add_f32_dpp v50, v50, v50 quad_perm:[2,3,0,1] row_mask:0xf bank_mask:0xf bound_ctrl:1
	v_add_f32_dpp v51, v51, v51 quad_perm:[2,3,0,1] row_mask:0xf bank_mask:0xf bound_ctrl:1
	v_pk_fma_f32 v[102:103], v[144:145], v[122:123], v[102:103] op_sel:[0,1,0] op_sel_hi:[1,1,1]
	v_pk_fma_f32 v[104:105], v[144:145], v[124:125], v[104:105] op_sel:[0,0,0] op_sel_hi:[1,0,1]
	v_pk_fma_f32 v[106:107], v[144:145], v[124:125], v[106:107] op_sel:[0,1,0] op_sel_hi:[1,1,1]
	v_add_f32_dpp v48, v48, v48 row_half_mirror row_mask:0xf bank_mask:0xf bound_ctrl:1
	v_add_f32_dpp v49, v49, v49 row_half_mirror row_mask:0xf bank_mask:0xf bound_ctrl:1
	v_add_f32_dpp v50, v50, v50 row_half_mirror row_mask:0xf bank_mask:0xf bound_ctrl:1
	v_add_f32_dpp v51, v51, v51 row_half_mirror row_mask:0xf bank_mask:0xf bound_ctrl:1
	v_pk_fma_f32 v[108:109], v[144:145], v[126:127], v[108:109] op_sel:[0,0,0] op_sel_hi:[1,0,1]
	s_mov_b64 exec, s[10:11]
	ds_write_b64 v45, v[48:49] offset:5888
	s_mov_b64 exec, s[0:1]
	v_pk_fma_f32 v[110:111], v[144:145], v[126:127], v[110:111] op_sel:[0,1,0] op_sel_hi:[1,1,1]
	s_nop 0
	v_pk_fma_f32 v[96:97], v[50:51], v[128:129], v[96:97] op_sel:[0,0,0] op_sel_hi:[1,0,1]
	v_pk_fma_f32 v[98:99], v[50:51], v[128:129], v[98:99] op_sel:[0,1,0] op_sel_hi:[1,1,1]
	v_pk_fma_f32 v[100:101], v[50:51], v[130:131], v[100:101] op_sel:[0,0,0] op_sel_hi:[1,0,1]
	v_pk_fma_f32 v[102:103], v[50:51], v[130:131], v[102:103] op_sel:[0,1,0] op_sel_hi:[1,1,1]
	v_pk_fma_f32 v[104:105], v[50:51], v[132:133], v[104:105] op_sel:[0,0,0] op_sel_hi:[1,0,1]
	v_pk_fma_f32 v[106:107], v[50:51], v[132:133], v[106:107] op_sel:[0,1,0] op_sel_hi:[1,1,1]
	v_pk_fma_f32 v[108:109], v[50:51], v[134:135], v[108:109] op_sel:[0,0,0] op_sel_hi:[1,0,1]
	v_pk_fma_f32 v[110:111], v[50:51], v[134:135], v[110:111] op_sel:[0,1,0] op_sel_hi:[1,1,1]
	v_pk_mul_f32 v[14:15], v[96:97], v[136:137] op_sel:[0,0] op_sel_hi:[1,0]
	v_pk_mul_f32 v[18:19], v[96:97], v[156:157] op_sel:[0,0] op_sel_hi:[1,0]
	v_pk_mul_f32 v[16:17], v[98:99], v[136:137] op_sel:[0,1] op_sel_hi:[1,1]
	v_pk_mul_f32 v[20:21], v[98:99], v[156:157] op_sel:[0,1] op_sel_hi:[1,1]
	v_pk_fma_f32 v[14:15], v[100:101], v[138:139], v[14:15] op_sel:[0,0,0] op_sel_hi:[1,0,1]
	v_pk_fma_f32 v[18:19], v[100:101], v[158:159], v[18:19] op_sel:[0,0,0] op_sel_hi:[1,0,1]
	v_pk_fma_f32 v[16:17], v[102:103], v[138:139], v[16:17] op_sel:[0,1,0] op_sel_hi:[1,1,1]
	v_pk_fma_f32 v[20:21], v[102:103], v[158:159], v[20:21] op_sel:[0,1,0] op_sel_hi:[1,1,1]
	v_pk_fma_f32 v[14:15], v[104:105], v[140:141], v[14:15] op_sel:[0,0,0] op_sel_hi:[1,0,1]
	v_pk_fma_f32 v[18:19], v[104:105], v[160:161], v[18:19] op_sel:[0,0,0] op_sel_hi:[1,0,1]
	v_pk_fma_f32 v[16:17], v[106:107], v[140:141], v[16:17] op_sel:[0,1,0] op_sel_hi:[1,1,1]
	v_pk_fma_f32 v[20:21], v[106:107], v[160:161], v[20:21] op_sel:[0,1,0] op_sel_hi:[1,1,1]
	v_pk_fma_f32 v[14:15], v[108:109], v[142:143], v[14:15] op_sel:[0,0,0] op_sel_hi:[1,0,1]
	v_pk_fma_f32 v[18:19], v[108:109], v[162:163], v[18:19] op_sel:[0,0,0] op_sel_hi:[1,0,1]
	v_pk_fma_f32 v[16:17], v[110:111], v[142:143], v[16:17] op_sel:[0,1,0] op_sel_hi:[1,1,1]
	v_pk_fma_f32 v[20:21], v[110:111], v[162:163], v[20:21] op_sel:[0,1,0] op_sel_hi:[1,1,1]
	v_pk_add_f32 v[48:49], v[14:15], v[16:17]
	v_pk_add_f32 v[50:51], v[18:19], v[20:21]
	s_waitcnt lgkmcnt(11)
; #define LAS __attribute__((address_space(3)))
; template <int CTRL> __device__ __forceinline__ float dpp_mov(float x) { return __int_as_float(__builtin_amdgcn_update_dpp(0, __float_as_int(x), CTRL, 0xF, 0xF, true)); }
; __device__ __forceinline__ float red8(float x) { x += dpp_mov<0xB1>(x); x += dpp_mov<0x4E>(x); x += dpp_mov<0x141>(x); return x; }
; __device__ __forceinline__ void scan_phase(const KP& P, LAS unsigned char* lds, const int tid, const int bx, const int G) {
;     ...
;             for (int s = 0; s < 32; ++s) {
;                 const LAS float* p = cb + s * 384;
;                 const f32x4 w0 = *(const LAS f32x4*)(p), w1 = *(const LAS f32x4*)(p + 4);
;                 const f32x4 k0 = *(const LAS f32x4*)(p + 64), k1 = *(const LAS f32x4*)(p + 68);
;                 const f32x4 a0 = *(const LAS f32x4*)(p + 128), a1 = *(const LAS f32x4*)(p + 132);
;                 const f32x4 b0 = *(const LAS f32x4*)(p + 192), b1 = *(const LAS f32x4*)(p + 196);
;                 const f32x4 r0 = *(const LAS f32x4*)(p + 256), r1 = *(const LAS f32x4*)(p + 260);
;                 const float vv = buf[(c & 1) * 12288 + s * 384 + 320 + v];
;                 f32x2 sa2 = S[0] * (f32x2){a0.x, a0.y};
;                 sa2 += S[1] * (f32x2){a0.z, a0.w}; sa2 += S[2] * (f32x2){a1.x, a1.y}; sa2 += S[3] * (f32x2){a1.z, a1.w};
;                 const float sa = red8(sa2.x + sa2.y);
;                 const f32x2 sav = {sa, sa}, vv2 = {vv, vv};
;                 S[0] = S[0] * (f32x2){w0.x, w0.y} + sav * (f32x2){b0.x, b0.y} + vv2 * (f32x2){k0.x, k0.y};
;                 S[1] = S[1] * (f32x2){w0.z, w0.w} + sav * (f32x2){b0.z, b0.w} + vv2 * (f32x2){k0.z, k0.w};
;                 S[2] = S[2] * (f32x2){w1.x, w1.y} + sav * (f32x2){b1.x, b1.y} + vv2 * (f32x2){k1.x, k1.y};
;                 S[3] = S[3] * (f32x2){w1.z, w1.w} + sav * (f32x2){b1.z, b1.w} + vv2 * (f32x2){k1.z, k1.w};
;                 f32x2 y2 = S[0] * (f32x2){r0.x, r0.y};
;                 y2 += S[1] * (f32x2){r0.z, r0.w}; y2 += S[2] * (f32x2){r1.x, r1.y}; y2 += S[3] * (f32x2){r1.z, r1.w};
;                 const float y = red8(y2.x + y2.y);
;                 if (kc == 0) ybuf[s * 64 + v] = y;
	ds_read_b128 v[120:123], v44 offset:41728
	ds_read_b128 v[124:127], v44 offset:41744
	ds_read_b128 v[128:131], v44 offset:42240
	ds_read_b128 v[132:135], v44 offset:42256
	ds_read_b128 v[136:139], v44 offset:42496
	ds_read_b128 v[140:143], v44 offset:42512
	ds_read_b64 v[144:145], v46 offset:41472
	ds_read_b128 v[156:159], v44 offset:43520
	ds_read_b128 v[160:163], v44 offset:43536
	v_add_f32_dpp v48, v48, v48 quad_perm:[1,0,3,2] row_mask:0xf bank_mask:0xf bound_ctrl:1
	v_add_f32_dpp v49, v49, v49 quad_perm:[1,0,3,2] row_mask:0xf bank_mask:0xf bound_ctrl:1
	v_add_f32_dpp v50, v50, v50 quad_perm:[1,0,3,2] row_mask:0xf bank_mask:0xf bound_ctrl:1
	v_add_f32_dpp v51, v51, v51 quad_perm:[1,0,3,2] row_mask:0xf bank_mask:0xf bound_ctrl:1
	v_pk_fma_f32 v[96:97], v[146:147], v[70:71], v[96:97] op_sel:[0,0,0] op_sel_hi:[1,0,1]
	v_pk_fma_f32 v[98:99], v[146:147], v[70:71], v[98:99] op_sel:[0,1,0] op_sel_hi:[1,1,1]
	v_pk_fma_f32 v[100:101], v[146:147], v[72:73], v[100:101] op_sel:[0,0,0] op_sel_hi:[1,0,1]
	v_add_f32_dpp v48, v48, v48 quad_perm:[2,3,0,1] row_mask:0xf bank_mask:0xf bound_ctrl:1
	v_add_f32_dpp v49, v49, v49 quad_perm:[2,3,0,1] row_mask:0xf bank_mask:0xf bound_ctrl:1
	v_add_f32_dpp v50, v50, v50 quad_perm:[2,3,0,1] row_mask:0xf bank_mask:0xf bound_ctrl:1
	v_add_f32_dpp v51, v51, v51 quad_perm:[2,3,0,1] row_mask:0xf bank_mask:0xf bound_ctrl:1
	v_pk_fma_f32 v[102:103], v[146:147], v[72:73], v[102:103] op_sel:[0,1,0] op_sel_hi:[1,1,1]
	v_pk_fma_f32 v[104:105], v[146:147], v[74:75], v[104:105] op_sel:[0,0,0] op_sel_hi:[1,0,1]
	v_pk_fma_f32 v[106:107], v[146:147], v[74:75], v[106:107] op_sel:[0,1,0] op_sel_hi:[1,1,1]
	v_add_f32_dpp v48, v48, v48 row_half_mirror row_mask:0xf bank_mask:0xf bound_ctrl:1
	v_add_f32_dpp v49, v49, v49 row_half_mirror row_mask:0xf bank_mask:0xf bound_ctrl:1
	v_add_f32_dpp v50, v50, v50 row_half_mirror row_mask:0xf bank_mask:0xf bound_ctrl:1
	v_add_f32_dpp v51, v51, v51 row_half_mirror row_mask:0xf bank_mask:0xf bound_ctrl:1
	v_pk_fma_f32 v[108:109], v[146:147], v[76:77], v[108:109] op_sel:[0,0,0] op_sel_hi:[1,0,1]
	s_mov_b64 exec, s[10:11]
	ds_write_b64 v45, v[48:49] offset:6144
	s_mov_b64 exec, s[0:1]
	v_pk_fma_f32 v[110:111], v[146:147], v[76:77], v[110:111] op_sel:[0,1,0] op_sel_hi:[1,1,1]
	s_nop 0
	v_pk_fma_f32 v[96:97], v[50:51], v[78:79], v[96:97] op_sel:[0,0,0] op_sel_hi:[1,0,1]
	v_pk_fma_f32 v[98:99], v[50:51], v[78:79], v[98:99] op_sel:[0,1,0] op_sel_hi:[1,1,1]
	v_pk_fma_f32 v[100:101], v[50:51], v[80:81], v[100:101] op_sel:[0,0,0] op_sel_hi:[1,0,1]
	v_pk_fma_f32 v[102:103], v[50:51], v[80:81], v[102:103] op_sel:[0,1,0] op_sel_hi:[1,1,1]
	v_pk_fma_f32 v[104:105], v[50:51], v[82:83], v[104:105] op_sel:[0,0,0] op_sel_hi:[1,0,1]
	v_pk_fma_f32 v[106:107], v[50:51], v[82:83], v[106:107] op_sel:[0,1,0] op_sel_hi:[1,1,1]
	v_pk_fma_f32 v[108:109], v[50:51], v[84:85], v[108:109] op_sel:[0,0,0] op_sel_hi:[1,0,1]
	v_pk_fma_f32 v[110:111], v[50:51], v[84:85], v[110:111] op_sel:[0,1,0] op_sel_hi:[1,1,1]
	v_pk_mul_f32 v[14:15], v[96:97], v[86:87] op_sel:[0,0] op_sel_hi:[1,0]
	v_pk_mul_f32 v[18:19], v[96:97], v[62:63] op_sel:[0,0] op_sel_hi:[1,0]
	v_pk_mul_f32 v[16:17], v[98:99], v[86:87] op_sel:[0,1] op_sel_hi:[1,1]
	v_pk_mul_f32 v[20:21], v[98:99], v[62:63] op_sel:[0,1] op_sel_hi:[1,1]
	v_pk_fma_f32 v[14:15], v[100:101], v[88:89], v[14:15] op_sel:[0,0,0] op_sel_hi:[1,0,1]
	v_pk_fma_f32 v[18:19], v[100:101], v[64:65], v[18:19] op_sel:[0,0,0] op_sel_hi:[1,0,1]
	v_pk_fma_f32 v[16:17], v[102:103], v[88:89], v[16:17] op_sel:[0,1,0] op_sel_hi:[1,1,1]
	v_pk_fma_f32 v[20:21], v[102:103], v[64:65], v[20:21] op_sel:[0,1,0] op_sel_hi:[1,1,1]
	v_pk_fma_f32 v[14:15], v[104:105], v[90:91], v[14:15] op_sel:[0,0,0] op_sel_hi:[1,0,1]
	v_pk_fma_f32 v[18:19], v[104:105], v[66:67], v[18:19] op_sel:[0,0,0] op_sel_hi:[1,0,1]
	v_pk_fma_f32 v[16:17], v[106:107], v[90:91], v[16:17] op_sel:[0,1,0] op_sel_hi:[1,1,1]
	v_pk_fma_f32 v[20:21], v[106:107], v[66:67], v[20:21] op_sel:[0,1,0] op_sel_hi:[1,1,1]
	v_pk_fma_f32 v[14:15], v[108:109], v[92:93], v[14:15] op_sel:[0,0,0] op_sel_hi:[1,0,1]
	v_pk_fma_f32 v[18:19], v[108:109], v[68:69], v[18:19] op_sel:[0,0,0] op_sel_hi:[1,0,1]
	v_pk_fma_f32 v[16:17], v[110:111], v[92:93], v[16:17] op_sel:[0,1,0] op_sel_hi:[1,1,1]
	v_pk_fma_f32 v[20:21], v[110:111], v[68:69], v[20:21] op_sel:[0,1,0] op_sel_hi:[1,1,1]
	v_pk_add_f32 v[48:49], v[14:15], v[16:17]
	v_pk_add_f32 v[50:51], v[18:19], v[20:21]
	s_waitcnt lgkmcnt(11)
; #define LAS __attribute__((address_space(3)))
; template <int CTRL> __device__ __forceinline__ float dpp_mov(float x) { return __int_as_float(__builtin_amdgcn_update_dpp(0, __float_as_int(x), CTRL, 0xF, 0xF, true)); }
; __device__ __forceinline__ float red8(float x) { x += dpp_mov<0xB1>(x); x += dpp_mov<0x4E>(x); x += dpp_mov<0x141>(x); return x; }
; __device__ __forceinline__ void scan_phase(const KP& P, LAS unsigned char* lds, const int tid, const int bx, const int G) {
;     ...
;             for (int s = 0; s < 32; ++s) {
;                 const LAS float* p = cb + s * 384;
;                 const f32x4 w0 = *(const LAS f32x4*)(p), w1 = *(const LAS f32x4*)(p + 4);
;                 const f32x4 k0 = *(const LAS f32x4*)(p + 64), k1 = *(const LAS f32x4*)(p + 68);
;                 const f32x4 a0 = *(const LAS f32x4*)(p + 128), a1 = *(const LAS f32x4*)(p + 132);
;                 const f32x4 b0 = *(const LAS f32x4*)(p + 192), b1 = *(const LAS f32x4*)(p + 196);
;                 const f32x4 r0 = *(const LAS f32x4*)(p + 256), r1 = *(const LAS f32x4*)(p + 260);
;                 const float vv = buf[(c & 1) * 12288 + s * 384 + 320 + v];
;                 f32x2 sa2 = S[0] * (f32x2){a0.x, a0.y};
;                 sa2 += S[1] * (f32x2){a0.z, a0.w}; sa2 += S[2] * (f32x2){a1.x, a1.y}; sa2 += S[3] * (f32x2){a1.z, a1.w};
;                 const float sa = red8(sa2.x + sa2.y);
;                 const f32x2 sav = {sa, sa}, vv2 = {vv, vv};
;                 S[0] = S[0] * (f32x2){w0.x, w0.y} + sav * (f32x2){b0.x, b0.y} + vv2 * (f32x2){k0.x, k0.y};
;                 S[1] = S[1] * (f32x2){w0.z, w0.w} + sav * (f32x2){b0.z, b0.w} + vv2 * (f32x2){k0.z, k0.w};
;                 S[2] = S[2] * (f32x2){w1.x, w1.y} + sav * (f32x2){b1.x, b1.y} + vv2 * (f32x2){k1.x, k1.y};
;                 S[3] = S[3] * (f32x2){w1.z, w1.w} + sav * (f32x2){b1.z, b1.w} + vv2 * (f32x2){k1.z, k1.w};
;                 f32x2 y2 = S[0] * (f32x2){r0.x, r0.y};
;                 y2 += S[1] * (f32x2){r0.z, r0.w}; y2 += S[2] * (f32x2){r1.x, r1.y}; y2 += S[3] * (f32x2){r1.z, r1.w};
;                 const float y = red8(y2.x + y2.y);
;                 if (kc == 0) ybuf[s * 64 + v] = y;
	ds_read_b128 v[70:73], v44 offset:43264
	ds_read_b128 v[74:77], v44 offset:43280
	ds_read_b128 v[78:81], v44 offset:43776
	ds_read_b128 v[82:85], v44 offset:43792
	ds_read_b128 v[86:89], v44 offset:44032
	ds_read_b128 v[90:93], v44 offset:44048
	ds_read_b64 v[146:147], v46 offset:43008
	ds_read_b128 v[62:65], v44 offset:45056
	ds_read_b128 v[66:69], v44 offset:45072
	v_add_f32_dpp v48, v48, v48 quad_perm:[1,0,3,2] row_mask:0xf bank_mask:0xf bound_ctrl:1
	v_add_f32_dpp v49, v49, v49 quad_perm:[1,0,3,2] row_mask:0xf bank_mask:0xf bound_ctrl:1
	v_add_f32_dpp v50, v50, v50 quad_perm:[1,0,3,2] row_mask:0xf bank_mask:0xf bound_ctrl:1
	v_add_f32_dpp v51, v51, v51 quad_perm:[1,0,3,2] row_mask:0xf bank_mask:0xf bound_ctrl:1
	v_pk_fma_f32 v[96:97], v[192:193], v[168:169], v[96:97] op_sel:[0,0,0] op_sel_hi:[1,0,1]
	v_pk_fma_f32 v[98:99], v[192:193], v[168:169], v[98:99] op_sel:[0,1,0] op_sel_hi:[1,1,1]
	v_pk_fma_f32 v[100:101], v[192:193], v[170:171], v[100:101] op_sel:[0,0,0] op_sel_hi:[1,0,1]
	v_add_f32_dpp v48, v48, v48 quad_perm:[2,3,0,1] row_mask:0xf bank_mask:0xf bound_ctrl:1
	v_add_f32_dpp v49, v49, v49 quad_perm:[2,3,0,1] row_mask:0xf bank_mask:0xf bound_ctrl:1
	v_add_f32_dpp v50, v50, v50 quad_perm:[2,3,0,1] row_mask:0xf bank_mask:0xf bound_ctrl:1
	v_add_f32_dpp v51, v51, v51 quad_perm:[2,3,0,1] row_mask:0xf bank_mask:0xf bound_ctrl:1
	v_pk_fma_f32 v[102:103], v[192:193], v[170:171], v[102:103] op_sel:[0,1,0] op_sel_hi:[1,1,1]
	v_pk_fma_f32 v[104:105], v[192:193], v[172:173], v[104:105] op_sel:[0,0,0] op_sel_hi:[1,0,1]
	v_pk_fma_f32 v[106:107], v[192:193], v[172:173], v[106:107] op_sel:[0,1,0] op_sel_hi:[1,1,1]
	v_add_f32_dpp v48, v48, v48 row_half_mirror row_mask:0xf bank_mask:0xf bound_ctrl:1
	v_add_f32_dpp v49, v49, v49 row_half_mirror row_mask:0xf bank_mask:0xf bound_ctrl:1
	v_add_f32_dpp v50, v50, v50 row_half_mirror row_mask:0xf bank_mask:0xf bound_ctrl:1
	v_add_f32_dpp v51, v51, v51 row_half_mirror row_mask:0xf bank_mask:0xf bound_ctrl:1
	v_pk_fma_f32 v[108:109], v[192:193], v[174:175], v[108:109] op_sel:[0,0,0] op_sel_hi:[1,0,1]
	s_mov_b64 exec, s[10:11]
	ds_write_b64 v45, v[48:49] offset:6400
	s_mov_b64 exec, s[0:1]
	v_pk_fma_f32 v[110:111], v[192:193], v[174:175], v[110:111] op_sel:[0,1,0] op_sel_hi:[1,1,1]
	s_nop 0
	v_pk_fma_f32 v[96:97], v[50:51], v[176:177], v[96:97] op_sel:[0,0,0] op_sel_hi:[1,0,1]
	v_pk_fma_f32 v[98:99], v[50:51], v[176:177], v[98:99] op_sel:[0,1,0] op_sel_hi:[1,1,1]
	v_pk_fma_f32 v[100:101], v[50:51], v[178:179], v[100:101] op_sel:[0,0,0] op_sel_hi:[1,0,1]
	v_pk_fma_f32 v[102:103], v[50:51], v[178:179], v[102:103] op_sel:[0,1,0] op_sel_hi:[1,1,1]
	v_pk_fma_f32 v[104:105], v[50:51], v[180:181], v[104:105] op_sel:[0,0,0] op_sel_hi:[1,0,1]
	v_pk_fma_f32 v[106:107], v[50:51], v[180:181], v[106:107] op_sel:[0,1,0] op_sel_hi:[1,1,1]
	v_pk_fma_f32 v[108:109], v[50:51], v[182:183], v[108:109] op_sel:[0,0,0] op_sel_hi:[1,0,1]
	v_pk_fma_f32 v[110:111], v[50:51], v[182:183], v[110:111] op_sel:[0,1,0] op_sel_hi:[1,1,1]
	v_pk_mul_f32 v[14:15], v[96:97], v[184:185] op_sel:[0,0] op_sel_hi:[1,0]
	v_pk_mul_f32 v[18:19], v[96:97], v[148:149] op_sel:[0,0] op_sel_hi:[1,0]
	v_pk_mul_f32 v[16:17], v[98:99], v[184:185] op_sel:[0,1] op_sel_hi:[1,1]
	v_pk_mul_f32 v[20:21], v[98:99], v[148:149] op_sel:[0,1] op_sel_hi:[1,1]
	v_pk_fma_f32 v[14:15], v[100:101], v[186:187], v[14:15] op_sel:[0,0,0] op_sel_hi:[1,0,1]
	v_pk_fma_f32 v[18:19], v[100:101], v[150:151], v[18:19] op_sel:[0,0,0] op_sel_hi:[1,0,1]
	v_pk_fma_f32 v[16:17], v[102:103], v[186:187], v[16:17] op_sel:[0,1,0] op_sel_hi:[1,1,1]
	v_pk_fma_f32 v[20:21], v[102:103], v[150:151], v[20:21] op_sel:[0,1,0] op_sel_hi:[1,1,1]
	v_pk_fma_f32 v[14:15], v[104:105], v[188:189], v[14:15] op_sel:[0,0,0] op_sel_hi:[1,0,1]
	v_pk_fma_f32 v[18:19], v[104:105], v[152:153], v[18:19] op_sel:[0,0,0] op_sel_hi:[1,0,1]
	v_pk_fma_f32 v[16:17], v[106:107], v[188:189], v[16:17] op_sel:[0,1,0] op_sel_hi:[1,1,1]
	v_pk_fma_f32 v[20:21], v[106:107], v[152:153], v[20:21] op_sel:[0,1,0] op_sel_hi:[1,1,1]
	v_pk_fma_f32 v[14:15], v[108:109], v[190:191], v[14:15] op_sel:[0,0,0] op_sel_hi:[1,0,1]
	v_pk_fma_f32 v[18:19], v[108:109], v[154:155], v[18:19] op_sel:[0,0,0] op_sel_hi:[1,0,1]
	v_pk_fma_f32 v[16:17], v[110:111], v[190:191], v[16:17] op_sel:[0,1,0] op_sel_hi:[1,1,1]
	v_pk_fma_f32 v[20:21], v[110:111], v[154:155], v[20:21] op_sel:[0,1,0] op_sel_hi:[1,1,1]
	v_pk_add_f32 v[48:49], v[14:15], v[16:17]
	v_pk_add_f32 v[50:51], v[18:19], v[20:21]
	s_waitcnt lgkmcnt(11)
; #define LAS __attribute__((address_space(3)))
; template <int CTRL> __device__ __forceinline__ float dpp_mov(float x) { return __int_as_float(__builtin_amdgcn_update_dpp(0, __float_as_int(x), CTRL, 0xF, 0xF, true)); }
; __device__ __forceinline__ float red8(float x) { x += dpp_mov<0xB1>(x); x += dpp_mov<0x4E>(x); x += dpp_mov<0x141>(x); return x; }
; __device__ __forceinline__ void scan_phase(const KP& P, LAS unsigned char* lds, const int tid, const int bx, const int G) {
;     ...
;             for (int s = 0; s < 32; ++s) {
;                 const LAS float* p = cb + s * 384;
;                 const f32x4 w0 = *(const LAS f32x4*)(p), w1 = *(const LAS f32x4*)(p + 4);
;                 const f32x4 k0 = *(const LAS f32x4*)(p + 64), k1 = *(const LAS f32x4*)(p + 68);
;                 const f32x4 a0 = *(const LAS f32x4*)(p + 128), a1 = *(const LAS f32x4*)(p + 132);
;                 const f32x4 b0 = *(const LAS f32x4*)(p + 192), b1 = *(const LAS f32x4*)(p + 196);
;                 const f32x4 r0 = *(const LAS f32x4*)(p + 256), r1 = *(const LAS f32x4*)(p + 260);
;                 const float vv = buf[(c & 1) * 12288 + s * 384 + 320 + v];
;                 f32x2 sa2 = S[0] * (f32x2){a0.x, a0.y};
;                 sa2 += S[1] * (f32x2){a0.z, a0.w}; sa2 += S[2] * (f32x2){a1.x, a1.y}; sa2 += S[3] * (f32x2){a1.z, a1.w};
;                 const float sa = red8(sa2.x + sa2.y);
;                 const f32x2 sav = {sa, sa}, vv2 = {vv, vv};
;                 S[0] = S[0] * (f32x2){w0.x, w0.y} + sav * (f32x2){b0.x, b0.y} + vv2 * (f32x2){k0.x, k0.y};
;                 S[1] = S[1] * (f32x2){w0.z, w0.w} + sav * (f32x2){b0.z, b0.w} + vv2 * (f32x2){k0.z, k0.w};
;                 S[2] = S[2] * (f32x2){w1.x, w1.y} + sav * (f32x2){b1.x, b1.y} + vv2 * (f32x2){k1.x, k1.y};
;                 S[3] = S[3] * (f32x2){w1.z, w1.w} + sav * (f32x2){b1.z, b1.w} + vv2 * (f32x2){k1.z, k1.w};
;                 f32x2 y2 = S[0] * (f32x2){r0.x, r0.y};
;                 y2 += S[1] * (f32x2){r0.z, r0.w}; y2 += S[2] * (f32x2){r1.x, r1.y}; y2 += S[3] * (f32x2){r1.z, r1.w};
;                 const float y = red8(y2.x + y2.y);
;                 if (kc == 0) ybuf[s * 64 + v] = y;
	ds_read_b128 v[168:171], v44 offset:44800
	ds_read_b128 v[172:175], v44 offset:44816
	ds_read_b128 v[176:179], v44 offset:45312
	ds_read_b128 v[180:183], v44 offset:45328
	ds_read_b128 v[184:187], v44 offset:45568
	ds_read_b128 v[188:191], v44 offset:45584
	ds_read_b64 v[192:193], v46 offset:44544
	ds_read_b128 v[148:151], v44 offset:46592
	ds_read_b128 v[152:155], v44 offset:46608
	v_add_f32_dpp v48, v48, v48 quad_perm:[1,0,3,2] row_mask:0xf bank_mask:0xf bound_ctrl:1
	v_add_f32_dpp v49, v49, v49 quad_perm:[1,0,3,2] row_mask:0xf bank_mask:0xf bound_ctrl:1
	v_add_f32_dpp v50, v50, v50 quad_perm:[1,0,3,2] row_mask:0xf bank_mask:0xf bound_ctrl:1
	v_add_f32_dpp v51, v51, v51 quad_perm:[1,0,3,2] row_mask:0xf bank_mask:0xf bound_ctrl:1
	v_pk_fma_f32 v[96:97], v[144:145], v[120:121], v[96:97] op_sel:[0,0,0] op_sel_hi:[1,0,1]
	v_pk_fma_f32 v[98:99], v[144:145], v[120:121], v[98:99] op_sel:[0,1,0] op_sel_hi:[1,1,1]
	v_pk_fma_f32 v[100:101], v[144:145], v[122:123], v[100:101] op_sel:[0,0,0] op_sel_hi:[1,0,1]
	v_add_f32_dpp v48, v48, v48 quad_perm:[2,3,0,1] row_mask:0xf bank_mask:0xf bound_ctrl:1
	v_add_f32_dpp v49, v49, v49 quad_perm:[2,3,0,1] row_mask:0xf bank_mask:0xf bound_ctrl:1
	v_add_f32_dpp v50, v50, v50 quad_perm:[2,3,0,1] row_mask:0xf bank_mask:0xf bound_ctrl:1
	v_add_f32_dpp v51, v51, v51 quad_perm:[2,3,0,1] row_mask:0xf bank_mask:0xf bound_ctrl:1
	v_pk_fma_f32 v[102:103], v[144:145], v[122:123], v[102:103] op_sel:[0,1,0] op_sel_hi:[1,1,1]
	v_pk_fma_f32 v[104:105], v[144:145], v[124:125], v[104:105] op_sel:[0,0,0] op_sel_hi:[1,0,1]
	v_pk_fma_f32 v[106:107], v[144:145], v[124:125], v[106:107] op_sel:[0,1,0] op_sel_hi:[1,1,1]
	v_add_f32_dpp v48, v48, v48 row_half_mirror row_mask:0xf bank_mask:0xf bound_ctrl:1
	v_add_f32_dpp v49, v49, v49 row_half_mirror row_mask:0xf bank_mask:0xf bound_ctrl:1
	v_add_f32_dpp v50, v50, v50 row_half_mirror row_mask:0xf bank_mask:0xf bound_ctrl:1
	v_add_f32_dpp v51, v51, v51 row_half_mirror row_mask:0xf bank_mask:0xf bound_ctrl:1
	v_pk_fma_f32 v[108:109], v[144:145], v[126:127], v[108:109] op_sel:[0,0,0] op_sel_hi:[1,0,1]
	s_mov_b64 exec, s[10:11]
	ds_write_b64 v45, v[48:49] offset:6656
	s_mov_b64 exec, s[0:1]
	v_pk_fma_f32 v[110:111], v[144:145], v[126:127], v[110:111] op_sel:[0,1,0] op_sel_hi:[1,1,1]
	s_nop 0
	v_pk_fma_f32 v[96:97], v[50:51], v[128:129], v[96:97] op_sel:[0,0,0] op_sel_hi:[1,0,1]
	v_pk_fma_f32 v[98:99], v[50:51], v[128:129], v[98:99] op_sel:[0,1,0] op_sel_hi:[1,1,1]
	v_pk_fma_f32 v[100:101], v[50:51], v[130:131], v[100:101] op_sel:[0,0,0] op_sel_hi:[1,0,1]
	v_pk_fma_f32 v[102:103], v[50:51], v[130:131], v[102:103] op_sel:[0,1,0] op_sel_hi:[1,1,1]
	v_pk_fma_f32 v[104:105], v[50:51], v[132:133], v[104:105] op_sel:[0,0,0] op_sel_hi:[1,0,1]
	v_pk_fma_f32 v[106:107], v[50:51], v[132:133], v[106:107] op_sel:[0,1,0] op_sel_hi:[1,1,1]
	v_pk_fma_f32 v[108:109], v[50:51], v[134:135], v[108:109] op_sel:[0,0,0] op_sel_hi:[1,0,1]
	v_pk_fma_f32 v[110:111], v[50:51], v[134:135], v[110:111] op_sel:[0,1,0] op_sel_hi:[1,1,1]
	v_pk_mul_f32 v[14:15], v[96:97], v[136:137] op_sel:[0,0] op_sel_hi:[1,0]
	v_pk_mul_f32 v[18:19], v[96:97], v[156:157] op_sel:[0,0] op_sel_hi:[1,0]
	v_pk_mul_f32 v[16:17], v[98:99], v[136:137] op_sel:[0,1] op_sel_hi:[1,1]
	v_pk_mul_f32 v[20:21], v[98:99], v[156:157] op_sel:[0,1] op_sel_hi:[1,1]
	v_pk_fma_f32 v[14:15], v[100:101], v[138:139], v[14:15] op_sel:[0,0,0] op_sel_hi:[1,0,1]
	v_pk_fma_f32 v[18:19], v[100:101], v[158:159], v[18:19] op_sel:[0,0,0] op_sel_hi:[1,0,1]
	v_pk_fma_f32 v[16:17], v[102:103], v[138:139], v[16:17] op_sel:[0,1,0] op_sel_hi:[1,1,1]
	v_pk_fma_f32 v[20:21], v[102:103], v[158:159], v[20:21] op_sel:[0,1,0] op_sel_hi:[1,1,1]
	v_pk_fma_f32 v[14:15], v[104:105], v[140:141], v[14:15] op_sel:[0,0,0] op_sel_hi:[1,0,1]
	v_pk_fma_f32 v[18:19], v[104:105], v[160:161], v[18:19] op_sel:[0,0,0] op_sel_hi:[1,0,1]
	v_pk_fma_f32 v[16:17], v[106:107], v[140:141], v[16:17] op_sel:[0,1,0] op_sel_hi:[1,1,1]
	v_pk_fma_f32 v[20:21], v[106:107], v[160:161], v[20:21] op_sel:[0,1,0] op_sel_hi:[1,1,1]
	v_pk_fma_f32 v[14:15], v[108:109], v[142:143], v[14:15] op_sel:[0,0,0] op_sel_hi:[1,0,1]
	v_pk_fma_f32 v[18:19], v[108:109], v[162:163], v[18:19] op_sel:[0,0,0] op_sel_hi:[1,0,1]
	v_pk_fma_f32 v[16:17], v[110:111], v[142:143], v[16:17] op_sel:[0,1,0] op_sel_hi:[1,1,1]
	v_pk_fma_f32 v[20:21], v[110:111], v[162:163], v[20:21] op_sel:[0,1,0] op_sel_hi:[1,1,1]
	v_pk_add_f32 v[48:49], v[14:15], v[16:17]
	v_pk_add_f32 v[50:51], v[18:19], v[20:21]
	s_waitcnt lgkmcnt(11)
; #define LAS __attribute__((address_space(3)))
; template <int CTRL> __device__ __forceinline__ float dpp_mov(float x) { return __int_as_float(__builtin_amdgcn_update_dpp(0, __float_as_int(x), CTRL, 0xF, 0xF, true)); }
; __device__ __forceinline__ float red8(float x) { x += dpp_mov<0xB1>(x); x += dpp_mov<0x4E>(x); x += dpp_mov<0x141>(x); return x; }
; __device__ __forceinline__ void scan_phase(const KP& P, LAS unsigned char* lds, const int tid, const int bx, const int G) {
;     ...
;             for (int s = 0; s < 32; ++s) {
;                 const LAS float* p = cb + s * 384;
;                 const f32x4 w0 = *(const LAS f32x4*)(p), w1 = *(const LAS f32x4*)(p + 4);
;                 const f32x4 k0 = *(const LAS f32x4*)(p + 64), k1 = *(const LAS f32x4*)(p + 68);
;                 const f32x4 a0 = *(const LAS f32x4*)(p + 128), a1 = *(const LAS f32x4*)(p + 132);
;                 const f32x4 b0 = *(const LAS f32x4*)(p + 192), b1 = *(const LAS f32x4*)(p + 196);
;                 const f32x4 r0 = *(const LAS f32x4*)(p + 256), r1 = *(const LAS f32x4*)(p + 260);
;                 const float vv = buf[(c & 1) * 12288 + s * 384 + 320 + v];
;                 f32x2 sa2 = S[0] * (f32x2){a0.x, a0.y};
;                 sa2 += S[1] * (f32x2){a0.z, a0.w}; sa2 += S[2] * (f32x2){a1.x, a1.y}; sa2 += S[3] * (f32x2){a1.z, a1.w};
;                 const float sa = red8(sa2.x + sa2.y);
;                 const f32x2 sav = {sa, sa}, vv2 = {vv, vv};
;                 S[0] = S[0] * (f32x2){w0.x, w0.y} + sav * (f32x2){b0.x, b0.y} + vv2 * (f32x2){k0.x, k0.y};
;                 S[1] = S[1] * (f32x2){w0.z, w0.w} + sav * (f32x2){b0.z, b0.w} + vv2 * (f32x2){k0.z, k0.w};
;                 S[2] = S[2] * (f32x2){w1.x, w1.y} + sav * (f32x2){b1.x, b1.y} + vv2 * (f32x2){k1.x, k1.y};
;                 S[3] = S[3] * (f32x2){w1.z, w1.w} + sav * (f32x2){b1.z, b1.w} + vv2 * (f32x2){k1.z, k1.w};
;                 f32x2 y2 = S[0] * (f32x2){r0.x, r0.y};
;                 y2 += S[1] * (f32x2){r0.z, r0.w}; y2 += S[2] * (f32x2){r1.x, r1.y}; y2 += S[3] * (f32x2){r1.z, r1.w};
;                 const float y = red8(y2.x + y2.y);
;                 if (kc == 0) ybuf[s * 64 + v] = y;
	ds_read_b128 v[120:123], v44 offset:46336
	ds_read_b128 v[124:127], v44 offset:46352
	ds_read_b128 v[128:131], v44 offset:46848
	ds_read_b128 v[132:135], v44 offset:46864
	ds_read_b128 v[136:139], v44 offset:47104
	ds_read_b128 v[140:143], v44 offset:47120
	ds_read_b64 v[144:145], v46 offset:46080
	ds_read_b128 v[156:159], v44 offset:48128
	ds_read_b128 v[160:163], v44 offset:48144
	v_add_f32_dpp v48, v48, v48 quad_perm:[1,0,3,2] row_mask:0xf bank_mask:0xf bound_ctrl:1
	v_add_f32_dpp v49, v49, v49 quad_perm:[1,0,3,2] row_mask:0xf bank_mask:0xf bound_ctrl:1
	v_add_f32_dpp v50, v50, v50 quad_perm:[1,0,3,2] row_mask:0xf bank_mask:0xf bound_ctrl:1
	v_add_f32_dpp v51, v51, v51 quad_perm:[1,0,3,2] row_mask:0xf bank_mask:0xf bound_ctrl:1
	v_pk_fma_f32 v[96:97], v[146:147], v[70:71], v[96:97] op_sel:[0,0,0] op_sel_hi:[1,0,1]
	v_pk_fma_f32 v[98:99], v[146:147], v[70:71], v[98:99] op_sel:[0,1,0] op_sel_hi:[1,1,1]
	v_pk_fma_f32 v[100:101], v[146:147], v[72:73], v[100:101] op_sel:[0,0,0] op_sel_hi:[1,0,1]
	v_add_f32_dpp v48, v48, v48 quad_perm:[2,3,0,1] row_mask:0xf bank_mask:0xf bound_ctrl:1
	v_add_f32_dpp v49, v49, v49 quad_perm:[2,3,0,1] row_mask:0xf bank_mask:0xf bound_ctrl:1
	v_add_f32_dpp v50, v50, v50 quad_perm:[2,3,0,1] row_mask:0xf bank_mask:0xf bound_ctrl:1
	v_add_f32_dpp v51, v51, v51 quad_perm:[2,3,0,1] row_mask:0xf bank_mask:0xf bound_ctrl:1
	v_pk_fma_f32 v[102:103], v[146:147], v[72:73], v[102:103] op_sel:[0,1,0] op_sel_hi:[1,1,1]
	v_pk_fma_f32 v[104:105], v[146:147], v[74:75], v[104:105] op_sel:[0,0,0] op_sel_hi:[1,0,1]
	v_pk_fma_f32 v[106:107], v[146:147], v[74:75], v[106:107] op_sel:[0,1,0] op_sel_hi:[1,1,1]
	v_add_f32_dpp v48, v48, v48 row_half_mirror row_mask:0xf bank_mask:0xf bound_ctrl:1
	v_add_f32_dpp v49, v49, v49 row_half_mirror row_mask:0xf bank_mask:0xf bound_ctrl:1
	v_add_f32_dpp v50, v50, v50 row_half_mirror row_mask:0xf bank_mask:0xf bound_ctrl:1
	v_add_f32_dpp v51, v51, v51 row_half_mirror row_mask:0xf bank_mask:0xf bound_ctrl:1
	v_pk_fma_f32 v[108:109], v[146:147], v[76:77], v[108:109] op_sel:[0,0,0] op_sel_hi:[1,0,1]
	s_mov_b64 exec, s[10:11]
	ds_write_b64 v45, v[48:49] offset:6912
	s_mov_b64 exec, s[0:1]
	v_pk_fma_f32 v[110:111], v[146:147], v[76:77], v[110:111] op_sel:[0,1,0] op_sel_hi:[1,1,1]
	s_nop 0
	v_pk_fma_f32 v[96:97], v[50:51], v[78:79], v[96:97] op_sel:[0,0,0] op_sel_hi:[1,0,1]
	v_pk_fma_f32 v[98:99], v[50:51], v[78:79], v[98:99] op_sel:[0,1,0] op_sel_hi:[1,1,1]
	v_pk_fma_f32 v[100:101], v[50:51], v[80:81], v[100:101] op_sel:[0,0,0] op_sel_hi:[1,0,1]
	v_pk_fma_f32 v[102:103], v[50:51], v[80:81], v[102:103] op_sel:[0,1,0] op_sel_hi:[1,1,1]
	v_pk_fma_f32 v[104:105], v[50:51], v[82:83], v[104:105] op_sel:[0,0,0] op_sel_hi:[1,0,1]
	v_pk_fma_f32 v[106:107], v[50:51], v[82:83], v[106:107] op_sel:[0,1,0] op_sel_hi:[1,1,1]
	v_pk_fma_f32 v[108:109], v[50:51], v[84:85], v[108:109] op_sel:[0,0,0] op_sel_hi:[1,0,1]
	v_pk_fma_f32 v[110:111], v[50:51], v[84:85], v[110:111] op_sel:[0,1,0] op_sel_hi:[1,1,1]
	v_pk_mul_f32 v[14:15], v[96:97], v[86:87] op_sel:[0,0] op_sel_hi:[1,0]
	v_pk_mul_f32 v[18:19], v[96:97], v[62:63] op_sel:[0,0] op_sel_hi:[1,0]
	v_pk_mul_f32 v[16:17], v[98:99], v[86:87] op_sel:[0,1] op_sel_hi:[1,1]
	v_pk_mul_f32 v[20:21], v[98:99], v[62:63] op_sel:[0,1] op_sel_hi:[1,1]
	v_pk_fma_f32 v[14:15], v[100:101], v[88:89], v[14:15] op_sel:[0,0,0] op_sel_hi:[1,0,1]
	v_pk_fma_f32 v[18:19], v[100:101], v[64:65], v[18:19] op_sel:[0,0,0] op_sel_hi:[1,0,1]
	v_pk_fma_f32 v[16:17], v[102:103], v[88:89], v[16:17] op_sel:[0,1,0] op_sel_hi:[1,1,1]
	v_pk_fma_f32 v[20:21], v[102:103], v[64:65], v[20:21] op_sel:[0,1,0] op_sel_hi:[1,1,1]
	v_pk_fma_f32 v[14:15], v[104:105], v[90:91], v[14:15] op_sel:[0,0,0] op_sel_hi:[1,0,1]
	v_pk_fma_f32 v[18:19], v[104:105], v[66:67], v[18:19] op_sel:[0,0,0] op_sel_hi:[1,0,1]
	v_pk_fma_f32 v[16:17], v[106:107], v[90:91], v[16:17] op_sel:[0,1,0] op_sel_hi:[1,1,1]
	v_pk_fma_f32 v[20:21], v[106:107], v[66:67], v[20:21] op_sel:[0,1,0] op_sel_hi:[1,1,1]
	v_pk_fma_f32 v[14:15], v[108:109], v[92:93], v[14:15] op_sel:[0,0,0] op_sel_hi:[1,0,1]
	v_pk_fma_f32 v[18:19], v[108:109], v[68:69], v[18:19] op_sel:[0,0,0] op_sel_hi:[1,0,1]
	v_pk_fma_f32 v[16:17], v[110:111], v[92:93], v[16:17] op_sel:[0,1,0] op_sel_hi:[1,1,1]
	v_pk_fma_f32 v[20:21], v[110:111], v[68:69], v[20:21] op_sel:[0,1,0] op_sel_hi:[1,1,1]
	v_pk_add_f32 v[48:49], v[14:15], v[16:17]
	v_pk_add_f32 v[50:51], v[18:19], v[20:21]
	s_waitcnt lgkmcnt(11)
; #define LAS __attribute__((address_space(3)))
; template <int CTRL> __device__ __forceinline__ float dpp_mov(float x) { return __int_as_float(__builtin_amdgcn_update_dpp(0, __float_as_int(x), CTRL, 0xF, 0xF, true)); }
; __device__ __forceinline__ float red8(float x) { x += dpp_mov<0xB1>(x); x += dpp_mov<0x4E>(x); x += dpp_mov<0x141>(x); return x; }
; __device__ __forceinline__ void scan_phase(const KP& P, LAS unsigned char* lds, const int tid, const int bx, const int G) {
;     ...
;             for (int s = 0; s < 32; ++s) {
;                 const LAS float* p = cb + s * 384;
;                 const f32x4 w0 = *(const LAS f32x4*)(p), w1 = *(const LAS f32x4*)(p + 4);
;                 const f32x4 k0 = *(const LAS f32x4*)(p + 64), k1 = *(const LAS f32x4*)(p + 68);
;                 const f32x4 a0 = *(const LAS f32x4*)(p + 128), a1 = *(const LAS f32x4*)(p + 132);
;                 const f32x4 b0 = *(const LAS f32x4*)(p + 192), b1 = *(const LAS f32x4*)(p + 196);
;                 const f32x4 r0 = *(const LAS f32x4*)(p + 256), r1 = *(const LAS f32x4*)(p + 260);
;                 const float vv = buf[(c & 1) * 12288 + s * 384 + 320 + v];
;                 f32x2 sa2 = S[0] * (f32x2){a0.x, a0.y};
;                 sa2 += S[1] * (f32x2){a0.z, a0.w}; sa2 += S[2] * (f32x2){a1.x, a1.y}; sa2 += S[3] * (f32x2){a1.z, a1.w};
;                 const float sa = red8(sa2.x + sa2.y);
;                 const f32x2 sav = {sa, sa}, vv2 = {vv, vv};
;                 S[0] = S[0] * (f32x2){w0.x, w0.y} + sav * (f32x2){b0.x, b0.y} + vv2 * (f32x2){k0.x, k0.y};
;                 S[1] = S[1] * (f32x2){w0.z, w0.w} + sav * (f32x2){b0.z, b0.w} + vv2 * (f32x2){k0.z, k0.w};
;                 S[2] = S[2] * (f32x2){w1.x, w1.y} + sav * (f32x2){b1.x, b1.y} + vv2 * (f32x2){k1.x, k1.y};
;                 S[3] = S[3] * (f32x2){w1.z, w1.w} + sav * (f32x2){b1.z, b1.w} + vv2 * (f32x2){k1.z, k1.w};
;                 f32x2 y2 = S[0] * (f32x2){r0.x, r0.y};
;                 y2 += S[1] * (f32x2){r0.z, r0.w}; y2 += S[2] * (f32x2){r1.x, r1.y}; y2 += S[3] * (f32x2){r1.z, r1.w};
;                 const float y = red8(y2.x + y2.y);
;                 if (kc == 0) ybuf[s * 64 + v] = y;
	ds_read_b128 v[70:73], v44 offset:47872
	ds_read_b128 v[74:77], v44 offset:47888
	ds_read_b128 v[78:81], v44 offset:48384
	ds_read_b128 v[82:85], v44 offset:48400
	ds_read_b128 v[86:89], v44 offset:48640
	ds_read_b128 v[90:93], v44 offset:48656
	ds_read_b64 v[146:147], v46 offset:47616
	v_add_f32_dpp v48, v48, v48 quad_perm:[1,0,3,2] row_mask:0xf bank_mask:0xf bound_ctrl:1
	v_add_f32_dpp v49, v49, v49 quad_perm:[1,0,3,2] row_mask:0xf bank_mask:0xf bound_ctrl:1
	v_add_f32_dpp v50, v50, v50 quad_perm:[1,0,3,2] row_mask:0xf bank_mask:0xf bound_ctrl:1
	v_add_f32_dpp v51, v51, v51 quad_perm:[1,0,3,2] row_mask:0xf bank_mask:0xf bound_ctrl:1
	v_pk_fma_f32 v[96:97], v[192:193], v[168:169], v[96:97] op_sel:[0,0,0] op_sel_hi:[1,0,1]
	v_pk_fma_f32 v[98:99], v[192:193], v[168:169], v[98:99] op_sel:[0,1,0] op_sel_hi:[1,1,1]
	v_pk_fma_f32 v[100:101], v[192:193], v[170:171], v[100:101] op_sel:[0,0,0] op_sel_hi:[1,0,1]
	v_add_f32_dpp v48, v48, v48 quad_perm:[2,3,0,1] row_mask:0xf bank_mask:0xf bound_ctrl:1
	v_add_f32_dpp v49, v49, v49 quad_perm:[2,3,0,1] row_mask:0xf bank_mask:0xf bound_ctrl:1
	v_add_f32_dpp v50, v50, v50 quad_perm:[2,3,0,1] row_mask:0xf bank_mask:0xf bound_ctrl:1
	v_add_f32_dpp v51, v51, v51 quad_perm:[2,3,0,1] row_mask:0xf bank_mask:0xf bound_ctrl:1
	v_pk_fma_f32 v[102:103], v[192:193], v[170:171], v[102:103] op_sel:[0,1,0] op_sel_hi:[1,1,1]
	v_pk_fma_f32 v[104:105], v[192:193], v[172:173], v[104:105] op_sel:[0,0,0] op_sel_hi:[1,0,1]
	v_pk_fma_f32 v[106:107], v[192:193], v[172:173], v[106:107] op_sel:[0,1,0] op_sel_hi:[1,1,1]
	v_add_f32_dpp v48, v48, v48 row_half_mirror row_mask:0xf bank_mask:0xf bound_ctrl:1
	v_add_f32_dpp v49, v49, v49 row_half_mirror row_mask:0xf bank_mask:0xf bound_ctrl:1
	v_add_f32_dpp v50, v50, v50 row_half_mirror row_mask:0xf bank_mask:0xf bound_ctrl:1
	v_add_f32_dpp v51, v51, v51 row_half_mirror row_mask:0xf bank_mask:0xf bound_ctrl:1
	v_pk_fma_f32 v[108:109], v[192:193], v[174:175], v[108:109] op_sel:[0,0,0] op_sel_hi:[1,0,1]
	s_mov_b64 exec, s[10:11]
	ds_write_b64 v45, v[48:49] offset:7168
	s_mov_b64 exec, s[0:1]
	v_pk_fma_f32 v[110:111], v[192:193], v[174:175], v[110:111] op_sel:[0,1,0] op_sel_hi:[1,1,1]
	s_nop 0
	v_pk_fma_f32 v[96:97], v[50:51], v[176:177], v[96:97] op_sel:[0,0,0] op_sel_hi:[1,0,1]
	v_pk_fma_f32 v[98:99], v[50:51], v[176:177], v[98:99] op_sel:[0,1,0] op_sel_hi:[1,1,1]
	v_pk_fma_f32 v[100:101], v[50:51], v[178:179], v[100:101] op_sel:[0,0,0] op_sel_hi:[1,0,1]
	v_pk_fma_f32 v[102:103], v[50:51], v[178:179], v[102:103] op_sel:[0,1,0] op_sel_hi:[1,1,1]
	v_pk_fma_f32 v[104:105], v[50:51], v[180:181], v[104:105] op_sel:[0,0,0] op_sel_hi:[1,0,1]
	v_pk_fma_f32 v[106:107], v[50:51], v[180:181], v[106:107] op_sel:[0,1,0] op_sel_hi:[1,1,1]
	v_pk_fma_f32 v[108:109], v[50:51], v[182:183], v[108:109] op_sel:[0,0,0] op_sel_hi:[1,0,1]
	v_pk_fma_f32 v[110:111], v[50:51], v[182:183], v[110:111] op_sel:[0,1,0] op_sel_hi:[1,1,1]
	v_pk_mul_f32 v[14:15], v[96:97], v[184:185] op_sel:[0,0] op_sel_hi:[1,0]
	v_pk_mul_f32 v[18:19], v[96:97], v[148:149] op_sel:[0,0] op_sel_hi:[1,0]
	v_pk_mul_f32 v[16:17], v[98:99], v[184:185] op_sel:[0,1] op_sel_hi:[1,1]
	v_pk_mul_f32 v[20:21], v[98:99], v[148:149] op_sel:[0,1] op_sel_hi:[1,1]
	v_pk_fma_f32 v[14:15], v[100:101], v[186:187], v[14:15] op_sel:[0,0,0] op_sel_hi:[1,0,1]
	v_pk_fma_f32 v[18:19], v[100:101], v[150:151], v[18:19] op_sel:[0,0,0] op_sel_hi:[1,0,1]
	v_pk_fma_f32 v[16:17], v[102:103], v[186:187], v[16:17] op_sel:[0,1,0] op_sel_hi:[1,1,1]
	v_pk_fma_f32 v[20:21], v[102:103], v[150:151], v[20:21] op_sel:[0,1,0] op_sel_hi:[1,1,1]
	v_pk_fma_f32 v[14:15], v[104:105], v[188:189], v[14:15] op_sel:[0,0,0] op_sel_hi:[1,0,1]
	v_pk_fma_f32 v[18:19], v[104:105], v[152:153], v[18:19] op_sel:[0,0,0] op_sel_hi:[1,0,1]
	v_pk_fma_f32 v[16:17], v[106:107], v[188:189], v[16:17] op_sel:[0,1,0] op_sel_hi:[1,1,1]
	v_pk_fma_f32 v[20:21], v[106:107], v[152:153], v[20:21] op_sel:[0,1,0] op_sel_hi:[1,1,1]
	v_pk_fma_f32 v[14:15], v[108:109], v[190:191], v[14:15] op_sel:[0,0,0] op_sel_hi:[1,0,1]
	v_pk_fma_f32 v[18:19], v[108:109], v[154:155], v[18:19] op_sel:[0,0,0] op_sel_hi:[1,0,1]
	v_pk_fma_f32 v[16:17], v[110:111], v[190:191], v[16:17] op_sel:[0,1,0] op_sel_hi:[1,1,1]
	v_pk_fma_f32 v[20:21], v[110:111], v[154:155], v[20:21] op_sel:[0,1,0] op_sel_hi:[1,1,1]
	v_pk_add_f32 v[48:49], v[14:15], v[16:17]
	v_pk_add_f32 v[50:51], v[18:19], v[20:21]
	s_waitcnt lgkmcnt(9)
; #define LAS __attribute__((address_space(3)))
; template <int CTRL> __device__ __forceinline__ float dpp_mov(float x) { return __int_as_float(__builtin_amdgcn_update_dpp(0, __float_as_int(x), CTRL, 0xF, 0xF, true)); }
; __device__ __forceinline__ float red8(float x) { x += dpp_mov<0xB1>(x); x += dpp_mov<0x4E>(x); x += dpp_mov<0x141>(x); return x; }
; __device__ __forceinline__ void scan_phase(const KP& P, LAS unsigned char* lds, const int tid, const int bx, const int G) {
;     ...
;             for (int s = 0; s < 32; ++s) {
;                 const LAS float* p = cb + s * 384;
;                 const f32x4 w0 = *(const LAS f32x4*)(p), w1 = *(const LAS f32x4*)(p + 4);
;                 const f32x4 k0 = *(const LAS f32x4*)(p + 64), k1 = *(const LAS f32x4*)(p + 68);
;                 const f32x4 a0 = *(const LAS f32x4*)(p + 128), a1 = *(const LAS f32x4*)(p + 132);
;                 const f32x4 b0 = *(const LAS f32x4*)(p + 192), b1 = *(const LAS f32x4*)(p + 196);
;                 const f32x4 r0 = *(const LAS f32x4*)(p + 256), r1 = *(const LAS f32x4*)(p + 260);
;                 const float vv = buf[(c & 1) * 12288 + s * 384 + 320 + v];
;                 f32x2 sa2 = S[0] * (f32x2){a0.x, a0.y};
;                 sa2 += S[1] * (f32x2){a0.z, a0.w}; sa2 += S[2] * (f32x2){a1.x, a1.y}; sa2 += S[3] * (f32x2){a1.z, a1.w};
;                 const float sa = red8(sa2.x + sa2.y);
;                 const f32x2 sav = {sa, sa}, vv2 = {vv, vv};
;                 S[0] = S[0] * (f32x2){w0.x, w0.y} + sav * (f32x2){b0.x, b0.y} + vv2 * (f32x2){k0.x, k0.y};
;                 S[1] = S[1] * (f32x2){w0.z, w0.w} + sav * (f32x2){b0.z, b0.w} + vv2 * (f32x2){k0.z, k0.w};
;                 S[2] = S[2] * (f32x2){w1.x, w1.y} + sav * (f32x2){b1.x, b1.y} + vv2 * (f32x2){k1.x, k1.y};
;                 S[3] = S[3] * (f32x2){w1.z, w1.w} + sav * (f32x2){b1.z, b1.w} + vv2 * (f32x2){k1.z, k1.w};
;                 f32x2 y2 = S[0] * (f32x2){r0.x, r0.y};
;                 y2 += S[1] * (f32x2){r0.z, r0.w}; y2 += S[2] * (f32x2){r1.x, r1.y}; y2 += S[3] * (f32x2){r1.z, r1.w};
;                 const float y = red8(y2.x + y2.y);
;                 if (kc == 0) ybuf[s * 64 + v] = y;
	s_nop 1
	v_add_f32_dpp v48, v48, v48 quad_perm:[1,0,3,2] row_mask:0xf bank_mask:0xf bound_ctrl:1
	v_add_f32_dpp v49, v49, v49 quad_perm:[1,0,3,2] row_mask:0xf bank_mask:0xf bound_ctrl:1
	v_add_f32_dpp v50, v50, v50 quad_perm:[1,0,3,2] row_mask:0xf bank_mask:0xf bound_ctrl:1
	v_add_f32_dpp v51, v51, v51 quad_perm:[1,0,3,2] row_mask:0xf bank_mask:0xf bound_ctrl:1
	v_pk_fma_f32 v[96:97], v[144:145], v[120:121], v[96:97] op_sel:[0,0,0] op_sel_hi:[1,0,1]
	v_pk_fma_f32 v[98:99], v[144:145], v[120:121], v[98:99] op_sel:[0,1,0] op_sel_hi:[1,1,1]
	v_pk_fma_f32 v[100:101], v[144:145], v[122:123], v[100:101] op_sel:[0,0,0] op_sel_hi:[1,0,1]
	v_add_f32_dpp v48, v48, v48 quad_perm:[2,3,0,1] row_mask:0xf bank_mask:0xf bound_ctrl:1
	v_add_f32_dpp v49, v49, v49 quad_perm:[2,3,0,1] row_mask:0xf bank_mask:0xf bound_ctrl:1
	v_add_f32_dpp v50, v50, v50 quad_perm:[2,3,0,1] row_mask:0xf bank_mask:0xf bound_ctrl:1
	v_add_f32_dpp v51, v51, v51 quad_perm:[2,3,0,1] row_mask:0xf bank_mask:0xf bound_ctrl:1
	v_pk_fma_f32 v[102:103], v[144:145], v[122:123], v[102:103] op_sel:[0,1,0] op_sel_hi:[1,1,1]
	v_pk_fma_f32 v[104:105], v[144:145], v[124:125], v[104:105] op_sel:[0,0,0] op_sel_hi:[1,0,1]
	v_pk_fma_f32 v[106:107], v[144:145], v[124:125], v[106:107] op_sel:[0,1,0] op_sel_hi:[1,1,1]
	v_add_f32_dpp v48, v48, v48 row_half_mirror row_mask:0xf bank_mask:0xf bound_ctrl:1
	v_add_f32_dpp v49, v49, v49 row_half_mirror row_mask:0xf bank_mask:0xf bound_ctrl:1
	v_add_f32_dpp v50, v50, v50 row_half_mirror row_mask:0xf bank_mask:0xf bound_ctrl:1
	v_add_f32_dpp v51, v51, v51 row_half_mirror row_mask:0xf bank_mask:0xf bound_ctrl:1
	v_pk_fma_f32 v[108:109], v[144:145], v[126:127], v[108:109] op_sel:[0,0,0] op_sel_hi:[1,0,1]
	s_mov_b64 exec, s[10:11]
	ds_write_b64 v45, v[48:49] offset:7424
	s_mov_b64 exec, s[0:1]
	v_pk_fma_f32 v[110:111], v[144:145], v[126:127], v[110:111] op_sel:[0,1,0] op_sel_hi:[1,1,1]
	s_nop 0
	v_pk_fma_f32 v[96:97], v[50:51], v[128:129], v[96:97] op_sel:[0,0,0] op_sel_hi:[1,0,1]
	v_pk_fma_f32 v[98:99], v[50:51], v[128:129], v[98:99] op_sel:[0,1,0] op_sel_hi:[1,1,1]
	v_pk_fma_f32 v[100:101], v[50:51], v[130:131], v[100:101] op_sel:[0,0,0] op_sel_hi:[1,0,1]
	v_pk_fma_f32 v[102:103], v[50:51], v[130:131], v[102:103] op_sel:[0,1,0] op_sel_hi:[1,1,1]
	v_pk_fma_f32 v[104:105], v[50:51], v[132:133], v[104:105] op_sel:[0,0,0] op_sel_hi:[1,0,1]
	v_pk_fma_f32 v[106:107], v[50:51], v[132:133], v[106:107] op_sel:[0,1,0] op_sel_hi:[1,1,1]
	v_pk_fma_f32 v[108:109], v[50:51], v[134:135], v[108:109] op_sel:[0,0,0] op_sel_hi:[1,0,1]
	v_pk_fma_f32 v[110:111], v[50:51], v[134:135], v[110:111] op_sel:[0,1,0] op_sel_hi:[1,1,1]
	v_pk_mul_f32 v[14:15], v[96:97], v[136:137] op_sel:[0,0] op_sel_hi:[1,0]
	v_pk_mul_f32 v[18:19], v[96:97], v[156:157] op_sel:[0,0] op_sel_hi:[1,0]
	v_pk_mul_f32 v[16:17], v[98:99], v[136:137] op_sel:[0,1] op_sel_hi:[1,1]
	v_pk_mul_f32 v[20:21], v[98:99], v[156:157] op_sel:[0,1] op_sel_hi:[1,1]
	v_pk_fma_f32 v[14:15], v[100:101], v[138:139], v[14:15] op_sel:[0,0,0] op_sel_hi:[1,0,1]
	v_pk_fma_f32 v[18:19], v[100:101], v[158:159], v[18:19] op_sel:[0,0,0] op_sel_hi:[1,0,1]
	v_pk_fma_f32 v[16:17], v[102:103], v[138:139], v[16:17] op_sel:[0,1,0] op_sel_hi:[1,1,1]
	v_pk_fma_f32 v[20:21], v[102:103], v[158:159], v[20:21] op_sel:[0,1,0] op_sel_hi:[1,1,1]
	v_pk_fma_f32 v[14:15], v[104:105], v[140:141], v[14:15] op_sel:[0,0,0] op_sel_hi:[1,0,1]
	v_pk_fma_f32 v[18:19], v[104:105], v[160:161], v[18:19] op_sel:[0,0,0] op_sel_hi:[1,0,1]
	v_pk_fma_f32 v[16:17], v[106:107], v[140:141], v[16:17] op_sel:[0,1,0] op_sel_hi:[1,1,1]
	v_pk_fma_f32 v[20:21], v[106:107], v[160:161], v[20:21] op_sel:[0,1,0] op_sel_hi:[1,1,1]
	v_pk_fma_f32 v[14:15], v[108:109], v[142:143], v[14:15] op_sel:[0,0,0] op_sel_hi:[1,0,1]
	v_pk_fma_f32 v[18:19], v[108:109], v[162:163], v[18:19] op_sel:[0,0,0] op_sel_hi:[1,0,1]
	v_pk_fma_f32 v[16:17], v[110:111], v[142:143], v[16:17] op_sel:[0,1,0] op_sel_hi:[1,1,1]
	v_pk_fma_f32 v[20:21], v[110:111], v[162:163], v[20:21] op_sel:[0,1,0] op_sel_hi:[1,1,1]
	v_pk_add_f32 v[48:49], v[14:15], v[16:17]
	v_pk_add_f32 v[50:51], v[18:19], v[20:21]
	s_waitcnt lgkmcnt(2)
; #define LAS __attribute__((address_space(3)))
; template <int CTRL> __device__ __forceinline__ float dpp_mov(float x) { return __int_as_float(__builtin_amdgcn_update_dpp(0, __float_as_int(x), CTRL, 0xF, 0xF, true)); }
; __device__ __forceinline__ float red8(float x) { x += dpp_mov<0xB1>(x); x += dpp_mov<0x4E>(x); x += dpp_mov<0x141>(x); return x; }
; __device__ __forceinline__ void scan_phase(const KP& P, LAS unsigned char* lds, const int tid, const int bx, const int G) {
;     ...
;             for (int s = 0; s < 32; ++s) {
;                 const LAS float* p = cb + s * 384;
;                 const f32x4 w0 = *(const LAS f32x4*)(p), w1 = *(const LAS f32x4*)(p + 4);
;                 const f32x4 k0 = *(const LAS f32x4*)(p + 64), k1 = *(const LAS f32x4*)(p + 68);
;                 const f32x4 a0 = *(const LAS f32x4*)(p + 128), a1 = *(const LAS f32x4*)(p + 132);
;                 const f32x4 b0 = *(const LAS f32x4*)(p + 192), b1 = *(const LAS f32x4*)(p + 196);
;                 const f32x4 r0 = *(const LAS f32x4*)(p + 256), r1 = *(const LAS f32x4*)(p + 260);
;                 const float vv = buf[(c & 1) * 12288 + s * 384 + 320 + v];
;                 f32x2 sa2 = S[0] * (f32x2){a0.x, a0.y};
;                 sa2 += S[1] * (f32x2){a0.z, a0.w}; sa2 += S[2] * (f32x2){a1.x, a1.y}; sa2 += S[3] * (f32x2){a1.z, a1.w};
;                 const float sa = red8(sa2.x + sa2.y);
;                 const f32x2 sav = {sa, sa}, vv2 = {vv, vv};
;                 S[0] = S[0] * (f32x2){w0.x, w0.y} + sav * (f32x2){b0.x, b0.y} + vv2 * (f32x2){k0.x, k0.y};
;                 S[1] = S[1] * (f32x2){w0.z, w0.w} + sav * (f32x2){b0.z, b0.w} + vv2 * (f32x2){k0.z, k0.w};
;                 S[2] = S[2] * (f32x2){w1.x, w1.y} + sav * (f32x2){b1.x, b1.y} + vv2 * (f32x2){k1.x, k1.y};
;                 S[3] = S[3] * (f32x2){w1.z, w1.w} + sav * (f32x2){b1.z, b1.w} + vv2 * (f32x2){k1.z, k1.w};
;                 f32x2 y2 = S[0] * (f32x2){r0.x, r0.y};
;                 y2 += S[1] * (f32x2){r0.z, r0.w}; y2 += S[2] * (f32x2){r1.x, r1.y}; y2 += S[3] * (f32x2){r1.z, r1.w};
;                 const float y = red8(y2.x + y2.y);
;                 if (kc == 0) ybuf[s * 64 + v] = y;
	s_nop 1
	v_add_f32_dpp v48, v48, v48 quad_perm:[1,0,3,2] row_mask:0xf bank_mask:0xf bound_ctrl:1
	v_add_f32_dpp v49, v49, v49 quad_perm:[1,0,3,2] row_mask:0xf bank_mask:0xf bound_ctrl:1
	v_add_f32_dpp v50, v50, v50 quad_perm:[1,0,3,2] row_mask:0xf bank_mask:0xf bound_ctrl:1
	v_add_f32_dpp v51, v51, v51 quad_perm:[1,0,3,2] row_mask:0xf bank_mask:0xf bound_ctrl:1
	v_pk_fma_f32 v[96:97], v[146:147], v[70:71], v[96:97] op_sel:[0,0,0] op_sel_hi:[1,0,1]
	v_pk_fma_f32 v[98:99], v[146:147], v[70:71], v[98:99] op_sel:[0,1,0] op_sel_hi:[1,1,1]
	v_pk_fma_f32 v[100:101], v[146:147], v[72:73], v[100:101] op_sel:[0,0,0] op_sel_hi:[1,0,1]
	v_add_f32_dpp v48, v48, v48 quad_perm:[2,3,0,1] row_mask:0xf bank_mask:0xf bound_ctrl:1
	v_add_f32_dpp v49, v49, v49 quad_perm:[2,3,0,1] row_mask:0xf bank_mask:0xf bound_ctrl:1
	v_add_f32_dpp v50, v50, v50 quad_perm:[2,3,0,1] row_mask:0xf bank_mask:0xf bound_ctrl:1
	v_add_f32_dpp v51, v51, v51 quad_perm:[2,3,0,1] row_mask:0xf bank_mask:0xf bound_ctrl:1
	v_pk_fma_f32 v[102:103], v[146:147], v[72:73], v[102:103] op_sel:[0,1,0] op_sel_hi:[1,1,1]
	v_pk_fma_f32 v[104:105], v[146:147], v[74:75], v[104:105] op_sel:[0,0,0] op_sel_hi:[1,0,1]
	v_pk_fma_f32 v[106:107], v[146:147], v[74:75], v[106:107] op_sel:[0,1,0] op_sel_hi:[1,1,1]
	v_add_f32_dpp v48, v48, v48 row_half_mirror row_mask:0xf bank_mask:0xf bound_ctrl:1
	v_add_f32_dpp v49, v49, v49 row_half_mirror row_mask:0xf bank_mask:0xf bound_ctrl:1
	v_add_f32_dpp v50, v50, v50 row_half_mirror row_mask:0xf bank_mask:0xf bound_ctrl:1
	v_add_f32_dpp v51, v51, v51 row_half_mirror row_mask:0xf bank_mask:0xf bound_ctrl:1
	v_pk_fma_f32 v[108:109], v[146:147], v[76:77], v[108:109] op_sel:[0,0,0] op_sel_hi:[1,0,1]
	s_mov_b64 exec, s[10:11]
	ds_write_b64 v45, v[48:49] offset:7680
	s_mov_b64 exec, s[0:1]
	v_pk_fma_f32 v[110:111], v[146:147], v[76:77], v[110:111] op_sel:[0,1,0] op_sel_hi:[1,1,1]
	s_nop 0
	v_pk_fma_f32 v[96:97], v[50:51], v[78:79], v[96:97] op_sel:[0,0,0] op_sel_hi:[1,0,1]
	v_pk_fma_f32 v[98:99], v[50:51], v[78:79], v[98:99] op_sel:[0,1,0] op_sel_hi:[1,1,1]
	v_pk_fma_f32 v[100:101], v[50:51], v[80:81], v[100:101] op_sel:[0,0,0] op_sel_hi:[1,0,1]
	v_pk_fma_f32 v[102:103], v[50:51], v[80:81], v[102:103] op_sel:[0,1,0] op_sel_hi:[1,1,1]
	v_pk_fma_f32 v[104:105], v[50:51], v[82:83], v[104:105] op_sel:[0,0,0] op_sel_hi:[1,0,1]
	v_pk_fma_f32 v[106:107], v[50:51], v[82:83], v[106:107] op_sel:[0,1,0] op_sel_hi:[1,1,1]
	v_pk_fma_f32 v[108:109], v[50:51], v[84:85], v[108:109] op_sel:[0,0,0] op_sel_hi:[1,0,1]
	v_pk_fma_f32 v[110:111], v[50:51], v[84:85], v[110:111] op_sel:[0,1,0] op_sel_hi:[1,1,1]
	v_pk_mul_f32 v[14:15], v[96:97], v[86:87] op_sel:[0,0] op_sel_hi:[1,0]
	s_nop 0
	v_pk_mul_f32 v[16:17], v[98:99], v[86:87] op_sel:[0,1] op_sel_hi:[1,1]
	s_nop 0
	v_pk_fma_f32 v[14:15], v[100:101], v[88:89], v[14:15] op_sel:[0,0,0] op_sel_hi:[1,0,1]
	s_nop 0
	v_pk_fma_f32 v[16:17], v[102:103], v[88:89], v[16:17] op_sel:[0,1,0] op_sel_hi:[1,1,1]
	s_nop 0
	v_pk_fma_f32 v[14:15], v[104:105], v[90:91], v[14:15] op_sel:[0,0,0] op_sel_hi:[1,0,1]
	s_nop 0
	v_pk_fma_f32 v[16:17], v[106:107], v[90:91], v[16:17] op_sel:[0,1,0] op_sel_hi:[1,1,1]
	s_nop 0
	v_pk_fma_f32 v[14:15], v[108:109], v[92:93], v[14:15] op_sel:[0,0,0] op_sel_hi:[1,0,1]
	s_nop 0
	v_pk_fma_f32 v[16:17], v[110:111], v[92:93], v[16:17] op_sel:[0,1,0] op_sel_hi:[1,1,1]
	s_nop 0
	v_pk_add_f32 v[48:49], v[14:15], v[16:17]
	v_pk_mul_f32 v[96:97], v[96:97], v[112:113] op_sel:[0,0] op_sel_hi:[1,0]
	v_pk_mul_f32 v[98:99], v[98:99], v[112:113] op_sel:[0,1] op_sel_hi:[1,1]
	v_pk_mul_f32 v[100:101], v[100:101], v[114:115] op_sel:[0,0] op_sel_hi:[1,0]
	v_pk_mul_f32 v[102:103], v[102:103], v[114:115] op_sel:[0,1] op_sel_hi:[1,1]
	v_pk_mul_f32 v[104:105], v[104:105], v[116:117] op_sel:[0,0] op_sel_hi:[1,0]
	v_pk_mul_f32 v[106:107], v[106:107], v[116:117] op_sel:[0,1] op_sel_hi:[1,1]
	v_pk_mul_f32 v[108:109], v[108:109], v[118:119] op_sel:[0,0] op_sel_hi:[1,0]
	v_pk_mul_f32 v[110:111], v[110:111], v[118:119] op_sel:[0,1] op_sel_hi:[1,1]
	v_add_f32_dpp v48, v48, v48 quad_perm:[1,0,3,2] row_mask:0xf bank_mask:0xf bound_ctrl:1
	v_add_f32_dpp v49, v49, v49 quad_perm:[1,0,3,2] row_mask:0xf bank_mask:0xf bound_ctrl:1
	s_nop 1
	v_add_f32_dpp v48, v48, v48 quad_perm:[2,3,0,1] row_mask:0xf bank_mask:0xf bound_ctrl:1
	v_add_f32_dpp v49, v49, v49 quad_perm:[2,3,0,1] row_mask:0xf bank_mask:0xf bound_ctrl:1
	s_nop 1
	v_add_f32_dpp v48, v48, v48 row_half_mirror row_mask:0xf bank_mask:0xf bound_ctrl:1
	v_add_f32_dpp v49, v49, v49 row_half_mirror row_mask:0xf bank_mask:0xf bound_ctrl:1
	s_nop 1
	s_mov_b64 exec, s[10:11]
	ds_write_b64 v45, v[48:49] offset:7936
	s_mov_b64 exec, s[0:1]

; #define PG8_STAGE(bufoff, gbase, voff) do { _Pragma("unroll") for (int _i = 0; _i < 2; ++_i) \
;         __builtin_amdgcn_global_load_lds((const unsigned*)((const char*)(gbase) + _i * r64##voff + voff##_), (LAS unsigned*)(lds + (bufoff) + ldsw + _i * 8192), 16, 0, 0); } while (0)
; #define PG8_LDA(dst, b, h) do { _Pragma("unroll") for (int m = 0; m < 4; ++m) _Pragma("unroll") for (int k = 0; k < 2; ++k) dst[m][k] = *(const LAS bf16x8*)(lds + PG8_SA(b, h) + aoff + m * 2048 + k * 1024); } while (0)
; #define PG8_LDB(dst, b, h) do { _Pragma("unroll") for (int n = 0; n < 2; ++n) _Pragma("unroll") for (int k = 0; k < 2; ++k) dst[n][k] = *(const LAS bf16x8*)(lds + PG8_SB(b, h) + boff + n * 2048 + k * 1024); } while (0)
; #define PG8_MMA(ai, bj, At, Bt) do { __builtin_amdgcn_s_setprio(1); _Pragma("unroll") for (int m = 0; m < 4; ++m) _Pragma("unroll") for (int n = 0; n < 2; ++n) _Pragma("unroll") for (int k = 0; k < 2; ++k) \
;         acc[ai][bj][m][n] = __builtin_amdgcn_mfma_f32_16x16x32_bf16(Bt[n][k], At[m][k], acc[ai][bj][m][n], 0, 0, 0); __builtin_amdgcn_s_setprio(0); } while (0)
; #define PG8_WAIT_V(n) asm volatile("s_waitcnt vmcnt(" #n ")" ::: "memory")
; #define PG8_WAIT_L(n) asm volatile("s_waitcnt lgkmcnt(" #n ")" ::: "memory")
; #define PG8_BAR __builtin_amdgcn_s_barrier()
; #define PG8_SCHED __builtin_amdgcn_sched_barrier(0)
; __device__ __forceinline__ void gemm_phase(LAS unsigned char* lds, const Gemm g, const StaticOrder& S, const EpiSrc es, const int perm, const int tid) {
;     ...
;         for (int t = 0; t < nt; t += 2) {
;             const bool last = (t == nt - 2);
;             const char* a1 = cA + (size_t)(t + 1) * kstep;
;             const char* a2 = last ? nA : cA + (size_t)(t + 2) * kstep; const char* b2 = last ? nB : cB + (size_t)(t + 2) * kstep;
;             const char* a3 = a2 + kstep; const char* b3 = b2 + kstep;
;             PG8_LDB(B0, 0, 0); PG8_LDB(B1, 0, 1); PG8_SCHED; PG8_LDA(At, 0, 0); PG8_STAGE(PG8_SA(1, 1), a1 + hstepA, voffA);
;             PG8_WAIT_V(8); PG8_WAIT_L(0); PG8_BAR; PG8_MMA(0, 0, At, B0); PG8_MMA(0, 1, At, B1); PG8_BAR; PG8_SCHED;
;             PG8_LDA(At, 0, 1); PG8_STAGE(PG8_SB(0, 0), b2, voffB); PG8_STAGE(PG8_SB(0, 1), b2 + hstepB, voffB); PG8_STAGE(PG8_SA(0, 0), a2, voffA);
;             PG8_WAIT_V(8); PG8_WAIT_L(0); PG8_BAR; PG8_MMA(1, 0, At, B0); PG8_MMA(1, 1, At, B1); PG8_BAR; PG8_SCHED;
.LBB0_285:
	s_add_i32 s12, s2, 2
	s_add_u32 s13, s0, 0x80
	s_addc_u32 s3, s1, 0
	s_waitcnt lgkmcnt(0)
	s_add_i32 s16, 0, 0x10000
	s_cmp_eq_u32 s54, s2
	s_cselect_b32 s3, s47, s3
	s_cselect_b32 s2, s46, s13
	s_cselect_b32 s15, s39, s5
	s_cselect_b32 s14, s38, s4
	s_add_i32 s13, 0, 0x14000
	v_add_u32_e32 v142, s16, v229
	v_add_u32_e32 v158, s13, v229
	ds_read_b128 v[130:133], v142
	ds_read_b128 v[134:137], v142 offset:1024
	ds_read_b128 v[138:141], v142 offset:2048
	ds_read_b128 v[142:145], v142 offset:3072
	ds_read_b128 v[146:149], v158
	ds_read_b128 v[150:153], v158 offset:1024
	ds_read_b128 v[154:157], v158 offset:2048
	ds_read_b128 v[158:161], v158 offset:3072
	v_lshl_add_u64 v[252:253], s[0:1], 0, v[184:185]
	s_add_i32 m0, s31, 0xc000
	ds_read_b128 v[188:191], v231
	ds_read_b128 v[192:195], v231 offset:1024
	ds_read_b128 v[196:199], v231 offset:2048
	ds_read_b128 v[232:235], v231 offset:3072
	ds_read_b128 v[236:239], v231 offset:4096
	ds_read_b128 v[240:243], v231 offset:5120
	ds_read_b128 v[244:247], v231 offset:6144
	ds_read_b128 v[248:251], v231 offset:7168
	global_load_lds_dwordx4 v[252:253], off
	v_lshl_add_u64 v[252:253], s[0:1], 0, v[186:187]
	s_add_i32 m0, s31, 0xe000
	s_nop 0
	global_load_lds_dwordx4 v[252:253], off
	s_waitcnt vmcnt(8)
	s_waitcnt lgkmcnt(0)
	s_barrier
	s_waitcnt lgkmcnt(0)
	v_mfma_f32_16x16x32_bf16 v[94:97], v[130:133], v[188:191], v[94:97]
	v_mfma_f32_16x16x32_bf16 v[86:89], v[138:141], v[188:191], v[86:89]
	v_mfma_f32_16x16x32_bf16 v[110:113], v[130:133], v[196:199], v[110:113]
	v_mfma_f32_16x16x32_bf16 v[102:105], v[138:141], v[196:199], v[102:105]
	v_mfma_f32_16x16x32_bf16 v[90:93], v[130:133], v[236:239], v[90:93]
	v_mfma_f32_16x16x32_bf16 v[82:85], v[138:141], v[236:239], v[82:85]
	v_mfma_f32_16x16x32_bf16 v[78:81], v[130:133], v[244:247], v[78:81]
	v_mfma_f32_16x16x32_bf16 v[74:77], v[138:141], v[244:247], v[74:77]
	v_mfma_f32_16x16x32_bf16 v[94:97], v[134:137], v[192:195], v[94:97]
	v_mfma_f32_16x16x32_bf16 v[86:89], v[142:145], v[192:195], v[86:89]
	v_mfma_f32_16x16x32_bf16 v[110:113], v[134:137], v[232:235], v[110:113]
	v_mfma_f32_16x16x32_bf16 v[102:105], v[142:145], v[232:235], v[102:105]
	v_mfma_f32_16x16x32_bf16 v[90:93], v[134:137], v[240:243], v[90:93]
	v_mfma_f32_16x16x32_bf16 v[82:85], v[142:145], v[240:243], v[82:85]
	v_mfma_f32_16x16x32_bf16 v[78:81], v[134:137], v[248:251], v[78:81]
	v_mfma_f32_16x16x32_bf16 v[74:77], v[142:145], v[248:251], v[74:77]
	v_mfma_f32_16x16x32_bf16 v[126:129], v[146:149], v[188:191], v[126:129]
	v_mfma_f32_16x16x32_bf16 v[122:125], v[154:157], v[188:191], v[122:125]
	v_mfma_f32_16x16x32_bf16 v[118:121], v[146:149], v[196:199], v[118:121]
	v_mfma_f32_16x16x32_bf16 v[114:117], v[154:157], v[196:199], v[114:117]
	v_mfma_f32_16x16x32_bf16 v[106:109], v[146:149], v[236:239], v[106:109]
	v_mfma_f32_16x16x32_bf16 v[98:101], v[154:157], v[236:239], v[98:101]
	v_mfma_f32_16x16x32_bf16 v[70:73], v[146:149], v[244:247], v[70:73]
	v_mfma_f32_16x16x32_bf16 v[66:69], v[154:157], v[244:247], v[66:69]
	v_mfma_f32_16x16x32_bf16 v[126:129], v[150:153], v[192:195], v[126:129]
	v_mfma_f32_16x16x32_bf16 v[122:125], v[158:161], v[192:195], v[122:125]
	v_mfma_f32_16x16x32_bf16 v[118:121], v[150:153], v[232:235], v[118:121]
	v_mfma_f32_16x16x32_bf16 v[114:117], v[158:161], v[232:235], v[114:117]
	v_mfma_f32_16x16x32_bf16 v[106:109], v[150:153], v[240:243], v[106:109]
	v_mfma_f32_16x16x32_bf16 v[98:101], v[158:161], v[240:243], v[98:101]
	v_mfma_f32_16x16x32_bf16 v[70:73], v[150:153], v[248:251], v[70:73]
	v_mfma_f32_16x16x32_bf16 v[66:69], v[158:161], v[248:251], v[66:69]
	s_barrier
	s_add_i32 s16, s16, s70
	v_lshl_add_u64 v[252:253], s[14:15], 0, v[0:1]
	s_mov_b32 m0, s16
	ds_read_b128 v[188:191], v231 offset:16384
	ds_read_b128 v[192:195], v231 offset:17408
	ds_read_b128 v[196:199], v231 offset:18432
	ds_read_b128 v[232:235], v231 offset:19456
	ds_read_b128 v[236:239], v231 offset:20480
	ds_read_b128 v[240:243], v231 offset:21504
	ds_read_b128 v[244:247], v231 offset:22528
	ds_read_b128 v[248:251], v231 offset:23552
	global_load_lds_dwordx4 v[252:253], off
	s_add_i32 m0, s16, 0x2000
	s_add_u32 s14, s14, s92
	v_lshl_add_u64 v[214:215], v[252:253], 0, s[94:95]
	s_addc_u32 s15, s15, 0
	s_add_i32 s13, s13, s70
	global_load_lds_dwordx4 v[214:215], off
	v_lshl_add_u64 v[202:203], s[14:15], 0, v[0:1]
	s_mov_b32 m0, s13
	v_lshl_add_u64 v[206:207], v[202:203], 0, s[94:95]
	global_load_lds_dwordx4 v[202:203], off
	s_add_i32 m0, s13, 0x2000
	v_lshl_add_u64 v[208:209], s[2:3], 0, v[162:163]
	global_load_lds_dwordx4 v[206:207], off
	s_mov_b32 m0, s31
	v_lshl_add_u64 v[210:211], v[208:209], 0, s[94:95]
	global_load_lds_dwordx4 v[208:209], off
	s_mov_b32 m0, s81
	s_nop 0
	global_load_lds_dwordx4 v[210:211], off
	s_waitcnt vmcnt(8)
	s_waitcnt lgkmcnt(0)
	s_barrier
; #define PG8_STAGE(bufoff, gbase, voff) do { _Pragma("unroll") for (int _i = 0; _i < 2; ++_i) \
;         __builtin_amdgcn_global_load_lds((const unsigned*)((const char*)(gbase) + _i * r64##voff + voff##_), (LAS unsigned*)(lds + (bufoff) + ldsw + _i * 8192), 16, 0, 0); } while (0)
; #define PG8_LDA(dst, b, h) do { _Pragma("unroll") for (int m = 0; m < 4; ++m) _Pragma("unroll") for (int k = 0; k < 2; ++k) dst[m][k] = *(const LAS bf16x8*)(lds + PG8_SA(b, h) + aoff + m * 2048 + k * 1024); } while (0)
; #define PG8_LDB(dst, b, h) do { _Pragma("unroll") for (int n = 0; n < 2; ++n) _Pragma("unroll") for (int k = 0; k < 2; ++k) dst[n][k] = *(const LAS bf16x8*)(lds + PG8_SB(b, h) + boff + n * 2048 + k * 1024); } while (0)
; #define PG8_MMA(ai, bj, At, Bt) do { __builtin_amdgcn_s_setprio(1); _Pragma("unroll") for (int m = 0; m < 4; ++m) _Pragma("unroll") for (int n = 0; n < 2; ++n) _Pragma("unroll") for (int k = 0; k < 2; ++k) \
;         acc[ai][bj][m][n] = __builtin_amdgcn_mfma_f32_16x16x32_bf16(Bt[n][k], At[m][k], acc[ai][bj][m][n], 0, 0, 0); __builtin_amdgcn_s_setprio(0); } while (0)
; #define PG8_WAIT_V(n) asm volatile("s_waitcnt vmcnt(" #n ")" ::: "memory")
; #define PG8_WAIT_L(n) asm volatile("s_waitcnt lgkmcnt(" #n ")" ::: "memory")
; #define PG8_BAR __builtin_amdgcn_s_barrier()
; #define PG8_SCHED __builtin_amdgcn_sched_barrier(0)
; __device__ __forceinline__ void gemm_phase(LAS unsigned char* lds, const Gemm g, const StaticOrder& S, const EpiSrc es, const int perm, const int tid) {
;     ...
;             PG8_WAIT_V(8); PG8_WAIT_L(0); PG8_BAR; PG8_MMA(1, 0, At, B0); PG8_MMA(1, 1, At, B1); PG8_BAR; PG8_SCHED;
;             PG8_LDB(B0, 1, 0); PG8_LDB(B1, 1, 1); PG8_SCHED; PG8_LDA(At, 1, 0); PG8_STAGE(PG8_SA(0, 1), a2 + hstepA, voffA);
;             PG8_WAIT_V(8); PG8_WAIT_L(0); PG8_BAR; PG8_MMA(0, 0, At, B0); PG8_MMA(0, 1, At, B1); PG8_BAR; PG8_SCHED;
	s_waitcnt lgkmcnt(0)
	v_mfma_f32_16x16x32_bf16 v[30:33], v[130:133], v[188:191], v[30:33]
	v_mfma_f32_16x16x32_bf16 v[22:25], v[138:141], v[188:191], v[22:25]
	v_mfma_f32_16x16x32_bf16 v[46:49], v[130:133], v[196:199], v[46:49]
	v_mfma_f32_16x16x32_bf16 v[38:41], v[138:141], v[196:199], v[38:41]
	v_mfma_f32_16x16x32_bf16 v[26:29], v[130:133], v[236:239], v[26:29]
	v_mfma_f32_16x16x32_bf16 v[18:21], v[138:141], v[236:239], v[18:21]
	v_mfma_f32_16x16x32_bf16 v[14:17], v[130:133], v[244:247], v[14:17]
	v_mfma_f32_16x16x32_bf16 v[10:13], v[138:141], v[244:247], v[10:13]
	v_mfma_f32_16x16x32_bf16 v[30:33], v[134:137], v[192:195], v[30:33]
	v_mfma_f32_16x16x32_bf16 v[22:25], v[142:145], v[192:195], v[22:25]
	v_mfma_f32_16x16x32_bf16 v[46:49], v[134:137], v[232:235], v[46:49]
	v_mfma_f32_16x16x32_bf16 v[38:41], v[142:145], v[232:235], v[38:41]
	v_mfma_f32_16x16x32_bf16 v[26:29], v[134:137], v[240:243], v[26:29]
	v_mfma_f32_16x16x32_bf16 v[18:21], v[142:145], v[240:243], v[18:21]
	v_mfma_f32_16x16x32_bf16 v[14:17], v[134:137], v[248:251], v[14:17]
	v_mfma_f32_16x16x32_bf16 v[10:13], v[142:145], v[248:251], v[10:13]
	v_mfma_f32_16x16x32_bf16 v[62:65], v[146:149], v[188:191], v[62:65]
	v_mfma_f32_16x16x32_bf16 v[58:61], v[154:157], v[188:191], v[58:61]
	v_mfma_f32_16x16x32_bf16 v[54:57], v[146:149], v[196:199], v[54:57]
	v_mfma_f32_16x16x32_bf16 v[50:53], v[154:157], v[196:199], v[50:53]
	v_mfma_f32_16x16x32_bf16 v[42:45], v[146:149], v[236:239], v[42:45]
	v_mfma_f32_16x16x32_bf16 v[34:37], v[154:157], v[236:239], v[34:37]
	v_mfma_f32_16x16x32_bf16 v[6:9], v[146:149], v[244:247], v[6:9]
	v_mfma_f32_16x16x32_bf16 v[2:5], v[154:157], v[244:247], v[2:5]
	v_mfma_f32_16x16x32_bf16 v[62:65], v[150:153], v[192:195], v[62:65]
	v_mfma_f32_16x16x32_bf16 v[58:61], v[158:161], v[192:195], v[58:61]
	v_mfma_f32_16x16x32_bf16 v[54:57], v[150:153], v[232:235], v[54:57]
	v_mfma_f32_16x16x32_bf16 v[50:53], v[158:161], v[232:235], v[50:53]
	v_mfma_f32_16x16x32_bf16 v[42:45], v[150:153], v[240:243], v[42:45]
	v_mfma_f32_16x16x32_bf16 v[34:37], v[158:161], v[240:243], v[34:37]
	v_mfma_f32_16x16x32_bf16 v[6:9], v[150:153], v[248:251], v[6:9]
	v_mfma_f32_16x16x32_bf16 v[2:5], v[158:161], v[248:251], v[2:5]
	s_barrier
	s_add_i32 s13, 0, 0x18000
	s_add_i32 s14, 0, 0x1c000
	v_add_u32_e32 v142, s13, v229
	v_add_u32_e32 v158, s14, v229
	ds_read_b128 v[130:133], v142
	ds_read_b128 v[134:137], v142 offset:1024
	ds_read_b128 v[138:141], v142 offset:2048
	ds_read_b128 v[142:145], v142 offset:3072
	ds_read_b128 v[146:149], v158
	ds_read_b128 v[150:153], v158 offset:1024
	ds_read_b128 v[154:157], v158 offset:2048
	ds_read_b128 v[158:161], v158 offset:3072
	s_add_u32 s2, s2, s92
	s_addc_u32 s3, s3, 0
	s_mov_b32 m0, s64
	v_lshl_add_u64 v[212:213], s[2:3], 0, v[162:163]
	ds_read_b128 v[188:191], v231 offset:32768
	ds_read_b128 v[192:195], v231 offset:33792
	ds_read_b128 v[196:199], v231 offset:34816
	ds_read_b128 v[232:235], v231 offset:35840
	ds_read_b128 v[236:239], v231 offset:36864
	ds_read_b128 v[240:243], v231 offset:37888
	ds_read_b128 v[244:247], v231 offset:38912
	ds_read_b128 v[248:251], v231 offset:39936
	global_load_lds_dwordx4 v[212:213], off
	v_lshl_add_u64 v[212:213], v[212:213], 0, s[94:95]
	s_mov_b32 m0, s79
	s_nop 0
	global_load_lds_dwordx4 v[212:213], off
	s_waitcnt vmcnt(8)
	s_waitcnt lgkmcnt(0)
	s_barrier
	s_waitcnt lgkmcnt(0)
	v_mfma_f32_16x16x32_bf16 v[94:97], v[130:133], v[188:191], v[94:97]
	v_mfma_f32_16x16x32_bf16 v[86:89], v[138:141], v[188:191], v[86:89]
	v_mfma_f32_16x16x32_bf16 v[110:113], v[130:133], v[196:199], v[110:113]
	v_mfma_f32_16x16x32_bf16 v[102:105], v[138:141], v[196:199], v[102:105]
	v_mfma_f32_16x16x32_bf16 v[90:93], v[130:133], v[236:239], v[90:93]
	v_mfma_f32_16x16x32_bf16 v[82:85], v[138:141], v[236:239], v[82:85]
	v_mfma_f32_16x16x32_bf16 v[78:81], v[130:133], v[244:247], v[78:81]
	v_mfma_f32_16x16x32_bf16 v[74:77], v[138:141], v[244:247], v[74:77]
	v_mfma_f32_16x16x32_bf16 v[94:97], v[134:137], v[192:195], v[94:97]
	v_mfma_f32_16x16x32_bf16 v[86:89], v[142:145], v[192:195], v[86:89]
	v_mfma_f32_16x16x32_bf16 v[110:113], v[134:137], v[232:235], v[110:113]
	v_mfma_f32_16x16x32_bf16 v[102:105], v[142:145], v[232:235], v[102:105]
	v_mfma_f32_16x16x32_bf16 v[90:93], v[134:137], v[240:243], v[90:93]
	v_mfma_f32_16x16x32_bf16 v[82:85], v[142:145], v[240:243], v[82:85]
	v_mfma_f32_16x16x32_bf16 v[78:81], v[134:137], v[248:251], v[78:81]
	v_mfma_f32_16x16x32_bf16 v[74:77], v[142:145], v[248:251], v[74:77]
	v_mfma_f32_16x16x32_bf16 v[126:129], v[146:149], v[188:191], v[126:129]
	v_mfma_f32_16x16x32_bf16 v[122:125], v[154:157], v[188:191], v[122:125]
	v_mfma_f32_16x16x32_bf16 v[118:121], v[146:149], v[196:199], v[118:121]
	v_mfma_f32_16x16x32_bf16 v[114:117], v[154:157], v[196:199], v[114:117]
	v_mfma_f32_16x16x32_bf16 v[106:109], v[146:149], v[236:239], v[106:109]
	v_mfma_f32_16x16x32_bf16 v[98:101], v[154:157], v[236:239], v[98:101]
	v_mfma_f32_16x16x32_bf16 v[70:73], v[146:149], v[244:247], v[70:73]
	v_mfma_f32_16x16x32_bf16 v[66:69], v[154:157], v[244:247], v[66:69]
	v_mfma_f32_16x16x32_bf16 v[126:129], v[150:153], v[192:195], v[126:129]
	v_mfma_f32_16x16x32_bf16 v[122:125], v[158:161], v[192:195], v[122:125]
	v_mfma_f32_16x16x32_bf16 v[118:121], v[150:153], v[232:235], v[118:121]
	v_mfma_f32_16x16x32_bf16 v[114:117], v[158:161], v[232:235], v[114:117]
	v_mfma_f32_16x16x32_bf16 v[106:109], v[150:153], v[240:243], v[106:109]
	v_mfma_f32_16x16x32_bf16 v[98:101], v[158:161], v[240:243], v[98:101]
	v_mfma_f32_16x16x32_bf16 v[70:73], v[150:153], v[248:251], v[70:73]
	v_mfma_f32_16x16x32_bf16 v[66:69], v[158:161], v[248:251], v[66:69]
	s_barrier
; #define PG8_STAGE(bufoff, gbase, voff) do { _Pragma("unroll") for (int _i = 0; _i < 2; ++_i) \
;         __builtin_amdgcn_global_load_lds((const unsigned*)((const char*)(gbase) + _i * r64##voff + voff##_), (LAS unsigned*)(lds + (bufoff) + ldsw + _i * 8192), 16, 0, 0); } while (0)
; #define PG8_LDA(dst, b, h) do { _Pragma("unroll") for (int m = 0; m < 4; ++m) _Pragma("unroll") for (int k = 0; k < 2; ++k) dst[m][k] = *(const LAS bf16x8*)(lds + PG8_SA(b, h) + aoff + m * 2048 + k * 1024); } while (0)
; #define PG8_MMA(ai, bj, At, Bt) do { __builtin_amdgcn_s_setprio(1); _Pragma("unroll") for (int m = 0; m < 4; ++m) _Pragma("unroll") for (int n = 0; n < 2; ++n) _Pragma("unroll") for (int k = 0; k < 2; ++k) \
;         acc[ai][bj][m][n] = __builtin_amdgcn_mfma_f32_16x16x32_bf16(Bt[n][k], At[m][k], acc[ai][bj][m][n], 0, 0, 0); __builtin_amdgcn_s_setprio(0); } while (0)
; #define PG8_WAIT_V(n) asm volatile("s_waitcnt vmcnt(" #n ")" ::: "memory")
; #define PG8_WAIT_L(n) asm volatile("s_waitcnt lgkmcnt(" #n ")" ::: "memory")
; #define PG8_BAR __builtin_amdgcn_s_barrier()
; #define PG8_SCHED __builtin_amdgcn_sched_barrier(0)
; __device__ __forceinline__ void gemm_phase(LAS unsigned char* lds, const Gemm g, const StaticOrder& S, const EpiSrc es, const int perm, const int tid) {
;     ...
;             PG8_LDA(At, 1, 1); PG8_STAGE(PG8_SB(1, 0), b3, voffB); PG8_STAGE(PG8_SB(1, 1), b3 + hstepB, voffB); PG8_STAGE(PG8_SA(1, 0), a3, voffA);
;             PG8_WAIT_V(8); PG8_WAIT_L(0); PG8_BAR; PG8_MMA(1, 0, At, B0); PG8_MMA(1, 1, At, B1); PG8_BAR; PG8_SCHED;
;         }
	s_add_i32 s2, s13, s70
	v_lshl_add_u64 v[212:213], v[252:253], 0, s[44:45]
	s_mov_b32 m0, s2
	ds_read_b128 v[188:191], v231 offset:49152
	ds_read_b128 v[192:195], v231 offset:50176
	ds_read_b128 v[196:199], v231 offset:51200
	ds_read_b128 v[232:235], v231 offset:52224
	ds_read_b128 v[236:239], v231 offset:53248
	ds_read_b128 v[240:243], v231 offset:54272
	ds_read_b128 v[244:247], v231 offset:55296
	ds_read_b128 v[248:251], v231 offset:56320
	global_load_lds_dwordx4 v[212:213], off
	v_lshl_add_u64 v[212:213], v[214:215], 0, s[44:45]
	s_add_i32 m0, s2, 0x2000
	s_add_i32 s2, s14, s70
	global_load_lds_dwordx4 v[212:213], off
	v_lshl_add_u64 v[202:203], v[202:203], 0, s[44:45]
	s_mov_b32 m0, s2
	s_nop 0
	global_load_lds_dwordx4 v[202:203], off
	v_lshl_add_u64 v[202:203], v[206:207], 0, s[44:45]
	s_add_i32 m0, s2, 0x2000
	s_nop 0
	global_load_lds_dwordx4 v[202:203], off
	v_lshl_add_u64 v[202:203], v[208:209], 0, s[44:45]
	s_mov_b32 m0, s80
	s_nop 0
	global_load_lds_dwordx4 v[202:203], off
	v_lshl_add_u64 v[202:203], v[210:211], 0, s[44:45]
	s_mov_b32 m0, s55
	s_nop 0
	global_load_lds_dwordx4 v[202:203], off
	s_waitcnt vmcnt(8)
	s_waitcnt lgkmcnt(0)
	s_barrier
	s_waitcnt lgkmcnt(0)
	v_mfma_f32_16x16x32_bf16 v[30:33], v[130:133], v[188:191], v[30:33]
	v_mfma_f32_16x16x32_bf16 v[22:25], v[138:141], v[188:191], v[22:25]
	v_mfma_f32_16x16x32_bf16 v[46:49], v[130:133], v[196:199], v[46:49]
	v_mfma_f32_16x16x32_bf16 v[38:41], v[138:141], v[196:199], v[38:41]
	v_mfma_f32_16x16x32_bf16 v[26:29], v[130:133], v[236:239], v[26:29]
	v_mfma_f32_16x16x32_bf16 v[18:21], v[138:141], v[236:239], v[18:21]
	v_mfma_f32_16x16x32_bf16 v[14:17], v[130:133], v[244:247], v[14:17]
	v_mfma_f32_16x16x32_bf16 v[10:13], v[138:141], v[244:247], v[10:13]
	v_mfma_f32_16x16x32_bf16 v[30:33], v[134:137], v[192:195], v[30:33]
	v_mfma_f32_16x16x32_bf16 v[22:25], v[142:145], v[192:195], v[22:25]
	v_mfma_f32_16x16x32_bf16 v[46:49], v[134:137], v[232:235], v[46:49]
	v_mfma_f32_16x16x32_bf16 v[38:41], v[142:145], v[232:235], v[38:41]
	v_mfma_f32_16x16x32_bf16 v[26:29], v[134:137], v[240:243], v[26:29]
	v_mfma_f32_16x16x32_bf16 v[18:21], v[142:145], v[240:243], v[18:21]
	v_mfma_f32_16x16x32_bf16 v[14:17], v[134:137], v[248:251], v[14:17]
	v_mfma_f32_16x16x32_bf16 v[10:13], v[142:145], v[248:251], v[10:13]
	v_mfma_f32_16x16x32_bf16 v[62:65], v[146:149], v[188:191], v[62:65]
	v_mfma_f32_16x16x32_bf16 v[58:61], v[154:157], v[188:191], v[58:61]
	v_mfma_f32_16x16x32_bf16 v[54:57], v[146:149], v[196:199], v[54:57]
	v_mfma_f32_16x16x32_bf16 v[50:53], v[154:157], v[196:199], v[50:53]
	v_mfma_f32_16x16x32_bf16 v[42:45], v[146:149], v[236:239], v[42:45]
	v_mfma_f32_16x16x32_bf16 v[34:37], v[154:157], v[236:239], v[34:37]
	v_mfma_f32_16x16x32_bf16 v[6:9], v[146:149], v[244:247], v[6:9]
	v_mfma_f32_16x16x32_bf16 v[2:5], v[154:157], v[244:247], v[2:5]
	v_mfma_f32_16x16x32_bf16 v[62:65], v[150:153], v[192:195], v[62:65]
	v_mfma_f32_16x16x32_bf16 v[58:61], v[158:161], v[192:195], v[58:61]
	v_mfma_f32_16x16x32_bf16 v[54:57], v[150:153], v[232:235], v[54:57]
	v_mfma_f32_16x16x32_bf16 v[50:53], v[158:161], v[232:235], v[50:53]
	v_mfma_f32_16x16x32_bf16 v[42:45], v[150:153], v[240:243], v[42:45]
	v_mfma_f32_16x16x32_bf16 v[34:37], v[158:161], v[240:243], v[34:37]
	v_mfma_f32_16x16x32_bf16 v[6:9], v[150:153], v[248:251], v[6:9]
	v_mfma_f32_16x16x32_bf16 v[2:5], v[158:161], v[248:251], v[2:5]
	s_barrier
	s_add_u32 s0, s0, 0x100
	s_addc_u32 s1, s1, 0
	s_add_u32 s4, s4, 0x100
	s_addc_u32 s5, s5, 0
	s_cmp_ge_u32 s12, s57
	s_mov_b32 s2, s12
	s_cbranch_scc0 .LBB0_285
	s_and_b64 vcc, exec, s[26:27]
	s_cbranch_vccz .LBB0_288
	s_barrier
